# v23 + nt hint on the once-read f32 weight tiles of the deferred transposes
# speedup vs baseline: 1.0617x; 1.0133x over previous
; #define GAS __attribute__((address_space(1)))
; #define LAS __attribute__((address_space(3)))
; __device__ __forceinline__ void transpose_item(const float* W, int ldw, bf16* WT, int K, int k0, int sn0, int dn0, int lane, LAS unsigned char* T, const float* kgain = nullptr) {
;     const int nb = lane & 15, kq = lane >> 4;
; #pragma unroll
;     for (int j = 0; j < 4; ++j) { const int kb = kq + 4 * j, k = k0 + 4 * kb; f32x4 r[4];
; #pragma unroll
;         for (int jj = 0; jj < 4; ++jj) r[jj] = *(const GAS f32x4*)(W + (size_t)(k + jj) * ldw + sn0 + 4 * nb);
;         f32x4 g = {1.f, 1.f, 1.f, 1.f}; if (kgain) g = *(const GAS f32x4*)(kgain + k);
;         const f32x4 a = r[0] * g.x, bq = r[1] * g.y, c = r[2] * g.z, d = r[3] * g.w;
;         LAS unsigned char* t = T + (4 * nb) * 128 + ((kb ^ nb) << 3);
;         v2u w; w.x = pk2(a.x, bq.x); w.y = pk2(c.x, d.x); *(LAS v2u*)t = w;
;         w.x = pk2(a.y, bq.y); w.y = pk2(c.y, d.y); *(LAS v2u*)(t + 128) = w;
;         w.x = pk2(a.z, bq.z); w.y = pk2(c.z, d.z); *(LAS v2u*)(t + 256) = w;
;         w.x = pk2(a.w, bq.w); w.y = pk2(c.w, d.w); *(LAS v2u*)(t + 384) = w; }
; template <int PART> __device__ __forceinline__ void deferred_transposes(Frame& F, int gw, int ngw) {
;     ...
;     for (int it = gw; it < NITEMS; it += ngw) {
;         int r = (PART == 0) ? it : it + N0;
;         if (r < I_GLU) { const int nblk = S5W / 64, kb = r / nblk, nb = r % nblk; transpose_item(F.in[16], S5W, WgluT, S5W, kb * 64, nb * 64, nb * 64, F.lane, F.lds + F.wave * 8192); continue; } r -= I_GLU;
;         if (r < I_OUT) { const int nblk = DM / 64, kb = r / nblk, nb = r % nblk; transpose_item(F.in[18], DM, WoutT, DM, kb * 64, nb * 64, nb * 64, F.lane, F.lds + F.wave * 8192); continue; } r -= I_OUT;
;         if (r < I_G) { const int nblk = DFF / 64, kb = r / nblk, nb = r % nblk, sn0 = nb * 64; transpose_item(F.in[20], DFF, WguT, DM, kb * 64, sn0, 256 * (sn0 / 128) + (sn0 % 128), F.lane, F.lds + F.wave * 8192, F.in[19]); continue; } r -= I_G;
;         if (r < I_G) { const int nblk = DFF / 64, kb = r / nblk, nb = r % nblk, sn0 = nb * 64; transpose_item(F.in[21], DFF, WguT, DM, kb * 64, sn0, 256 * (sn0 / 128) + 128 + (sn0 % 128), F.lane, F.lds + F.wave * 8192, F.in[19]); continue; } r -= I_G;
.LBB0_157:
	s_cmp_gt_i32 s3, 63
	s_mov_b64 s[12:13], -1
	s_cbranch_scc0 .LBB0_182
	s_cmpk_gt_u32 s3, 0x13f
	s_cbranch_scc0 .LBB0_179
	s_cmpk_gt_u32 s3, 0x3ff
	s_cbranch_scc0 .LBB0_169
	s_add_i32 s4, s3, 0xfc00
	s_and_b32 s10, s4, 0xffff
	s_mul_i32 s10, s10, 0xba2f
	s_lshr_b32 s11, s10, 21
	s_mul_i32 s10, s11, 44
	s_sub_i32 s4, s4, s10
	s_and_b32 s10, s4, 0xffff
	s_lshl_b32 s11, s11, 6
	s_lshl_b32 s4, s10, 8
	v_or_b32_e32 v3, s11, v62
	v_lshl_add_u64 v[58:59], v[44:45], 0, s[4:5]
	v_mad_u32_u24 v42, v3, s19, s19
	v_lshl_add_u64 v[6:7], v[58:59], 0, v[42:43]
	v_mad_u32_u24 v42, v3, s19, v86
	v_mad_u64_u32 v[4:5], s[12:13], v3, s19, v[58:59]
	v_lshl_add_u64 v[8:9], v[58:59], 0, v[42:43]
	v_mad_u32_u24 v42, v3, s19, v87
	global_load_dwordx4 v[14:17], v[4:5], off nt
	s_nop 0
	global_load_dwordx4 v[4:7], v[6:7], off nt
	v_lshl_add_u64 v[10:11], v[58:59], 0, v[42:43]
	global_load_dwordx4 v[30:33], v[8:9], off nt
	global_load_dwordx4 v[22:25], v[10:11], off nt
	v_mov_b32_e32 v2, 1.0
	s_and_b64 vcc, exec, s[6:7]
	v_mov_b32_e32 v38, 1.0
	v_mov_b32_e32 v8, 1.0
	v_mov_b32_e32 v40, 1.0
	v_mov_b32_e32 v60, 1.0
	s_cbranch_vccnz .LBB0_162
	v_readlane_b32 s60, v238, 29
	v_lshlrev_b32_e32 v3, 2, v3
	v_readlane_b32 s66, v238, 35
	v_readlane_b32 s67, v238, 36
	v_readlane_b32 s61, v238, 30
	v_readlane_b32 s62, v238, 31
	v_readlane_b32 s63, v238, 32
	v_readlane_b32 s64, v238, 33
	v_readlane_b32 s65, v238, 34
	global_load_dwordx4 v[38:41], v3, s[66:67]
	v_readlane_b32 s68, v238, 37
	v_readlane_b32 s69, v238, 38
	v_readlane_b32 s70, v238, 39
	v_readlane_b32 s71, v238, 40
	v_readlane_b32 s72, v238, 41
	v_readlane_b32 s73, v238, 42
	v_readlane_b32 s74, v238, 43
	v_readlane_b32 s75, v238, 44
	s_waitcnt vmcnt(0)
	v_mov_b32_e32 v8, v39
	v_mov_b32_e32 v60, v41
.LBB0_162:
	v_or_b32_e32 v3, s11, v64
	v_mad_u32_u24 v42, v3, s19, s19
	v_lshl_add_u64 v[12:13], v[58:59], 0, v[42:43]
	v_mad_u32_u24 v42, v3, s19, v86
	v_lshl_add_u64 v[26:27], v[58:59], 0, v[42:43]
	v_mad_u32_u24 v42, v3, s19, v87
	v_mad_u64_u32 v[10:11], s[12:13], v3, s19, v[58:59]
	v_lshl_add_u64 v[28:29], v[58:59], 0, v[42:43]
	global_load_dwordx4 v[18:21], v[10:11], off nt
	s_nop 0
	global_load_dwordx4 v[10:13], v[12:13], off nt
	s_nop 0
	global_load_dwordx4 v[34:37], v[26:27], off nt
	s_nop 0
	global_load_dwordx4 v[26:29], v[28:29], off nt
	s_waitcnt vmcnt(0)
	v_pk_mul_f32 v[14:15], v[14:15], v[38:39] op_sel_hi:[1,0]
	v_pk_mul_f32 v[4:5], v[4:5], v[8:9] op_sel_hi:[1,0]
	v_pk_mul_f32 v[30:31], v[30:31], v[40:41] op_sel_hi:[1,0]
	v_pk_mul_f32 v[22:23], v[22:23], v[60:61] op_sel_hi:[1,0]
	v_pk_mul_f32 v[16:17], v[16:17], v[38:39] op_sel_hi:[1,0]
	v_pk_mul_f32 v[6:7], v[6:7], v[8:9] op_sel_hi:[1,0]
	v_pk_mul_f32 v[8:9], v[32:33], v[40:41] op_sel_hi:[1,0]
	v_pk_mul_f32 v[24:25], v[24:25], v[60:61] op_sel_hi:[1,0]
	v_cvt_pk_bf16_f32 v32, v14, v4
	v_cvt_pk_bf16_f32 v33, v30, v22
	v_add_u32_e32 v14, v61, v63
	v_cvt_pk_bf16_f32 v4, v15, v5
	v_cvt_pk_bf16_f32 v5, v31, v23
	ds_write2_b64 v14, v[32:33], v[4:5] offset1:16
	v_cvt_pk_bf16_f32 v4, v16, v6
	v_cvt_pk_bf16_f32 v5, v8, v24
	v_cvt_pk_bf16_f32 v6, v17, v7
	v_cvt_pk_bf16_f32 v7, v9, v25
	ds_write2_b64 v14, v[4:5], v[6:7] offset0:32 offset1:48
	s_and_b64 vcc, exec, s[6:7]
	v_mov_b32_e32 v38, 1.0
	v_mov_b32_e32 v4, 1.0
	v_mov_b32_e32 v40, 1.0
	s_cbranch_vccnz .LBB0_164
	v_readlane_b32 s60, v238, 29
	v_lshlrev_b32_e32 v2, 2, v3
	v_readlane_b32 s66, v238, 35
	v_readlane_b32 s67, v238, 36
	v_readlane_b32 s61, v238, 30
	v_readlane_b32 s62, v238, 31
	v_readlane_b32 s63, v238, 32
	v_readlane_b32 s64, v238, 33
	v_readlane_b32 s65, v238, 34
	global_load_dwordx4 v[2:5], v2, s[66:67]
	v_readlane_b32 s68, v238, 37
	v_readlane_b32 s69, v238, 38
	v_readlane_b32 s70, v238, 39
	v_readlane_b32 s71, v238, 40
	v_readlane_b32 s72, v238, 41
	v_readlane_b32 s73, v238, 42
	v_readlane_b32 s74, v238, 43
	v_readlane_b32 s75, v238, 44
	s_waitcnt vmcnt(0)
	v_mov_b32_e32 v38, v3
	v_mov_b32_e32 v40, v5
; #define GAS __attribute__((address_space(1)))
; #define LAS __attribute__((address_space(3)))
; __device__ __forceinline__ unsigned pk2(float lo, float hi) { f32x2_t v = {lo, hi}; bf16x2_t h = __builtin_convertvector(v, bf16x2_t); return __builtin_bit_cast(unsigned, h); }
; __device__ __forceinline__ void transpose_item(const float* W, int ldw, bf16* WT, int K, int k0, int sn0, int dn0, int lane, LAS unsigned char* T, const float* kgain = nullptr) {
;     const int nb = lane & 15, kq = lane >> 4;
; #pragma unroll
;     for (int j = 0; j < 4; ++j) { const int kb = kq + 4 * j, k = k0 + 4 * kb; f32x4 r[4];
; #pragma unroll
;         for (int jj = 0; jj < 4; ++jj) r[jj] = *(const GAS f32x4*)(W + (size_t)(k + jj) * ldw + sn0 + 4 * nb);
;         f32x4 g = {1.f, 1.f, 1.f, 1.f}; if (kgain) g = *(const GAS f32x4*)(kgain + k);
;         const f32x4 a = r[0] * g.x, bq = r[1] * g.y, c = r[2] * g.z, d = r[3] * g.w;
;         LAS unsigned char* t = T + (4 * nb) * 128 + ((kb ^ nb) << 3);
;         v2u w; w.x = pk2(a.x, bq.x); w.y = pk2(c.x, d.x); *(LAS v2u*)t = w;
;         w.x = pk2(a.y, bq.y); w.y = pk2(c.y, d.y); *(LAS v2u*)(t + 128) = w;
;         w.x = pk2(a.z, bq.z); w.y = pk2(c.z, d.z); *(LAS v2u*)(t + 256) = w;
;         w.x = pk2(a.w, bq.w); w.y = pk2(c.w, d.w); *(LAS v2u*)(t + 384) = w; }
.LBB0_164:
	v_or_b32_e32 v3, s11, v66
	v_mad_u32_u24 v42, v3, s19, s19
	v_lshl_add_u64 v[8:9], v[58:59], 0, v[42:43]
	v_mad_u32_u24 v42, v3, s19, v86
	v_lshl_add_u64 v[22:23], v[58:59], 0, v[42:43]
	v_mad_u32_u24 v42, v3, s19, v87
	v_mad_u64_u32 v[6:7], s[12:13], v3, s19, v[58:59]
	v_lshl_add_u64 v[24:25], v[58:59], 0, v[42:43]
	global_load_dwordx4 v[14:17], v[6:7], off nt
	s_nop 0
	global_load_dwordx4 v[6:9], v[8:9], off nt
	s_nop 0
	global_load_dwordx4 v[30:33], v[22:23], off nt
	s_nop 0
	global_load_dwordx4 v[22:25], v[24:25], off nt
	v_pk_mul_f32 v[18:19], v[18:19], v[2:3] op_sel_hi:[1,0]
	v_pk_mul_f32 v[10:11], v[10:11], v[38:39] op_sel_hi:[1,0]
	v_pk_mul_f32 v[36:37], v[36:37], v[4:5] op_sel_hi:[1,0]
	v_pk_mul_f32 v[4:5], v[34:35], v[4:5] op_sel_hi:[1,0]
	v_pk_mul_f32 v[26:27], v[26:27], v[40:41] op_sel_hi:[1,0]
	v_pk_mul_f32 v[20:21], v[20:21], v[2:3] op_sel_hi:[1,0]
	v_pk_mul_f32 v[12:13], v[12:13], v[38:39] op_sel_hi:[1,0]
	v_pk_mul_f32 v[28:29], v[28:29], v[40:41] op_sel_hi:[1,0]
	v_cvt_pk_bf16_f32 v34, v18, v10
	v_cvt_pk_bf16_f32 v35, v4, v26
	v_add_u32_e32 v2, v61, v65
	v_cvt_pk_bf16_f32 v4, v19, v11
	v_cvt_pk_bf16_f32 v5, v5, v27
	ds_write2_b64 v2, v[34:35], v[4:5] offset1:16
	v_cvt_pk_bf16_f32 v4, v20, v12
	v_cvt_pk_bf16_f32 v5, v36, v28
	v_cvt_pk_bf16_f32 v10, v21, v13
	v_cvt_pk_bf16_f32 v11, v37, v29
	ds_write2_b64 v2, v[4:5], v[10:11] offset0:32 offset1:48
	v_mov_b32_e32 v2, 1.0
	s_and_b64 vcc, exec, s[6:7]
	v_mov_b32_e32 v10, 1.0
	v_mov_b32_e32 v4, 1.0
	v_mov_b32_e32 v12, 1.0
	v_mov_b32_e32 v60, 1.0
	s_cbranch_vccnz .LBB0_166
	v_readlane_b32 s60, v238, 29
	v_lshlrev_b32_e32 v3, 2, v3
	v_readlane_b32 s66, v238, 35
	v_readlane_b32 s67, v238, 36
	v_readlane_b32 s61, v238, 30
	v_readlane_b32 s62, v238, 31
	v_readlane_b32 s63, v238, 32
	v_readlane_b32 s64, v238, 33
	v_readlane_b32 s65, v238, 34
	global_load_dwordx4 v[10:13], v3, s[66:67]
	v_readlane_b32 s68, v238, 37
	v_readlane_b32 s69, v238, 38
	v_readlane_b32 s70, v238, 39
	v_readlane_b32 s71, v238, 40
	v_readlane_b32 s72, v238, 41
	v_readlane_b32 s73, v238, 42
	v_readlane_b32 s74, v238, 43
	v_readlane_b32 s75, v238, 44
	s_waitcnt vmcnt(0)
	v_mov_b32_e32 v4, v11
	v_mov_b32_e32 v60, v13
.LBB0_166:
	v_or_b32_e32 v3, s11, v68
	v_mad_u32_u24 v42, v3, s19, s19
	v_lshl_add_u64 v[20:21], v[58:59], 0, v[42:43]
	v_mad_u32_u24 v42, v3, s19, v86
	v_lshl_add_u64 v[26:27], v[58:59], 0, v[42:43]
	v_mad_u32_u24 v42, v3, s19, v87
	v_mad_u64_u32 v[18:19], s[12:13], v3, s19, v[58:59]
	v_lshl_add_u64 v[28:29], v[58:59], 0, v[42:43]
	global_load_dwordx4 v[34:37], v[18:19], off nt
	s_nop 0
	global_load_dwordx4 v[18:21], v[20:21], off nt
	s_nop 0
	global_load_dwordx4 v[38:41], v[26:27], off nt
	s_nop 0
	global_load_dwordx4 v[26:29], v[28:29], off nt
	s_waitcnt vmcnt(7)
	v_pk_mul_f32 v[16:17], v[16:17], v[10:11] op_sel_hi:[1,0]
	v_pk_mul_f32 v[10:11], v[14:15], v[10:11] op_sel_hi:[1,0]
	s_waitcnt vmcnt(6)
	v_pk_mul_f32 v[8:9], v[8:9], v[4:5] op_sel_hi:[1,0]
	v_pk_mul_f32 v[4:5], v[6:7], v[4:5] op_sel_hi:[1,0]
	s_waitcnt vmcnt(5)
	v_pk_mul_f32 v[6:7], v[32:33], v[12:13] op_sel_hi:[1,0]
	v_pk_mul_f32 v[12:13], v[30:31], v[12:13] op_sel_hi:[1,0]
	s_waitcnt vmcnt(4)
	v_pk_mul_f32 v[22:23], v[22:23], v[60:61] op_sel_hi:[1,0]
	v_pk_mul_f32 v[14:15], v[24:25], v[60:61] op_sel_hi:[1,0]
	v_cvt_pk_bf16_f32 v24, v10, v4
	v_cvt_pk_bf16_f32 v25, v12, v22
	v_add_u32_e32 v10, v61, v67
	v_cvt_pk_bf16_f32 v4, v11, v5
	v_cvt_pk_bf16_f32 v5, v13, v23
	ds_write2_b64 v10, v[24:25], v[4:5] offset1:16
	v_cvt_pk_bf16_f32 v4, v16, v8
	v_cvt_pk_bf16_f32 v5, v6, v14
	v_cvt_pk_bf16_f32 v6, v17, v9
	v_cvt_pk_bf16_f32 v7, v7, v15
	ds_write2_b64 v10, v[4:5], v[6:7] offset0:32 offset1:48
	s_and_b64 vcc, exec, s[6:7]
	v_mov_b32_e32 v8, 1.0
	v_mov_b32_e32 v4, 1.0
	v_mov_b32_e32 v6, 1.0
	s_cbranch_vccnz .LBB0_168
	v_readlane_b32 s60, v238, 29
	v_lshlrev_b32_e32 v2, 2, v3
	v_readlane_b32 s66, v238, 35
	v_readlane_b32 s67, v238, 36
	v_readlane_b32 s61, v238, 30
	v_readlane_b32 s62, v238, 31
	v_readlane_b32 s63, v238, 32
	v_readlane_b32 s64, v238, 33
	v_readlane_b32 s65, v238, 34
	global_load_dwordx4 v[2:5], v2, s[66:67]
	v_readlane_b32 s68, v238, 37
	v_readlane_b32 s69, v238, 38
	v_readlane_b32 s70, v238, 39
	v_readlane_b32 s71, v238, 40
	v_readlane_b32 s72, v238, 41
	v_readlane_b32 s73, v238, 42
	v_readlane_b32 s74, v238, 43
	v_readlane_b32 s75, v238, 44
	s_waitcnt vmcnt(0)
	v_mov_b32_e32 v8, v3
	v_mov_b32_e32 v6, v5

; #define GAS __attribute__((address_space(1)))
; __device__ __forceinline__ void transpose_item(const float* W, int ldw, bf16* WT, int K, int k0, int sn0, int dn0, int lane, LAS unsigned char* T, const float* kgain = nullptr) {
;     ...
;     for (int j = 0; j < 4; ++j) { const int kb = kq + 4 * j, k = k0 + 4 * kb; f32x4 r[4];
; #pragma unroll
;         for (int jj = 0; jj < 4; ++jj) r[jj] = *(const GAS f32x4*)(W + (size_t)(k + jj) * ldw + sn0 + 4 * nb);
;         f32x4 g = {1.f, 1.f, 1.f, 1.f}; if (kgain) g = *(const GAS f32x4*)(kgain + k);
; template <int PART> __device__ __forceinline__ void deferred_transposes(Frame& F, int gw, int ngw) {
;     ...
;     for (int it = gw; it < NITEMS; it += ngw) {
;         int r = (PART == 0) ? it : it + N0;
;         if (r < I_GLU) { const int nblk = S5W / 64, kb = r / nblk, nb = r % nblk; transpose_item(F.in[16], S5W, WgluT, S5W, kb * 64, nb * 64, nb * 64, F.lane, F.lds + F.wave * 8192); continue; } r -= I_GLU;
;         if (r < I_OUT) { const int nblk = DM / 64, kb = r / nblk, nb = r % nblk; transpose_item(F.in[18], DM, WoutT, DM, kb * 64, nb * 64, nb * 64, F.lane, F.lds + F.wave * 8192); continue; } r -= I_OUT;
;         if (r < I_G) { const int nblk = DFF / 64, kb = r / nblk, nb = r % nblk, sn0 = nb * 64; transpose_item(F.in[20], DFF, WguT, DM, kb * 64, sn0, 256 * (sn0 / 128) + (sn0 % 128), F.lane, F.lds + F.wave * 8192, F.in[19]); continue; } r -= I_G;
.LBB0_169:
	s_and_b64 vcc, exec, s[12:13]
	s_cbranch_vccz .LBB0_184
	s_add_i32 s4, s3, 0xfec0
	s_and_b32 s10, s4, 0xffff
	s_mul_i32 s10, s10, 0xba2f
	s_lshr_b32 s11, s10, 21
	s_mul_i32 s10, s11, 44
	s_sub_i32 s4, s4, s10
	s_and_b32 s10, s4, 0xffff
	s_lshl_b32 s11, s11, 6
	s_lshl_b32 s4, s10, 8
	v_or_b32_e32 v3, s11, v62
	v_lshl_add_u64 v[58:59], v[48:49], 0, s[4:5]
	v_mad_u32_u24 v42, v3, s19, s19
	v_lshl_add_u64 v[6:7], v[58:59], 0, v[42:43]
	v_mad_u32_u24 v42, v3, s19, v86
	v_mad_u64_u32 v[4:5], s[12:13], v3, s19, v[58:59]
	v_lshl_add_u64 v[8:9], v[58:59], 0, v[42:43]
	v_mad_u32_u24 v42, v3, s19, v87
	global_load_dwordx4 v[14:17], v[4:5], off nt
	s_nop 0
	global_load_dwordx4 v[4:7], v[6:7], off nt
	v_lshl_add_u64 v[10:11], v[58:59], 0, v[42:43]
	global_load_dwordx4 v[30:33], v[8:9], off nt
	global_load_dwordx4 v[22:25], v[10:11], off nt
	v_mov_b32_e32 v2, 1.0
	s_and_b64 vcc, exec, s[6:7]
	v_mov_b32_e32 v38, 1.0
	v_mov_b32_e32 v8, 1.0
	v_mov_b32_e32 v40, 1.0
	v_mov_b32_e32 v60, 1.0
	s_cbranch_vccnz .LBB0_172
	v_readlane_b32 s60, v238, 29
	v_lshlrev_b32_e32 v3, 2, v3
	v_readlane_b32 s66, v238, 35
	v_readlane_b32 s67, v238, 36
	v_readlane_b32 s61, v238, 30
	v_readlane_b32 s62, v238, 31
	v_readlane_b32 s63, v238, 32
	v_readlane_b32 s64, v238, 33
	v_readlane_b32 s65, v238, 34
	global_load_dwordx4 v[38:41], v3, s[66:67]
	v_readlane_b32 s68, v238, 37
	v_readlane_b32 s69, v238, 38
	v_readlane_b32 s70, v238, 39
	v_readlane_b32 s71, v238, 40
	v_readlane_b32 s72, v238, 41
	v_readlane_b32 s73, v238, 42
	v_readlane_b32 s74, v238, 43
	v_readlane_b32 s75, v238, 44
	s_waitcnt vmcnt(0)
	v_mov_b32_e32 v8, v39
	v_mov_b32_e32 v60, v41

; #define GAS __attribute__((address_space(1)))
; #define LAS __attribute__((address_space(3)))
; __device__ __forceinline__ unsigned pk2(float lo, float hi) { f32x2_t v = {lo, hi}; bf16x2_t h = __builtin_convertvector(v, bf16x2_t); return __builtin_bit_cast(unsigned, h); }
; __device__ __forceinline__ void transpose_item(const float* W, int ldw, bf16* WT, int K, int k0, int sn0, int dn0, int lane, LAS unsigned char* T, const float* kgain = nullptr) {
;     const int nb = lane & 15, kq = lane >> 4;
; #pragma unroll
;     for (int j = 0; j < 4; ++j) { const int kb = kq + 4 * j, k = k0 + 4 * kb; f32x4 r[4];
; #pragma unroll
;         for (int jj = 0; jj < 4; ++jj) r[jj] = *(const GAS f32x4*)(W + (size_t)(k + jj) * ldw + sn0 + 4 * nb);
;         f32x4 g = {1.f, 1.f, 1.f, 1.f}; if (kgain) g = *(const GAS f32x4*)(kgain + k);
;         const f32x4 a = r[0] * g.x, bq = r[1] * g.y, c = r[2] * g.z, d = r[3] * g.w;
;         LAS unsigned char* t = T + (4 * nb) * 128 + ((kb ^ nb) << 3);
;         v2u w; w.x = pk2(a.x, bq.x); w.y = pk2(c.x, d.x); *(LAS v2u*)t = w;
;         w.x = pk2(a.y, bq.y); w.y = pk2(c.y, d.y); *(LAS v2u*)(t + 128) = w;
;         w.x = pk2(a.z, bq.z); w.y = pk2(c.z, d.z); *(LAS v2u*)(t + 256) = w;
;         w.x = pk2(a.w, bq.w); w.y = pk2(c.w, d.w); *(LAS v2u*)(t + 384) = w; }
; template <int PART> __device__ __forceinline__ void deferred_transposes(Frame& F, int gw, int ngw) {
;     ...
;         if (r < I_OUT) { const int nblk = DM / 64, kb = r / nblk, nb = r % nblk; transpose_item(F.in[18], DM, WoutT, DM, kb * 64, nb * 64, nb * 64, F.lane, F.lds + F.wave * 8192); continue; } r -= I_OUT;
.LBB0_180:
	s_and_b32 s4, s17, 0x7c0
	s_add_i32 s12, s4, 0xffffff00
	v_or_b32_e32 v42, s12, v62
	s_and_b32 s10, s15, 0x3c0
	v_lshlrev_b64 v[2:3], 12, v[42:43]
	v_or_b32_e32 v4, 1, v42
	v_or_b32_e32 v10, 2, v42
	v_or_b32_e32 v42, 3, v42
	s_lshl_b32 s4, s10, 2
	v_mov_b32_e32 v5, v43
	v_mov_b32_e32 v11, v43
	v_lshlrev_b64 v[12:13], 12, v[42:43]
	v_or_b32_e32 v42, s12, v64
	v_lshl_add_u64 v[58:59], v[50:51], 0, s[4:5]
	v_lshlrev_b64 v[4:5], 12, v[4:5]
	v_lshlrev_b64 v[10:11], 12, v[10:11]
	v_lshlrev_b64 v[18:19], 12, v[42:43]
	v_or_b32_e32 v20, 1, v42
	v_mov_b32_e32 v21, v43
	v_or_b32_e32 v26, 2, v42
	v_mov_b32_e32 v27, v43
	v_or_b32_e32 v42, 3, v42
	v_lshl_add_u64 v[2:3], v[58:59], 0, v[2:3]
	v_lshl_add_u64 v[6:7], v[58:59], 0, v[4:5]
	v_lshl_add_u64 v[10:11], v[58:59], 0, v[10:11]
	v_lshl_add_u64 v[14:15], v[58:59], 0, v[12:13]
	v_lshlrev_b64 v[20:21], 12, v[20:21]
	v_lshlrev_b64 v[26:27], 12, v[26:27]
	v_lshlrev_b64 v[28:29], 12, v[42:43]
	v_or_b32_e32 v42, s12, v66
	global_load_dwordx4 v[2:5], v[2:3], off nt
	s_nop 0
	global_load_dwordx4 v[6:9], v[6:7], off nt
	s_nop 0
	global_load_dwordx4 v[10:13], v[10:11], off nt
	s_nop 0
	global_load_dwordx4 v[14:17], v[14:15], off nt
	v_lshl_add_u64 v[18:19], v[58:59], 0, v[18:19]
	v_lshl_add_u64 v[22:23], v[58:59], 0, v[20:21]
	v_lshl_add_u64 v[26:27], v[58:59], 0, v[26:27]
	v_lshl_add_u64 v[30:31], v[58:59], 0, v[28:29]
	v_lshlrev_b64 v[34:35], 12, v[42:43]
	v_or_b32_e32 v36, 1, v42
	v_mov_b32_e32 v37, v43
	v_or_b32_e32 v88, 2, v42
	v_mov_b32_e32 v89, v43
	v_or_b32_e32 v42, 3, v42
	global_load_dwordx4 v[18:21], v[18:19], off nt
	s_nop 0
	global_load_dwordx4 v[22:25], v[22:23], off nt
	s_nop 0
	global_load_dwordx4 v[26:29], v[26:27], off nt
	s_nop 0
	global_load_dwordx4 v[30:33], v[30:31], off nt
	v_lshlrev_b64 v[36:37], 12, v[36:37]
	v_lshlrev_b64 v[88:89], 12, v[88:89]
	v_lshlrev_b64 v[90:91], 12, v[42:43]
	v_or_b32_e32 v42, s12, v68
	v_lshl_add_u64 v[34:35], v[58:59], 0, v[34:35]
	v_lshl_add_u64 v[38:39], v[58:59], 0, v[36:37]
	v_lshl_add_u64 v[88:89], v[58:59], 0, v[88:89]
	v_lshl_add_u64 v[92:93], v[58:59], 0, v[90:91]
	v_or_b32_e32 v98, 1, v42
	v_mov_b32_e32 v99, v43
	v_or_b32_e32 v104, 2, v42
	v_mov_b32_e32 v105, v43
	global_load_dwordx4 v[34:37], v[34:35], off nt
	s_nop 0
	global_load_dwordx4 v[38:41], v[38:39], off nt
	s_nop 0
	global_load_dwordx4 v[88:91], v[88:89], off nt
	s_nop 0
	global_load_dwordx4 v[92:95], v[92:93], off nt
	v_lshlrev_b64 v[96:97], 12, v[42:43]
	v_lshlrev_b64 v[98:99], 12, v[98:99]
	v_lshlrev_b64 v[104:105], 12, v[104:105]
	v_or_b32_e32 v42, 3, v42
	v_lshl_add_u64 v[96:97], v[58:59], 0, v[96:97]
	v_lshl_add_u64 v[100:101], v[58:59], 0, v[98:99]
	v_lshl_add_u64 v[104:105], v[58:59], 0, v[104:105]
	v_lshlrev_b64 v[106:107], 12, v[42:43]
	global_load_dwordx4 v[96:99], v[96:97], off nt
	s_nop 0
	global_load_dwordx4 v[100:103], v[100:101], off nt
	v_lshl_add_u64 v[58:59], v[58:59], 0, v[106:107]
	global_load_dwordx4 v[104:107], v[104:105], off nt
	s_nop 0
	global_load_dwordx4 v[108:111], v[58:59], off nt
	v_add_u32_e32 v42, v61, v63
	s_mov_b32 s13, s5
	s_waitcnt vmcnt(0)
	v_cvt_pk_bf16_f32 v58, v2, v6
	v_cvt_pk_bf16_f32 v59, v10, v14
	v_cvt_pk_bf16_f32 v2, v3, v7
	v_cvt_pk_bf16_f32 v3, v11, v15
	v_cvt_pk_bf16_f32 v6, v4, v8
	v_cvt_pk_bf16_f32 v4, v5, v9
	v_cvt_pk_bf16_f32 v5, v13, v17
	v_cvt_pk_bf16_f32 v7, v12, v16
	ds_write2_b64 v42, v[58:59], v[2:3] offset1:16
	ds_write2_b64 v42, v[6:7], v[4:5] offset0:32 offset1:48
	v_add_u32_e32 v6, v61, v65
	v_cvt_pk_bf16_f32 v2, v18, v22
	v_cvt_pk_bf16_f32 v3, v26, v30
	v_cvt_pk_bf16_f32 v4, v19, v23
	v_cvt_pk_bf16_f32 v5, v27, v31
	ds_write2_b64 v6, v[2:3], v[4:5] offset1:16
	v_cvt_pk_bf16_f32 v2, v20, v24
	v_cvt_pk_bf16_f32 v3, v28, v32
	v_cvt_pk_bf16_f32 v4, v21, v25
	v_cvt_pk_bf16_f32 v5, v29, v33
	ds_write2_b64 v6, v[2:3], v[4:5] offset0:32 offset1:48
	v_add_u32_e32 v6, v61, v67
	v_cvt_pk_bf16_f32 v2, v34, v38
	v_cvt_pk_bf16_f32 v3, v88, v92
	v_cvt_pk_bf16_f32 v4, v35, v39
	v_cvt_pk_bf16_f32 v5, v89, v93
	ds_write2_b64 v6, v[2:3], v[4:5] offset1:16
	v_cvt_pk_bf16_f32 v2, v36, v40
	v_cvt_pk_bf16_f32 v3, v90, v94
	v_cvt_pk_bf16_f32 v4, v37, v41
	v_cvt_pk_bf16_f32 v5, v91, v95
	ds_write2_b64 v6, v[2:3], v[4:5] offset0:32 offset1:48
	v_cvt_pk_bf16_f32 v2, v96, v100
	v_add_u32_e32 v6, v61, v69
	v_cvt_pk_bf16_f32 v3, v104, v108
	v_cvt_pk_bf16_f32 v4, v97, v101
	v_cvt_pk_bf16_f32 v5, v105, v109
	ds_write2_b64 v6, v[2:3], v[4:5] offset1:16
	v_cvt_pk_bf16_f32 v2, v98, v102
	v_cvt_pk_bf16_f32 v3, v106, v110
	v_cvt_pk_bf16_f32 v4, v99, v103
	v_cvt_pk_bf16_f32 v5, v107, v111
	ds_write2_b64 v6, v[2:3], v[4:5] offset0:32 offset1:48
	v_lshl_add_u64 v[2:3], s[12:13], 1, v[52:53]

; #define GAS __attribute__((address_space(1)))
; #define LAS __attribute__((address_space(3)))
; __device__ __forceinline__ unsigned pk2(float lo, float hi) { f32x2_t v = {lo, hi}; bf16x2_t h = __builtin_convertvector(v, bf16x2_t); return __builtin_bit_cast(unsigned, h); }
; __device__ __forceinline__ void transpose_item(const float* W, int ldw, bf16* WT, int K, int k0, int sn0, int dn0, int lane, LAS unsigned char* T, const float* kgain = nullptr) {
;     const int nb = lane & 15, kq = lane >> 4;
; #pragma unroll
;     for (int j = 0; j < 4; ++j) { const int kb = kq + 4 * j, k = k0 + 4 * kb; f32x4 r[4];
; #pragma unroll
;         for (int jj = 0; jj < 4; ++jj) r[jj] = *(const GAS f32x4*)(W + (size_t)(k + jj) * ldw + sn0 + 4 * nb);
;         f32x4 g = {1.f, 1.f, 1.f, 1.f}; if (kgain) g = *(const GAS f32x4*)(kgain + k);
;         const f32x4 a = r[0] * g.x, bq = r[1] * g.y, c = r[2] * g.z, d = r[3] * g.w;
;         LAS unsigned char* t = T + (4 * nb) * 128 + ((kb ^ nb) << 3);
;         v2u w; w.x = pk2(a.x, bq.x); w.y = pk2(c.x, d.x); *(LAS v2u*)t = w;
;         w.x = pk2(a.y, bq.y); w.y = pk2(c.y, d.y); *(LAS v2u*)(t + 128) = w;
;         w.x = pk2(a.z, bq.z); w.y = pk2(c.z, d.z); *(LAS v2u*)(t + 256) = w;
;         w.x = pk2(a.w, bq.w); w.y = pk2(c.w, d.w); *(LAS v2u*)(t + 384) = w; }
; template <int PART> __device__ __forceinline__ void deferred_transposes(Frame& F, int gw, int ngw) {
;     ...
;         if (r < I_GLU) { const int nblk = S5W / 64, kb = r / nblk, nb = r % nblk; transpose_item(F.in[16], S5W, WgluT, S5W, kb * 64, nb * 64, nb * 64, F.lane, F.lds + F.wave * 8192); continue; } r -= I_GLU;
.LBB0_182:
	s_andn2_b64 vcc, exec, s[12:13]
	s_mov_b64 s[12:13], 11
	s_cbranch_vccnz .LBB0_156
	s_ashr_i32 s4, s3, 31
	s_lshr_b32 s4, s4, 29
	s_add_i32 s4, s3, s4
	s_ashr_i32 s4, s4, 3
	s_lshl_b32 s12, s4, 6
	v_or_b32_e32 v10, s12, v62
	s_lshl_b32 s4, s4, 9
	v_ashrrev_i32_e32 v11, 31, v10
	s_sub_i32 s10, s15, s4
	v_lshlrev_b64 v[2:3], 11, v[10:11]
	v_or_b32_e32 v4, 1, v10
	v_or_b32_e32 v12, 2, v10
	v_or_b32_e32 v10, 3, v10
	v_or_b32_e32 v26, s12, v64
	s_ashr_i32 s11, s10, 31
	v_ashrrev_i32_e32 v5, 31, v4
	v_ashrrev_i32_e32 v13, 31, v12
	v_ashrrev_i32_e32 v11, 31, v10
	v_ashrrev_i32_e32 v27, 31, v26
	v_lshl_add_u64 v[58:59], s[10:11], 2, v[54:55]
	v_lshlrev_b64 v[4:5], 11, v[4:5]
	v_lshlrev_b64 v[12:13], 11, v[12:13]
	v_lshlrev_b64 v[10:11], 11, v[10:11]
	v_lshlrev_b64 v[18:19], 11, v[26:27]
	v_or_b32_e32 v20, 1, v26
	v_or_b32_e32 v28, 2, v26
	v_or_b32_e32 v26, 3, v26
	v_or_b32_e32 v88, s12, v66
	v_lshl_add_u64 v[2:3], v[58:59], 0, v[2:3]
	v_lshl_add_u64 v[6:7], v[58:59], 0, v[4:5]
	v_lshl_add_u64 v[12:13], v[58:59], 0, v[12:13]
	v_lshl_add_u64 v[14:15], v[58:59], 0, v[10:11]
	v_ashrrev_i32_e32 v21, 31, v20
	v_ashrrev_i32_e32 v29, 31, v28
	v_ashrrev_i32_e32 v27, 31, v26
	v_ashrrev_i32_e32 v89, 31, v88
	global_load_dwordx4 v[2:5], v[2:3], off nt
	s_nop 0
	global_load_dwordx4 v[6:9], v[6:7], off nt
	s_nop 0
	global_load_dwordx4 v[10:13], v[12:13], off nt
	s_nop 0
	global_load_dwordx4 v[14:17], v[14:15], off nt
	v_lshlrev_b64 v[20:21], 11, v[20:21]
	v_lshlrev_b64 v[28:29], 11, v[28:29]
	v_lshlrev_b64 v[26:27], 11, v[26:27]
	v_lshlrev_b64 v[34:35], 11, v[88:89]
	v_or_b32_e32 v36, 1, v88
	v_or_b32_e32 v90, 2, v88
	v_or_b32_e32 v88, 3, v88
	v_lshl_add_u64 v[18:19], v[58:59], 0, v[18:19]
	v_lshl_add_u64 v[22:23], v[58:59], 0, v[20:21]
	v_lshl_add_u64 v[28:29], v[58:59], 0, v[28:29]
	v_lshl_add_u64 v[30:31], v[58:59], 0, v[26:27]
	v_ashrrev_i32_e32 v37, 31, v36
	v_ashrrev_i32_e32 v91, 31, v90
	v_ashrrev_i32_e32 v89, 31, v88
	v_or_b32_e32 v104, s12, v68
	global_load_dwordx4 v[18:21], v[18:19], off nt
	s_nop 0
	global_load_dwordx4 v[22:25], v[22:23], off nt
	s_nop 0
	global_load_dwordx4 v[26:29], v[28:29], off nt
	s_nop 0
	global_load_dwordx4 v[30:33], v[30:31], off nt
	v_lshlrev_b64 v[36:37], 11, v[36:37]
	v_lshlrev_b64 v[90:91], 11, v[90:91]
	v_lshlrev_b64 v[88:89], 11, v[88:89]
	v_ashrrev_i32_e32 v105, 31, v104
	v_or_b32_e32 v98, 1, v104
	v_or_b32_e32 v106, 2, v104
	v_lshl_add_u64 v[34:35], v[58:59], 0, v[34:35]
	v_lshl_add_u64 v[38:39], v[58:59], 0, v[36:37]
	v_lshl_add_u64 v[90:91], v[58:59], 0, v[90:91]
	v_lshl_add_u64 v[92:93], v[58:59], 0, v[88:89]
	v_lshlrev_b64 v[96:97], 11, v[104:105]
	v_ashrrev_i32_e32 v99, 31, v98
	v_ashrrev_i32_e32 v107, 31, v106
	v_or_b32_e32 v104, 3, v104
	global_load_dwordx4 v[34:37], v[34:35], off nt
	s_nop 0
	global_load_dwordx4 v[38:41], v[38:39], off nt
	s_nop 0
	global_load_dwordx4 v[88:91], v[90:91], off nt
	s_nop 0
	global_load_dwordx4 v[92:95], v[92:93], off nt
	v_lshlrev_b64 v[98:99], 11, v[98:99]
	v_lshlrev_b64 v[106:107], 11, v[106:107]
	v_ashrrev_i32_e32 v105, 31, v104
	v_lshl_add_u64 v[96:97], v[58:59], 0, v[96:97]
	v_lshl_add_u64 v[100:101], v[58:59], 0, v[98:99]
	v_lshl_add_u64 v[106:107], v[58:59], 0, v[106:107]
	v_lshlrev_b64 v[104:105], 11, v[104:105]
	global_load_dwordx4 v[96:99], v[96:97], off nt
	s_nop 0
	global_load_dwordx4 v[100:103], v[100:101], off nt
	v_lshl_add_u64 v[58:59], v[58:59], 0, v[104:105]
	global_load_dwordx4 v[104:107], v[106:107], off nt
	s_nop 0
	global_load_dwordx4 v[108:111], v[58:59], off nt
	s_ashr_i32 s13, s12, 31
	s_waitcnt vmcnt(0)
	v_cvt_pk_bf16_f32 v58, v2, v6
	v_cvt_pk_bf16_f32 v59, v10, v14
	v_add_u32_e32 v6, v61, v63
	v_cvt_pk_bf16_f32 v2, v3, v7
	v_cvt_pk_bf16_f32 v3, v11, v15
	ds_write2_b64 v6, v[58:59], v[2:3] offset1:16
	v_cvt_pk_bf16_f32 v2, v4, v8
	v_cvt_pk_bf16_f32 v3, v12, v16
	v_cvt_pk_bf16_f32 v4, v5, v9
	v_cvt_pk_bf16_f32 v5, v13, v17
	ds_write2_b64 v6, v[2:3], v[4:5] offset0:32 offset1:48
	v_add_u32_e32 v6, v61, v65
	v_cvt_pk_bf16_f32 v2, v18, v22
	v_cvt_pk_bf16_f32 v3, v26, v30
	v_cvt_pk_bf16_f32 v4, v19, v23
	v_cvt_pk_bf16_f32 v5, v27, v31
	ds_write2_b64 v6, v[2:3], v[4:5] offset1:16
	v_cvt_pk_bf16_f32 v2, v20, v24
	v_cvt_pk_bf16_f32 v3, v28, v32
	v_cvt_pk_bf16_f32 v4, v21, v25
	v_cvt_pk_bf16_f32 v5, v29, v33
	ds_write2_b64 v6, v[2:3], v[4:5] offset0:32 offset1:48
	v_add_u32_e32 v6, v61, v67
	v_cvt_pk_bf16_f32 v2, v34, v38
	v_cvt_pk_bf16_f32 v3, v88, v92
	v_cvt_pk_bf16_f32 v4, v35, v39
	v_cvt_pk_bf16_f32 v5, v89, v93
	ds_write2_b64 v6, v[2:3], v[4:5] offset1:16
	v_cvt_pk_bf16_f32 v2, v36, v40
	v_cvt_pk_bf16_f32 v3, v90, v94
	v_cvt_pk_bf16_f32 v4, v37, v41
	v_cvt_pk_bf16_f32 v5, v91, v95
	ds_write2_b64 v6, v[2:3], v[4:5] offset0:32 offset1:48
	v_cvt_pk_bf16_f32 v2, v96, v100
	v_cvt_pk_bf16_f32 v3, v104, v108
	v_add_u32_e32 v6, v61, v69
	v_cvt_pk_bf16_f32 v4, v97, v101
	v_cvt_pk_bf16_f32 v5, v105, v109
	ds_write2_b64 v6, v[2:3], v[4:5] offset1:16
	v_cvt_pk_bf16_f32 v2, v98, v102
	v_cvt_pk_bf16_f32 v3, v106, v110
	v_cvt_pk_bf16_f32 v4, v99, v103
	v_cvt_pk_bf16_f32 v5, v107, v111
	ds_write2_b64 v6, v[2:3], v[4:5] offset0:32 offset1:48
	v_lshl_add_u64 v[2:3], s[12:13], 1, v[56:57]
	s_mov_b64 s[12:13], 10
	s_branch .LBB0_156

; #define GAS __attribute__((address_space(1)))
; #define LAS __attribute__((address_space(3)))
; __device__ __forceinline__ void transpose_item(const float* W, int ldw, bf16* WT, int K, int k0, int sn0, int dn0, int lane, LAS unsigned char* T, const float* kgain = nullptr) {
;     const int nb = lane & 15, kq = lane >> 4;
; #pragma unroll
;     for (int j = 0; j < 4; ++j) { const int kb = kq + 4 * j, k = k0 + 4 * kb; f32x4 r[4];
; #pragma unroll
;         for (int jj = 0; jj < 4; ++jj) r[jj] = *(const GAS f32x4*)(W + (size_t)(k + jj) * ldw + sn0 + 4 * nb);
;         f32x4 g = {1.f, 1.f, 1.f, 1.f}; if (kgain) g = *(const GAS f32x4*)(kgain + k);
;         const f32x4 a = r[0] * g.x, bq = r[1] * g.y, c = r[2] * g.z, d = r[3] * g.w;
;         LAS unsigned char* t = T + (4 * nb) * 128 + ((kb ^ nb) << 3);
;         v2u w; w.x = pk2(a.x, bq.x); w.y = pk2(c.x, d.x); *(LAS v2u*)t = w;
;         w.x = pk2(a.y, bq.y); w.y = pk2(c.y, d.y); *(LAS v2u*)(t + 128) = w;
;         w.x = pk2(a.z, bq.z); w.y = pk2(c.z, d.z); *(LAS v2u*)(t + 256) = w;
;         w.x = pk2(a.w, bq.w); w.y = pk2(c.w, d.w); *(LAS v2u*)(t + 384) = w; }
; template <int PART> __device__ __forceinline__ void deferred_transposes(Frame& F, int gw, int ngw) {
;     ...
;     for (int it = gw; it < NITEMS; it += ngw) {
;         int r = (PART == 0) ? it : it + N0;
;         if (r < I_GLU) { const int nblk = S5W / 64, kb = r / nblk, nb = r % nblk; transpose_item(F.in[16], S5W, WgluT, S5W, kb * 64, nb * 64, nb * 64, F.lane, F.lds + F.wave * 8192); continue; } r -= I_GLU;
;         if (r < I_OUT) { const int nblk = DM / 64, kb = r / nblk, nb = r % nblk; transpose_item(F.in[18], DM, WoutT, DM, kb * 64, nb * 64, nb * 64, F.lane, F.lds + F.wave * 8192); continue; } r -= I_OUT;
;         if (r < I_G) { const int nblk = DFF / 64, kb = r / nblk, nb = r % nblk, sn0 = nb * 64; transpose_item(F.in[20], DFF, WguT, DM, kb * 64, sn0, 256 * (sn0 / 128) + (sn0 % 128), F.lane, F.lds + F.wave * 8192, F.in[19]); continue; } r -= I_G;
;         if (r < I_G) { const int nblk = DFF / 64, kb = r / nblk, nb = r % nblk, sn0 = nb * 64; transpose_item(F.in[21], DFF, WguT, DM, kb * 64, sn0, 256 * (sn0 / 128) + 128 + (sn0 % 128), F.lane, F.lds + F.wave * 8192, F.in[19]); continue; } r -= I_G;
.LBB0_190:
	s_cmp_gt_i32 s18, 63
	s_mov_b64 s[12:13], -1
	s_cbranch_scc0 .LBB0_215
	s_cmpk_gt_u32 s18, 0x13f
	s_cbranch_scc0 .LBB0_212
	s_cmpk_gt_u32 s18, 0x3ff
	s_cbranch_scc0 .LBB0_202
	s_add_i32 s4, s18, 0xfc00
	s_and_b32 s10, s4, 0xffff
	s_mul_i32 s10, s10, 0xba2f
	s_lshr_b32 s11, s10, 21
	s_mul_i32 s10, s11, 44
	s_sub_i32 s4, s4, s10
	s_and_b32 s10, s4, 0xffff
	s_lshl_b32 s11, s11, 6
	s_lshl_b32 s4, s10, 8
	v_or_b32_e32 v3, s11, v62
	v_lshl_add_u64 v[58:59], v[44:45], 0, s[4:5]
	v_mad_u32_u24 v42, v3, s17, s17
	v_lshl_add_u64 v[6:7], v[58:59], 0, v[42:43]
	v_mad_u32_u24 v42, v3, s17, v86
	v_mad_u64_u32 v[4:5], s[12:13], v3, s17, v[58:59]
	v_lshl_add_u64 v[8:9], v[58:59], 0, v[42:43]
	v_mad_u32_u24 v42, v3, s17, v87
	global_load_dwordx4 v[14:17], v[4:5], off nt
	s_nop 0
	global_load_dwordx4 v[4:7], v[6:7], off nt
	v_lshl_add_u64 v[10:11], v[58:59], 0, v[42:43]
	global_load_dwordx4 v[30:33], v[8:9], off nt
	global_load_dwordx4 v[22:25], v[10:11], off nt
	v_mov_b32_e32 v2, 1.0
	s_and_b64 vcc, exec, s[6:7]
	v_mov_b32_e32 v38, 1.0
	v_mov_b32_e32 v8, 1.0
	v_mov_b32_e32 v40, 1.0
	v_mov_b32_e32 v60, 1.0
	s_cbranch_vccnz .LBB0_195
	v_readlane_b32 s60, v238, 29
	v_lshlrev_b32_e32 v3, 2, v3
	v_readlane_b32 s66, v238, 35
	v_readlane_b32 s67, v238, 36
	v_readlane_b32 s61, v238, 30
	v_readlane_b32 s62, v238, 31
	v_readlane_b32 s63, v238, 32
	v_readlane_b32 s64, v238, 33
	v_readlane_b32 s65, v238, 34
	global_load_dwordx4 v[38:41], v3, s[66:67]
	v_readlane_b32 s68, v238, 37
	v_readlane_b32 s69, v238, 38
	v_readlane_b32 s70, v238, 39
	v_readlane_b32 s71, v238, 40
	v_readlane_b32 s72, v238, 41
	v_readlane_b32 s73, v238, 42
	v_readlane_b32 s74, v238, 43
	v_readlane_b32 s75, v238, 44
	s_waitcnt vmcnt(0)
	v_mov_b32_e32 v8, v39
	v_mov_b32_e32 v60, v41
.LBB0_195:
	v_or_b32_e32 v3, s11, v64
	v_mad_u32_u24 v42, v3, s17, s17
	v_lshl_add_u64 v[12:13], v[58:59], 0, v[42:43]
	v_mad_u32_u24 v42, v3, s17, v86
	v_lshl_add_u64 v[26:27], v[58:59], 0, v[42:43]
	v_mad_u32_u24 v42, v3, s17, v87
	v_mad_u64_u32 v[10:11], s[12:13], v3, s17, v[58:59]
	v_lshl_add_u64 v[28:29], v[58:59], 0, v[42:43]
	global_load_dwordx4 v[18:21], v[10:11], off nt
	s_nop 0
	global_load_dwordx4 v[10:13], v[12:13], off nt
	s_nop 0
	global_load_dwordx4 v[34:37], v[26:27], off nt
	s_nop 0
	global_load_dwordx4 v[26:29], v[28:29], off nt
	s_waitcnt vmcnt(0)
	v_pk_mul_f32 v[14:15], v[14:15], v[38:39] op_sel_hi:[1,0]
	v_pk_mul_f32 v[4:5], v[4:5], v[8:9] op_sel_hi:[1,0]
	v_pk_mul_f32 v[30:31], v[30:31], v[40:41] op_sel_hi:[1,0]
	v_pk_mul_f32 v[22:23], v[22:23], v[60:61] op_sel_hi:[1,0]
	v_pk_mul_f32 v[16:17], v[16:17], v[38:39] op_sel_hi:[1,0]
	v_pk_mul_f32 v[6:7], v[6:7], v[8:9] op_sel_hi:[1,0]
	v_pk_mul_f32 v[8:9], v[32:33], v[40:41] op_sel_hi:[1,0]
	v_pk_mul_f32 v[24:25], v[24:25], v[60:61] op_sel_hi:[1,0]
	v_cvt_pk_bf16_f32 v32, v14, v4
	v_cvt_pk_bf16_f32 v33, v30, v22
	v_add_u32_e32 v14, v61, v63
	v_cvt_pk_bf16_f32 v4, v15, v5
	v_cvt_pk_bf16_f32 v5, v31, v23
	ds_write2_b64 v14, v[32:33], v[4:5] offset1:16
	v_cvt_pk_bf16_f32 v4, v16, v6
	v_cvt_pk_bf16_f32 v5, v8, v24
	v_cvt_pk_bf16_f32 v6, v17, v7
	v_cvt_pk_bf16_f32 v7, v9, v25
	ds_write2_b64 v14, v[4:5], v[6:7] offset0:32 offset1:48
	s_and_b64 vcc, exec, s[6:7]
	v_mov_b32_e32 v38, 1.0
	v_mov_b32_e32 v4, 1.0
	v_mov_b32_e32 v40, 1.0
	s_cbranch_vccnz .LBB0_197
	v_readlane_b32 s60, v238, 29
	v_lshlrev_b32_e32 v2, 2, v3
	v_readlane_b32 s66, v238, 35
	v_readlane_b32 s67, v238, 36
	v_readlane_b32 s61, v238, 30
	v_readlane_b32 s62, v238, 31
	v_readlane_b32 s63, v238, 32
	v_readlane_b32 s64, v238, 33
	v_readlane_b32 s65, v238, 34
	global_load_dwordx4 v[2:5], v2, s[66:67]
	v_readlane_b32 s68, v238, 37
	v_readlane_b32 s69, v238, 38
	v_readlane_b32 s70, v238, 39
	v_readlane_b32 s71, v238, 40
	v_readlane_b32 s72, v238, 41
	v_readlane_b32 s73, v238, 42
	v_readlane_b32 s74, v238, 43
	v_readlane_b32 s75, v238, 44
	s_waitcnt vmcnt(0)
	v_mov_b32_e32 v38, v3
	v_mov_b32_e32 v40, v5
; #define GAS __attribute__((address_space(1)))
; #define LAS __attribute__((address_space(3)))
; __device__ __forceinline__ unsigned pk2(float lo, float hi) { f32x2_t v = {lo, hi}; bf16x2_t h = __builtin_convertvector(v, bf16x2_t); return __builtin_bit_cast(unsigned, h); }
; __device__ __forceinline__ void transpose_item(const float* W, int ldw, bf16* WT, int K, int k0, int sn0, int dn0, int lane, LAS unsigned char* T, const float* kgain = nullptr) {
;     const int nb = lane & 15, kq = lane >> 4;
; #pragma unroll
;     for (int j = 0; j < 4; ++j) { const int kb = kq + 4 * j, k = k0 + 4 * kb; f32x4 r[4];
; #pragma unroll
;         for (int jj = 0; jj < 4; ++jj) r[jj] = *(const GAS f32x4*)(W + (size_t)(k + jj) * ldw + sn0 + 4 * nb);
;         f32x4 g = {1.f, 1.f, 1.f, 1.f}; if (kgain) g = *(const GAS f32x4*)(kgain + k);
;         const f32x4 a = r[0] * g.x, bq = r[1] * g.y, c = r[2] * g.z, d = r[3] * g.w;
;         LAS unsigned char* t = T + (4 * nb) * 128 + ((kb ^ nb) << 3);
;         v2u w; w.x = pk2(a.x, bq.x); w.y = pk2(c.x, d.x); *(LAS v2u*)t = w;
;         w.x = pk2(a.y, bq.y); w.y = pk2(c.y, d.y); *(LAS v2u*)(t + 128) = w;
;         w.x = pk2(a.z, bq.z); w.y = pk2(c.z, d.z); *(LAS v2u*)(t + 256) = w;
;         w.x = pk2(a.w, bq.w); w.y = pk2(c.w, d.w); *(LAS v2u*)(t + 384) = w; }
.LBB0_197:
	v_or_b32_e32 v3, s11, v66
	v_mad_u32_u24 v42, v3, s17, s17
	v_lshl_add_u64 v[8:9], v[58:59], 0, v[42:43]
	v_mad_u32_u24 v42, v3, s17, v86
	v_lshl_add_u64 v[22:23], v[58:59], 0, v[42:43]
	v_mad_u32_u24 v42, v3, s17, v87
	v_mad_u64_u32 v[6:7], s[12:13], v3, s17, v[58:59]
	v_lshl_add_u64 v[24:25], v[58:59], 0, v[42:43]
	global_load_dwordx4 v[14:17], v[6:7], off nt
	s_nop 0
	global_load_dwordx4 v[6:9], v[8:9], off nt
	s_nop 0
	global_load_dwordx4 v[30:33], v[22:23], off nt
	s_nop 0
	global_load_dwordx4 v[22:25], v[24:25], off nt
	v_pk_mul_f32 v[18:19], v[18:19], v[2:3] op_sel_hi:[1,0]
	v_pk_mul_f32 v[10:11], v[10:11], v[38:39] op_sel_hi:[1,0]
	v_pk_mul_f32 v[36:37], v[36:37], v[4:5] op_sel_hi:[1,0]
	v_pk_mul_f32 v[4:5], v[34:35], v[4:5] op_sel_hi:[1,0]
	v_pk_mul_f32 v[26:27], v[26:27], v[40:41] op_sel_hi:[1,0]
	v_pk_mul_f32 v[20:21], v[20:21], v[2:3] op_sel_hi:[1,0]
	v_pk_mul_f32 v[12:13], v[12:13], v[38:39] op_sel_hi:[1,0]
	v_pk_mul_f32 v[28:29], v[28:29], v[40:41] op_sel_hi:[1,0]
	v_cvt_pk_bf16_f32 v34, v18, v10
	v_cvt_pk_bf16_f32 v35, v4, v26
	v_add_u32_e32 v2, v61, v65
	v_cvt_pk_bf16_f32 v4, v19, v11
	v_cvt_pk_bf16_f32 v5, v5, v27
	ds_write2_b64 v2, v[34:35], v[4:5] offset1:16
	v_cvt_pk_bf16_f32 v4, v20, v12
	v_cvt_pk_bf16_f32 v5, v36, v28
	v_cvt_pk_bf16_f32 v10, v21, v13
	v_cvt_pk_bf16_f32 v11, v37, v29
	ds_write2_b64 v2, v[4:5], v[10:11] offset0:32 offset1:48
	v_mov_b32_e32 v2, 1.0
	s_and_b64 vcc, exec, s[6:7]
	v_mov_b32_e32 v10, 1.0
	v_mov_b32_e32 v4, 1.0
	v_mov_b32_e32 v12, 1.0
	v_mov_b32_e32 v60, 1.0
	s_cbranch_vccnz .LBB0_199
	v_readlane_b32 s60, v238, 29
	v_lshlrev_b32_e32 v3, 2, v3
	v_readlane_b32 s66, v238, 35
	v_readlane_b32 s67, v238, 36
	v_readlane_b32 s61, v238, 30
	v_readlane_b32 s62, v238, 31
	v_readlane_b32 s63, v238, 32
	v_readlane_b32 s64, v238, 33
	v_readlane_b32 s65, v238, 34
	global_load_dwordx4 v[10:13], v3, s[66:67]
	v_readlane_b32 s68, v238, 37
	v_readlane_b32 s69, v238, 38
	v_readlane_b32 s70, v238, 39
	v_readlane_b32 s71, v238, 40
	v_readlane_b32 s72, v238, 41
	v_readlane_b32 s73, v238, 42
	v_readlane_b32 s74, v238, 43
	v_readlane_b32 s75, v238, 44
	s_waitcnt vmcnt(0)
	v_mov_b32_e32 v4, v11
	v_mov_b32_e32 v60, v13
.LBB0_199:
	v_or_b32_e32 v3, s11, v68
	v_mad_u32_u24 v42, v3, s17, s17
	v_lshl_add_u64 v[20:21], v[58:59], 0, v[42:43]
	v_mad_u32_u24 v42, v3, s17, v86
	v_lshl_add_u64 v[26:27], v[58:59], 0, v[42:43]
	v_mad_u32_u24 v42, v3, s17, v87
	v_mad_u64_u32 v[18:19], s[12:13], v3, s17, v[58:59]
	v_lshl_add_u64 v[28:29], v[58:59], 0, v[42:43]
	global_load_dwordx4 v[34:37], v[18:19], off nt
	s_nop 0
	global_load_dwordx4 v[18:21], v[20:21], off nt
	s_nop 0
	global_load_dwordx4 v[38:41], v[26:27], off nt
	s_nop 0
	global_load_dwordx4 v[26:29], v[28:29], off nt
	s_waitcnt vmcnt(7)
	v_pk_mul_f32 v[16:17], v[16:17], v[10:11] op_sel_hi:[1,0]
	v_pk_mul_f32 v[10:11], v[14:15], v[10:11] op_sel_hi:[1,0]
	s_waitcnt vmcnt(6)
	v_pk_mul_f32 v[8:9], v[8:9], v[4:5] op_sel_hi:[1,0]
	v_pk_mul_f32 v[4:5], v[6:7], v[4:5] op_sel_hi:[1,0]
	s_waitcnt vmcnt(5)
	v_pk_mul_f32 v[6:7], v[32:33], v[12:13] op_sel_hi:[1,0]
	v_pk_mul_f32 v[12:13], v[30:31], v[12:13] op_sel_hi:[1,0]
	s_waitcnt vmcnt(4)
	v_pk_mul_f32 v[22:23], v[22:23], v[60:61] op_sel_hi:[1,0]
	v_pk_mul_f32 v[14:15], v[24:25], v[60:61] op_sel_hi:[1,0]
	v_cvt_pk_bf16_f32 v24, v10, v4
	v_cvt_pk_bf16_f32 v25, v12, v22
	v_add_u32_e32 v10, v61, v67
	v_cvt_pk_bf16_f32 v4, v11, v5
	v_cvt_pk_bf16_f32 v5, v13, v23
	ds_write2_b64 v10, v[24:25], v[4:5] offset1:16
	v_cvt_pk_bf16_f32 v4, v16, v8
	v_cvt_pk_bf16_f32 v5, v6, v14
	v_cvt_pk_bf16_f32 v6, v17, v9
	v_cvt_pk_bf16_f32 v7, v7, v15
	ds_write2_b64 v10, v[4:5], v[6:7] offset0:32 offset1:48
	s_and_b64 vcc, exec, s[6:7]
	v_mov_b32_e32 v8, 1.0
	v_mov_b32_e32 v4, 1.0
	v_mov_b32_e32 v6, 1.0
	s_cbranch_vccnz .LBB0_201
	v_readlane_b32 s60, v238, 29
	v_lshlrev_b32_e32 v2, 2, v3
	v_readlane_b32 s66, v238, 35
	v_readlane_b32 s67, v238, 36
	v_readlane_b32 s61, v238, 30
	v_readlane_b32 s62, v238, 31
	v_readlane_b32 s63, v238, 32
	v_readlane_b32 s64, v238, 33
	v_readlane_b32 s65, v238, 34
	global_load_dwordx4 v[2:5], v2, s[66:67]
	v_readlane_b32 s68, v238, 37
	v_readlane_b32 s69, v238, 38
	v_readlane_b32 s70, v238, 39
	v_readlane_b32 s71, v238, 40
	v_readlane_b32 s72, v238, 41
	v_readlane_b32 s73, v238, 42
	v_readlane_b32 s74, v238, 43
	v_readlane_b32 s75, v238, 44
	s_waitcnt vmcnt(0)
	v_mov_b32_e32 v8, v3
	v_mov_b32_e32 v6, v5

; #define GAS __attribute__((address_space(1)))
; __device__ __forceinline__ void transpose_item(const float* W, int ldw, bf16* WT, int K, int k0, int sn0, int dn0, int lane, LAS unsigned char* T, const float* kgain = nullptr) {
;     ...
;     for (int j = 0; j < 4; ++j) { const int kb = kq + 4 * j, k = k0 + 4 * kb; f32x4 r[4];
; #pragma unroll
;         for (int jj = 0; jj < 4; ++jj) r[jj] = *(const GAS f32x4*)(W + (size_t)(k + jj) * ldw + sn0 + 4 * nb);
;         f32x4 g = {1.f, 1.f, 1.f, 1.f}; if (kgain) g = *(const GAS f32x4*)(kgain + k);
; template <int PART> __device__ __forceinline__ void deferred_transposes(Frame& F, int gw, int ngw) {
;     ...
;     for (int it = gw; it < NITEMS; it += ngw) {
;         int r = (PART == 0) ? it : it + N0;
;         if (r < I_GLU) { const int nblk = S5W / 64, kb = r / nblk, nb = r % nblk; transpose_item(F.in[16], S5W, WgluT, S5W, kb * 64, nb * 64, nb * 64, F.lane, F.lds + F.wave * 8192); continue; } r -= I_GLU;
;         if (r < I_OUT) { const int nblk = DM / 64, kb = r / nblk, nb = r % nblk; transpose_item(F.in[18], DM, WoutT, DM, kb * 64, nb * 64, nb * 64, F.lane, F.lds + F.wave * 8192); continue; } r -= I_OUT;
;         if (r < I_G) { const int nblk = DFF / 64, kb = r / nblk, nb = r % nblk, sn0 = nb * 64; transpose_item(F.in[20], DFF, WguT, DM, kb * 64, sn0, 256 * (sn0 / 128) + (sn0 % 128), F.lane, F.lds + F.wave * 8192, F.in[19]); continue; } r -= I_G;
.LBB0_202:
	s_and_b64 vcc, exec, s[12:13]
	s_cbranch_vccz .LBB0_217
	s_add_i32 s4, s18, 0xfec0
	s_and_b32 s10, s4, 0xffff
	s_mul_i32 s10, s10, 0xba2f
	s_lshr_b32 s11, s10, 21
	s_mul_i32 s10, s11, 44
	s_sub_i32 s4, s4, s10
	s_and_b32 s10, s4, 0xffff
	s_lshl_b32 s11, s11, 6
	s_lshl_b32 s4, s10, 8
	v_or_b32_e32 v3, s11, v62
	v_lshl_add_u64 v[58:59], v[48:49], 0, s[4:5]
	v_mad_u32_u24 v42, v3, s17, s17
	v_lshl_add_u64 v[6:7], v[58:59], 0, v[42:43]
	v_mad_u32_u24 v42, v3, s17, v86
	v_mad_u64_u32 v[4:5], s[12:13], v3, s17, v[58:59]
	v_lshl_add_u64 v[8:9], v[58:59], 0, v[42:43]
	v_mad_u32_u24 v42, v3, s17, v87
	global_load_dwordx4 v[14:17], v[4:5], off nt
	s_nop 0
	global_load_dwordx4 v[4:7], v[6:7], off nt
	v_lshl_add_u64 v[10:11], v[58:59], 0, v[42:43]
	global_load_dwordx4 v[30:33], v[8:9], off nt
	global_load_dwordx4 v[22:25], v[10:11], off nt
	v_mov_b32_e32 v2, 1.0
	s_and_b64 vcc, exec, s[6:7]
	v_mov_b32_e32 v38, 1.0
	v_mov_b32_e32 v8, 1.0
	v_mov_b32_e32 v40, 1.0
	v_mov_b32_e32 v60, 1.0
	s_cbranch_vccnz .LBB0_205
	v_readlane_b32 s60, v238, 29
	v_lshlrev_b32_e32 v3, 2, v3
	v_readlane_b32 s66, v238, 35
	v_readlane_b32 s67, v238, 36
	v_readlane_b32 s61, v238, 30
	v_readlane_b32 s62, v238, 31
	v_readlane_b32 s63, v238, 32
	v_readlane_b32 s64, v238, 33
	v_readlane_b32 s65, v238, 34
	global_load_dwordx4 v[38:41], v3, s[66:67]
	v_readlane_b32 s68, v238, 37
	v_readlane_b32 s69, v238, 38
	v_readlane_b32 s70, v238, 39
	v_readlane_b32 s71, v238, 40
	v_readlane_b32 s72, v238, 41
	v_readlane_b32 s73, v238, 42
	v_readlane_b32 s74, v238, 43
	v_readlane_b32 s75, v238, 44
	s_waitcnt vmcnt(0)
	v_mov_b32_e32 v8, v39
	v_mov_b32_e32 v60, v41

; #define GAS __attribute__((address_space(1)))
; #define LAS __attribute__((address_space(3)))
; __device__ __forceinline__ unsigned pk2(float lo, float hi) { f32x2_t v = {lo, hi}; bf16x2_t h = __builtin_convertvector(v, bf16x2_t); return __builtin_bit_cast(unsigned, h); }
; __device__ __forceinline__ void transpose_item(const float* W, int ldw, bf16* WT, int K, int k0, int sn0, int dn0, int lane, LAS unsigned char* T, const float* kgain = nullptr) {
;     const int nb = lane & 15, kq = lane >> 4;
; #pragma unroll
;     for (int j = 0; j < 4; ++j) { const int kb = kq + 4 * j, k = k0 + 4 * kb; f32x4 r[4];
; #pragma unroll
;         for (int jj = 0; jj < 4; ++jj) r[jj] = *(const GAS f32x4*)(W + (size_t)(k + jj) * ldw + sn0 + 4 * nb);
;         f32x4 g = {1.f, 1.f, 1.f, 1.f}; if (kgain) g = *(const GAS f32x4*)(kgain + k);
;         const f32x4 a = r[0] * g.x, bq = r[1] * g.y, c = r[2] * g.z, d = r[3] * g.w;
;         LAS unsigned char* t = T + (4 * nb) * 128 + ((kb ^ nb) << 3);
;         v2u w; w.x = pk2(a.x, bq.x); w.y = pk2(c.x, d.x); *(LAS v2u*)t = w;
;         w.x = pk2(a.y, bq.y); w.y = pk2(c.y, d.y); *(LAS v2u*)(t + 128) = w;
;         w.x = pk2(a.z, bq.z); w.y = pk2(c.z, d.z); *(LAS v2u*)(t + 256) = w;
;         w.x = pk2(a.w, bq.w); w.y = pk2(c.w, d.w); *(LAS v2u*)(t + 384) = w; }
; template <int PART> __device__ __forceinline__ void deferred_transposes(Frame& F, int gw, int ngw) {
;     ...
;         if (r < I_OUT) { const int nblk = DM / 64, kb = r / nblk, nb = r % nblk; transpose_item(F.in[18], DM, WoutT, DM, kb * 64, nb * 64, nb * 64, F.lane, F.lds + F.wave * 8192); continue; } r -= I_OUT;
.LBB0_213:
	s_and_b32 s4, s15, 0x7c0
	s_add_i32 s12, s4, 0xffffff00
	v_or_b32_e32 v42, s12, v62
	s_and_b32 s10, s3, 0x3c0
	v_lshlrev_b64 v[2:3], 12, v[42:43]
	v_or_b32_e32 v4, 1, v42
	v_or_b32_e32 v10, 2, v42
	v_or_b32_e32 v42, 3, v42
	s_lshl_b32 s4, s10, 2
	v_mov_b32_e32 v5, v43
	v_mov_b32_e32 v11, v43
	v_lshlrev_b64 v[12:13], 12, v[42:43]
	v_or_b32_e32 v42, s12, v64
	v_lshl_add_u64 v[58:59], v[50:51], 0, s[4:5]
	v_lshlrev_b64 v[4:5], 12, v[4:5]
	v_lshlrev_b64 v[10:11], 12, v[10:11]
	v_lshlrev_b64 v[18:19], 12, v[42:43]
	v_or_b32_e32 v20, 1, v42
	v_mov_b32_e32 v21, v43
	v_or_b32_e32 v26, 2, v42
	v_mov_b32_e32 v27, v43
	v_or_b32_e32 v42, 3, v42
	v_lshl_add_u64 v[2:3], v[58:59], 0, v[2:3]
	v_lshl_add_u64 v[6:7], v[58:59], 0, v[4:5]
	v_lshl_add_u64 v[10:11], v[58:59], 0, v[10:11]
	v_lshl_add_u64 v[14:15], v[58:59], 0, v[12:13]
	v_lshlrev_b64 v[20:21], 12, v[20:21]
	v_lshlrev_b64 v[26:27], 12, v[26:27]
	v_lshlrev_b64 v[28:29], 12, v[42:43]
	v_or_b32_e32 v42, s12, v66
	global_load_dwordx4 v[2:5], v[2:3], off nt
	s_nop 0
	global_load_dwordx4 v[6:9], v[6:7], off nt
	s_nop 0
	global_load_dwordx4 v[10:13], v[10:11], off nt
	s_nop 0
	global_load_dwordx4 v[14:17], v[14:15], off nt
	v_lshl_add_u64 v[18:19], v[58:59], 0, v[18:19]
	v_lshl_add_u64 v[22:23], v[58:59], 0, v[20:21]
	v_lshl_add_u64 v[26:27], v[58:59], 0, v[26:27]
	v_lshl_add_u64 v[30:31], v[58:59], 0, v[28:29]
	v_lshlrev_b64 v[34:35], 12, v[42:43]
	v_or_b32_e32 v36, 1, v42
	v_mov_b32_e32 v37, v43
	v_or_b32_e32 v88, 2, v42
	v_mov_b32_e32 v89, v43
	v_or_b32_e32 v42, 3, v42
	global_load_dwordx4 v[18:21], v[18:19], off nt
	s_nop 0
	global_load_dwordx4 v[22:25], v[22:23], off nt
	s_nop 0
	global_load_dwordx4 v[26:29], v[26:27], off nt
	s_nop 0
	global_load_dwordx4 v[30:33], v[30:31], off nt
	v_lshlrev_b64 v[36:37], 12, v[36:37]
	v_lshlrev_b64 v[88:89], 12, v[88:89]
	v_lshlrev_b64 v[90:91], 12, v[42:43]
	v_or_b32_e32 v42, s12, v68
	v_lshl_add_u64 v[34:35], v[58:59], 0, v[34:35]
	v_lshl_add_u64 v[38:39], v[58:59], 0, v[36:37]
	v_lshl_add_u64 v[88:89], v[58:59], 0, v[88:89]
	v_lshl_add_u64 v[92:93], v[58:59], 0, v[90:91]
	v_or_b32_e32 v98, 1, v42
	v_mov_b32_e32 v99, v43
	v_or_b32_e32 v104, 2, v42
	v_mov_b32_e32 v105, v43
	global_load_dwordx4 v[34:37], v[34:35], off nt
	s_nop 0
	global_load_dwordx4 v[38:41], v[38:39], off nt
	s_nop 0
	global_load_dwordx4 v[88:91], v[88:89], off nt
	s_nop 0
	global_load_dwordx4 v[92:95], v[92:93], off nt
	v_lshlrev_b64 v[96:97], 12, v[42:43]
	v_lshlrev_b64 v[98:99], 12, v[98:99]
	v_lshlrev_b64 v[104:105], 12, v[104:105]
	v_or_b32_e32 v42, 3, v42
	v_lshl_add_u64 v[96:97], v[58:59], 0, v[96:97]
	v_lshl_add_u64 v[100:101], v[58:59], 0, v[98:99]
	v_lshl_add_u64 v[104:105], v[58:59], 0, v[104:105]
	v_lshlrev_b64 v[106:107], 12, v[42:43]
	global_load_dwordx4 v[96:99], v[96:97], off nt
	s_nop 0
	global_load_dwordx4 v[100:103], v[100:101], off nt
	v_lshl_add_u64 v[58:59], v[58:59], 0, v[106:107]
	global_load_dwordx4 v[104:107], v[104:105], off nt
	s_nop 0
	global_load_dwordx4 v[108:111], v[58:59], off nt
	v_add_u32_e32 v42, v61, v63
	s_mov_b32 s13, s5
	s_waitcnt vmcnt(0)
	v_cvt_pk_bf16_f32 v58, v2, v6
	v_cvt_pk_bf16_f32 v59, v10, v14
	v_cvt_pk_bf16_f32 v2, v3, v7
	v_cvt_pk_bf16_f32 v3, v11, v15
	v_cvt_pk_bf16_f32 v6, v4, v8
	v_cvt_pk_bf16_f32 v4, v5, v9
	v_cvt_pk_bf16_f32 v5, v13, v17
	v_cvt_pk_bf16_f32 v7, v12, v16
	ds_write2_b64 v42, v[58:59], v[2:3] offset1:16
	ds_write2_b64 v42, v[6:7], v[4:5] offset0:32 offset1:48
	v_add_u32_e32 v6, v61, v65
	v_cvt_pk_bf16_f32 v2, v18, v22
	v_cvt_pk_bf16_f32 v3, v26, v30
	v_cvt_pk_bf16_f32 v4, v19, v23
	v_cvt_pk_bf16_f32 v5, v27, v31
	ds_write2_b64 v6, v[2:3], v[4:5] offset1:16
	v_cvt_pk_bf16_f32 v2, v20, v24
	v_cvt_pk_bf16_f32 v3, v28, v32
	v_cvt_pk_bf16_f32 v4, v21, v25
	v_cvt_pk_bf16_f32 v5, v29, v33
	ds_write2_b64 v6, v[2:3], v[4:5] offset0:32 offset1:48
	v_add_u32_e32 v6, v61, v67
	v_cvt_pk_bf16_f32 v2, v34, v38
	v_cvt_pk_bf16_f32 v3, v88, v92
	v_cvt_pk_bf16_f32 v4, v35, v39
	v_cvt_pk_bf16_f32 v5, v89, v93
	ds_write2_b64 v6, v[2:3], v[4:5] offset1:16
	v_cvt_pk_bf16_f32 v2, v36, v40
	v_cvt_pk_bf16_f32 v3, v90, v94
	v_cvt_pk_bf16_f32 v4, v37, v41
	v_cvt_pk_bf16_f32 v5, v91, v95
	ds_write2_b64 v6, v[2:3], v[4:5] offset0:32 offset1:48
	v_cvt_pk_bf16_f32 v2, v96, v100
	v_add_u32_e32 v6, v61, v69
	v_cvt_pk_bf16_f32 v3, v104, v108
	v_cvt_pk_bf16_f32 v4, v97, v101
	v_cvt_pk_bf16_f32 v5, v105, v109
	ds_write2_b64 v6, v[2:3], v[4:5] offset1:16
	v_cvt_pk_bf16_f32 v2, v98, v102
	v_cvt_pk_bf16_f32 v3, v106, v110
	v_cvt_pk_bf16_f32 v4, v99, v103
	v_cvt_pk_bf16_f32 v5, v107, v111
	ds_write2_b64 v6, v[2:3], v[4:5] offset0:32 offset1:48
	v_lshl_add_u64 v[2:3], s[12:13], 1, v[52:53]

; #define GAS __attribute__((address_space(1)))
; #define LAS __attribute__((address_space(3)))
; __device__ __forceinline__ unsigned pk2(float lo, float hi) { f32x2_t v = {lo, hi}; bf16x2_t h = __builtin_convertvector(v, bf16x2_t); return __builtin_bit_cast(unsigned, h); }
; __device__ __forceinline__ void transpose_item(const float* W, int ldw, bf16* WT, int K, int k0, int sn0, int dn0, int lane, LAS unsigned char* T, const float* kgain = nullptr) {
;     const int nb = lane & 15, kq = lane >> 4;
; #pragma unroll
;     for (int j = 0; j < 4; ++j) { const int kb = kq + 4 * j, k = k0 + 4 * kb; f32x4 r[4];
; #pragma unroll
;         for (int jj = 0; jj < 4; ++jj) r[jj] = *(const GAS f32x4*)(W + (size_t)(k + jj) * ldw + sn0 + 4 * nb);
;         f32x4 g = {1.f, 1.f, 1.f, 1.f}; if (kgain) g = *(const GAS f32x4*)(kgain + k);
;         const f32x4 a = r[0] * g.x, bq = r[1] * g.y, c = r[2] * g.z, d = r[3] * g.w;
;         LAS unsigned char* t = T + (4 * nb) * 128 + ((kb ^ nb) << 3);
;         v2u w; w.x = pk2(a.x, bq.x); w.y = pk2(c.x, d.x); *(LAS v2u*)t = w;
;         w.x = pk2(a.y, bq.y); w.y = pk2(c.y, d.y); *(LAS v2u*)(t + 128) = w;
;         w.x = pk2(a.z, bq.z); w.y = pk2(c.z, d.z); *(LAS v2u*)(t + 256) = w;
;         w.x = pk2(a.w, bq.w); w.y = pk2(c.w, d.w); *(LAS v2u*)(t + 384) = w; }
; template <int PART> __device__ __forceinline__ void deferred_transposes(Frame& F, int gw, int ngw) {
;     ...
;         if (r < I_GLU) { const int nblk = S5W / 64, kb = r / nblk, nb = r % nblk; transpose_item(F.in[16], S5W, WgluT, S5W, kb * 64, nb * 64, nb * 64, F.lane, F.lds + F.wave * 8192); continue; } r -= I_GLU;
.LBB0_215:
	s_andn2_b64 vcc, exec, s[12:13]
	s_mov_b64 s[12:13], 11
	s_cbranch_vccnz .LBB0_189
	s_ashr_i32 s4, s18, 31
	s_lshr_b32 s4, s4, 29
	s_add_i32 s4, s18, s4
	s_ashr_i32 s4, s4, 3
	s_lshl_b32 s12, s4, 6
	v_or_b32_e32 v10, s12, v62
	s_lshl_b32 s4, s4, 9
	v_ashrrev_i32_e32 v11, 31, v10
	s_sub_i32 s10, s3, s4
	v_lshlrev_b64 v[2:3], 11, v[10:11]
	v_or_b32_e32 v4, 1, v10
	v_or_b32_e32 v12, 2, v10
	v_or_b32_e32 v10, 3, v10
	v_or_b32_e32 v26, s12, v64
	s_ashr_i32 s11, s10, 31
	v_ashrrev_i32_e32 v5, 31, v4
	v_ashrrev_i32_e32 v13, 31, v12
	v_ashrrev_i32_e32 v11, 31, v10
	v_ashrrev_i32_e32 v27, 31, v26
	v_lshl_add_u64 v[58:59], s[10:11], 2, v[54:55]
	v_lshlrev_b64 v[4:5], 11, v[4:5]
	v_lshlrev_b64 v[12:13], 11, v[12:13]
	v_lshlrev_b64 v[10:11], 11, v[10:11]
	v_lshlrev_b64 v[18:19], 11, v[26:27]
	v_or_b32_e32 v20, 1, v26
	v_or_b32_e32 v28, 2, v26
	v_or_b32_e32 v26, 3, v26
	v_or_b32_e32 v88, s12, v66
	v_lshl_add_u64 v[2:3], v[58:59], 0, v[2:3]
	v_lshl_add_u64 v[6:7], v[58:59], 0, v[4:5]
	v_lshl_add_u64 v[12:13], v[58:59], 0, v[12:13]
	v_lshl_add_u64 v[14:15], v[58:59], 0, v[10:11]
	v_ashrrev_i32_e32 v21, 31, v20
	v_ashrrev_i32_e32 v29, 31, v28
	v_ashrrev_i32_e32 v27, 31, v26
	v_ashrrev_i32_e32 v89, 31, v88
	global_load_dwordx4 v[2:5], v[2:3], off nt
	s_nop 0
	global_load_dwordx4 v[6:9], v[6:7], off nt
	s_nop 0
	global_load_dwordx4 v[10:13], v[12:13], off nt
	s_nop 0
	global_load_dwordx4 v[14:17], v[14:15], off nt
	v_lshlrev_b64 v[20:21], 11, v[20:21]
	v_lshlrev_b64 v[28:29], 11, v[28:29]
	v_lshlrev_b64 v[26:27], 11, v[26:27]
	v_lshlrev_b64 v[34:35], 11, v[88:89]
	v_or_b32_e32 v36, 1, v88
	v_or_b32_e32 v90, 2, v88
	v_or_b32_e32 v88, 3, v88
	v_lshl_add_u64 v[18:19], v[58:59], 0, v[18:19]
	v_lshl_add_u64 v[22:23], v[58:59], 0, v[20:21]
	v_lshl_add_u64 v[28:29], v[58:59], 0, v[28:29]
	v_lshl_add_u64 v[30:31], v[58:59], 0, v[26:27]
	v_ashrrev_i32_e32 v37, 31, v36
	v_ashrrev_i32_e32 v91, 31, v90
	v_ashrrev_i32_e32 v89, 31, v88
	v_or_b32_e32 v104, s12, v68
	global_load_dwordx4 v[18:21], v[18:19], off nt
	s_nop 0
	global_load_dwordx4 v[22:25], v[22:23], off nt
	s_nop 0
	global_load_dwordx4 v[26:29], v[28:29], off nt
	s_nop 0
	global_load_dwordx4 v[30:33], v[30:31], off nt
	v_lshlrev_b64 v[36:37], 11, v[36:37]
	v_lshlrev_b64 v[90:91], 11, v[90:91]
	v_lshlrev_b64 v[88:89], 11, v[88:89]
	v_ashrrev_i32_e32 v105, 31, v104
	v_or_b32_e32 v98, 1, v104
	v_or_b32_e32 v106, 2, v104
	v_lshl_add_u64 v[34:35], v[58:59], 0, v[34:35]
	v_lshl_add_u64 v[38:39], v[58:59], 0, v[36:37]
	v_lshl_add_u64 v[90:91], v[58:59], 0, v[90:91]
	v_lshl_add_u64 v[92:93], v[58:59], 0, v[88:89]
	v_lshlrev_b64 v[96:97], 11, v[104:105]
	v_ashrrev_i32_e32 v99, 31, v98
	v_ashrrev_i32_e32 v107, 31, v106
	v_or_b32_e32 v104, 3, v104
	global_load_dwordx4 v[34:37], v[34:35], off nt
	s_nop 0
	global_load_dwordx4 v[38:41], v[38:39], off nt
	s_nop 0
	global_load_dwordx4 v[88:91], v[90:91], off nt
	s_nop 0
	global_load_dwordx4 v[92:95], v[92:93], off nt
	v_lshlrev_b64 v[98:99], 11, v[98:99]
	v_lshlrev_b64 v[106:107], 11, v[106:107]
	v_ashrrev_i32_e32 v105, 31, v104
	v_lshl_add_u64 v[96:97], v[58:59], 0, v[96:97]
	v_lshl_add_u64 v[100:101], v[58:59], 0, v[98:99]
	v_lshl_add_u64 v[106:107], v[58:59], 0, v[106:107]
	v_lshlrev_b64 v[104:105], 11, v[104:105]
	global_load_dwordx4 v[96:99], v[96:97], off nt
	s_nop 0
	global_load_dwordx4 v[100:103], v[100:101], off nt
	v_lshl_add_u64 v[58:59], v[58:59], 0, v[104:105]
	global_load_dwordx4 v[104:107], v[106:107], off nt
	s_nop 0
	global_load_dwordx4 v[108:111], v[58:59], off nt
	s_ashr_i32 s13, s12, 31
	s_waitcnt vmcnt(0)
	v_cvt_pk_bf16_f32 v58, v2, v6
	v_cvt_pk_bf16_f32 v59, v10, v14
	v_add_u32_e32 v6, v61, v63
	v_cvt_pk_bf16_f32 v2, v3, v7
	v_cvt_pk_bf16_f32 v3, v11, v15
	ds_write2_b64 v6, v[58:59], v[2:3] offset1:16
	v_cvt_pk_bf16_f32 v2, v4, v8
	v_cvt_pk_bf16_f32 v3, v12, v16
	v_cvt_pk_bf16_f32 v4, v5, v9
	v_cvt_pk_bf16_f32 v5, v13, v17
	ds_write2_b64 v6, v[2:3], v[4:5] offset0:32 offset1:48
	v_add_u32_e32 v6, v61, v65
	v_cvt_pk_bf16_f32 v2, v18, v22
	v_cvt_pk_bf16_f32 v3, v26, v30
	v_cvt_pk_bf16_f32 v4, v19, v23
	v_cvt_pk_bf16_f32 v5, v27, v31
	ds_write2_b64 v6, v[2:3], v[4:5] offset1:16
	v_cvt_pk_bf16_f32 v2, v20, v24
	v_cvt_pk_bf16_f32 v3, v28, v32
	v_cvt_pk_bf16_f32 v4, v21, v25
	v_cvt_pk_bf16_f32 v5, v29, v33
	ds_write2_b64 v6, v[2:3], v[4:5] offset0:32 offset1:48
	v_add_u32_e32 v6, v61, v67
	v_cvt_pk_bf16_f32 v2, v34, v38
	v_cvt_pk_bf16_f32 v3, v88, v92
	v_cvt_pk_bf16_f32 v4, v35, v39
	v_cvt_pk_bf16_f32 v5, v89, v93
	ds_write2_b64 v6, v[2:3], v[4:5] offset1:16
	v_cvt_pk_bf16_f32 v2, v36, v40
	v_cvt_pk_bf16_f32 v3, v90, v94
	v_cvt_pk_bf16_f32 v4, v37, v41
	v_cvt_pk_bf16_f32 v5, v91, v95
	ds_write2_b64 v6, v[2:3], v[4:5] offset0:32 offset1:48
	v_cvt_pk_bf16_f32 v2, v96, v100
	v_cvt_pk_bf16_f32 v3, v104, v108
	v_add_u32_e32 v6, v61, v69
	v_cvt_pk_bf16_f32 v4, v97, v101
	v_cvt_pk_bf16_f32 v5, v105, v109
	ds_write2_b64 v6, v[2:3], v[4:5] offset1:16
	v_cvt_pk_bf16_f32 v2, v98, v102
	v_cvt_pk_bf16_f32 v3, v106, v110
	v_cvt_pk_bf16_f32 v4, v99, v103
	v_cvt_pk_bf16_f32 v5, v107, v111
	ds_write2_b64 v6, v[2:3], v[4:5] offset0:32 offset1:48
	v_lshl_add_u64 v[2:3], s[12:13], 1, v[56:57]
	s_mov_b64 s[12:13], 10
	s_branch .LBB0_189

; #define GAS __attribute__((address_space(1)))
; #define LAS __attribute__((address_space(3)))
; __device__ __forceinline__ unsigned pk2(float lo, float hi) { f32x2_t v = {lo, hi}; bf16x2_t h = __builtin_convertvector(v, bf16x2_t); return __builtin_bit_cast(unsigned, h); }
; __device__ __forceinline__ void transpose_item(const float* W, int ldw, bf16* WT, int K, int k0, int sn0, int dn0, int lane, LAS unsigned char* T, const float* kgain = nullptr) {
;     const int nb = lane & 15, kq = lane >> 4;
; #pragma unroll
;     for (int j = 0; j < 4; ++j) { const int kb = kq + 4 * j, k = k0 + 4 * kb; f32x4 r[4];
; #pragma unroll
;         for (int jj = 0; jj < 4; ++jj) r[jj] = *(const GAS f32x4*)(W + (size_t)(k + jj) * ldw + sn0 + 4 * nb);
;         f32x4 g = {1.f, 1.f, 1.f, 1.f}; if (kgain) g = *(const GAS f32x4*)(kgain + k);
;         const f32x4 a = r[0] * g.x, bq = r[1] * g.y, c = r[2] * g.z, d = r[3] * g.w;
;         LAS unsigned char* t = T + (4 * nb) * 128 + ((kb ^ nb) << 3);
;         v2u w; w.x = pk2(a.x, bq.x); w.y = pk2(c.x, d.x); *(LAS v2u*)t = w;
;         w.x = pk2(a.y, bq.y); w.y = pk2(c.y, d.y); *(LAS v2u*)(t + 128) = w;
;         w.x = pk2(a.z, bq.z); w.y = pk2(c.z, d.z); *(LAS v2u*)(t + 256) = w;
;         w.x = pk2(a.w, bq.w); w.y = pk2(c.w, d.w); *(LAS v2u*)(t + 384) = w; }
; #pragma unroll
;     for (int i = 0; i < 8; ++i) { const int n = 8 * i + (lane >> 3), p = lane & 7, s = (n >> 2) & 15;
;         v4u o = *(const LAS v4u*)(T + n * 128 + ((p ^ (s >> 1)) << 4));
;         if (s & 1) { const unsigned tx = o.x, ty = o.y; o.x = o.z; o.y = o.w; o.z = tx; o.w = ty; }
;         *(GAS v4u*)(WT + (size_t)(dn0 + n) * K + k0 + 8 * p) = o; }
; template <int PART> __device__ __forceinline__ void deferred_transposes(Frame& F, int gw, int ngw) {
;     ...
;         { const int nblk = DM / 64, kb = r / nblk, nb = r % nblk; transpose_item(F.in[22], DM, WdT, DFF, kb * 64, nb * 64, nb * 64, F.lane, F.lds + F.wave * 8192); }
.LBB0_889:
	s_cmpk_gt_i32 s3, 0xf97f
	s_mov_b64 s[4:5], -1
	s_cbranch_scc0 .LBB0_919
	s_cmpk_gt_i32 s3, 0xfa7f
	s_cbranch_scc0 .LBB0_916
	s_cmpk_gt_i32 s3, 0xfd3f
	s_cbranch_scc0 .LBB0_905
	s_cmp_gt_i32 s3, -1
	s_cbranch_scc0 .LBB0_894
	s_and_b32 s5, s3, 0x1ffffff0
	v_or_b32_e32 v2, s5, v67
	v_lshlrev_b32_e32 v42, 2, v2
	s_and_b32 s4, s19, 0x3c0
	v_lshlrev_b64 v[2:3], 12, v[42:43]
	v_or_b32_e32 v4, 1, v42
	v_or_b32_e32 v10, 2, v42
	v_or_b32_e32 v42, 3, v42
	s_waitcnt vmcnt(0)
	v_or_b32_e32 v18, s5, v70
	s_lshl_b32 s12, s4, 2
	v_mov_b32_e32 v5, v43
	v_mov_b32_e32 v11, v43
	v_lshlrev_b64 v[12:13], 12, v[42:43]
	v_lshlrev_b32_e32 v42, 2, v18
	v_lshl_add_u64 v[64:65], v[44:45], 0, s[12:13]
	v_lshlrev_b64 v[4:5], 12, v[4:5]
	v_lshlrev_b64 v[10:11], 12, v[10:11]
	v_lshlrev_b64 v[18:19], 12, v[42:43]
	v_or_b32_e32 v20, 1, v42
	v_or_b32_e32 v26, 2, v42
	v_or_b32_e32 v42, 3, v42
	v_or_b32_e32 v34, s5, v72
	v_lshl_add_u64 v[2:3], v[64:65], 0, v[2:3]
	v_lshl_add_u64 v[6:7], v[64:65], 0, v[4:5]
	v_lshl_add_u64 v[10:11], v[64:65], 0, v[10:11]
	v_lshl_add_u64 v[14:15], v[64:65], 0, v[12:13]
	v_mov_b32_e32 v21, v43
	v_mov_b32_e32 v27, v43
	s_waitcnt lgkmcnt(0)
	v_lshlrev_b64 v[28:29], 12, v[42:43]
	v_lshlrev_b32_e32 v42, 2, v34
	global_load_dwordx4 v[2:5], v[2:3], off nt
	s_nop 0
	global_load_dwordx4 v[6:9], v[6:7], off nt
	s_nop 0
	global_load_dwordx4 v[10:13], v[10:11], off nt
	s_nop 0
	global_load_dwordx4 v[14:17], v[14:15], off nt
	v_lshlrev_b64 v[20:21], 12, v[20:21]
	v_lshlrev_b64 v[26:27], 12, v[26:27]
	v_lshlrev_b64 v[34:35], 12, v[42:43]
	v_or_b32_e32 v36, 1, v42
	v_or_b32_e32 v104, 2, v42
	v_or_b32_e32 v42, 3, v42
	v_lshl_add_u64 v[18:19], v[64:65], 0, v[18:19]
	v_lshl_add_u64 v[22:23], v[64:65], 0, v[20:21]
	v_lshl_add_u64 v[26:27], v[64:65], 0, v[26:27]
	v_lshl_add_u64 v[30:31], v[64:65], 0, v[28:29]
	v_mov_b32_e32 v37, v43
	v_mov_b32_e32 v105, v43
	v_lshlrev_b64 v[106:107], 12, v[42:43]
	v_or_b32_e32 v42, s5, v74
	global_load_dwordx4 v[18:21], v[18:19], off nt
	s_nop 0
	global_load_dwordx4 v[22:25], v[22:23], off nt
	s_nop 0
	global_load_dwordx4 v[26:29], v[26:27], off nt
	s_nop 0
	global_load_dwordx4 v[30:33], v[30:31], off nt
	v_lshlrev_b64 v[36:37], 12, v[36:37]
	v_lshlrev_b64 v[104:105], 12, v[104:105]
	v_lshlrev_b32_e32 v42, 2, v42
	v_lshl_add_u64 v[34:35], v[64:65], 0, v[34:35]
	v_lshl_add_u64 v[38:39], v[64:65], 0, v[36:37]
	v_lshl_add_u64 v[104:105], v[64:65], 0, v[104:105]
	v_lshl_add_u64 v[108:109], v[64:65], 0, v[106:107]
	v_or_b32_e32 v114, 1, v42
	v_mov_b32_e32 v115, v43
	v_or_b32_e32 v120, 2, v42
	v_mov_b32_e32 v121, v43
	global_load_dwordx4 v[34:37], v[34:35], off nt
	s_nop 0
	global_load_dwordx4 v[38:41], v[38:39], off nt
	s_nop 0
	global_load_dwordx4 v[104:107], v[104:105], off nt
	s_nop 0
	global_load_dwordx4 v[108:111], v[108:109], off nt
	v_lshlrev_b64 v[112:113], 12, v[42:43]
	v_lshlrev_b64 v[114:115], 12, v[114:115]
	v_lshlrev_b64 v[120:121], 12, v[120:121]
	v_or_b32_e32 v42, 3, v42
	v_lshl_add_u64 v[112:113], v[64:65], 0, v[112:113]
	v_lshl_add_u64 v[116:117], v[64:65], 0, v[114:115]
	v_lshl_add_u64 v[120:121], v[64:65], 0, v[120:121]
	v_lshlrev_b64 v[122:123], 12, v[42:43]
	global_load_dwordx4 v[112:115], v[112:113], off nt
	s_nop 0
	global_load_dwordx4 v[116:119], v[116:117], off nt
	v_lshl_add_u64 v[64:65], v[64:65], 0, v[122:123]
	global_load_dwordx4 v[120:123], v[120:121], off nt
	s_nop 0
	global_load_dwordx4 v[124:127], v[64:65], off nt
	v_add_u32_e32 v42, v68, v69
	s_and_b32 s5, s17, 0x7fffffc0
	s_lshl_b32 s12, s5, 1
	s_waitcnt vmcnt(14)
	v_cvt_pk_bf16_f32 v64, v2, v6
	s_waitcnt vmcnt(12)
	v_cvt_pk_bf16_f32 v65, v10, v14
	v_cvt_pk_bf16_f32 v2, v3, v7
	v_cvt_pk_bf16_f32 v3, v11, v15
	v_cvt_pk_bf16_f32 v6, v4, v8
	ds_write2_b64 v42, v[64:65], v[2:3] offset1:16
	v_cvt_pk_bf16_f32 v7, v12, v16
	v_cvt_pk_bf16_f32 v2, v5, v9
	v_cvt_pk_bf16_f32 v3, v13, v17
	ds_write2_b64 v42, v[6:7], v[2:3] offset0:32 offset1:48
	v_add_u32_e32 v6, v68, v71
	v_lshl_add_u64 v[16:17], v[48:49], 0, s[12:13]
	s_waitcnt vmcnt(10)
	v_cvt_pk_bf16_f32 v2, v18, v22
	s_waitcnt vmcnt(8)
	v_cvt_pk_bf16_f32 v3, v26, v30
	v_cvt_pk_bf16_f32 v4, v19, v23
	v_cvt_pk_bf16_f32 v5, v27, v31
	ds_write2_b64 v6, v[2:3], v[4:5] offset1:16
	v_cvt_pk_bf16_f32 v2, v20, v24
	v_cvt_pk_bf16_f32 v3, v28, v32
	v_cvt_pk_bf16_f32 v4, v21, v25
	v_cvt_pk_bf16_f32 v5, v29, v33
	ds_write2_b64 v6, v[2:3], v[4:5] offset0:32 offset1:48
	v_add_u32_e32 v6, v68, v73
	s_waitcnt vmcnt(6)
	v_cvt_pk_bf16_f32 v2, v34, v38
	s_waitcnt vmcnt(4)
	v_cvt_pk_bf16_f32 v3, v104, v108
	v_cvt_pk_bf16_f32 v4, v35, v39
	v_cvt_pk_bf16_f32 v5, v105, v109
	ds_write2_b64 v6, v[2:3], v[4:5] offset1:16
	v_cvt_pk_bf16_f32 v2, v36, v40
	v_cvt_pk_bf16_f32 v3, v106, v110
	v_cvt_pk_bf16_f32 v4, v37, v41
	v_cvt_pk_bf16_f32 v5, v107, v111
	ds_write2_b64 v6, v[2:3], v[4:5] offset0:32 offset1:48
	s_waitcnt vmcnt(2)
	v_cvt_pk_bf16_f32 v2, v112, v116
	v_add_u32_e32 v6, v68, v75
	s_waitcnt vmcnt(0)
	v_cvt_pk_bf16_f32 v3, v120, v124
	v_cvt_pk_bf16_f32 v4, v113, v117
	v_cvt_pk_bf16_f32 v5, v121, v125
	ds_write2_b64 v6, v[2:3], v[4:5] offset1:16
	v_cvt_pk_bf16_f32 v2, v114, v118
	v_cvt_pk_bf16_f32 v3, v122, v126
	v_cvt_pk_bf16_f32 v4, v115, v119
	v_cvt_pk_bf16_f32 v5, v123, v127
	ds_write2_b64 v6, v[2:3], v[4:5] offset0:32 offset1:48
	v_add_u32_e32 v2, v77, v46
	ds_read_b128 v[2:5], v2
	v_add_u32_e32 v6, v79, v80
	ds_read_b128 v[6:9], v6
	s_waitcnt lgkmcnt(1)
	v_cndmask_b32_e64 v12, v2, v4, s[0:1]
	v_cndmask_b32_e64 v10, v4, v2, s[0:1]
	v_or_b32_e32 v2, s4, v76
	v_mul_u32_u24_e32 v42, 0x1600, v2
	v_cndmask_b32_e64 v13, v3, v5, s[0:1]
	v_cndmask_b32_e64 v11, v5, v3, s[0:1]
	v_lshl_add_u64 v[2:3], v[16:17], 0, v[42:43]
	global_store_dwordx4 v[2:3], v[10:13], off
	s_waitcnt lgkmcnt(0)
; #define GAS __attribute__((address_space(1)))
; #define LAS __attribute__((address_space(3)))
; __device__ __forceinline__ unsigned pk2(float lo, float hi) { f32x2_t v = {lo, hi}; bf16x2_t h = __builtin_convertvector(v, bf16x2_t); return __builtin_bit_cast(unsigned, h); }
; __device__ __forceinline__ void transpose_item(const float* W, int ldw, bf16* WT, int K, int k0, int sn0, int dn0, int lane, LAS unsigned char* T, const float* kgain = nullptr) {
;     ...
;     for (int j = 0; j < 4; ++j) { const int kb = kq + 4 * j, k = k0 + 4 * kb; f32x4 r[4];
; #pragma unroll
;         for (int jj = 0; jj < 4; ++jj) r[jj] = *(const GAS f32x4*)(W + (size_t)(k + jj) * ldw + sn0 + 4 * nb);
;         f32x4 g = {1.f, 1.f, 1.f, 1.f}; if (kgain) g = *(const GAS f32x4*)(kgain + k);
;         const f32x4 a = r[0] * g.x, bq = r[1] * g.y, c = r[2] * g.z, d = r[3] * g.w;
;         LAS unsigned char* t = T + (4 * nb) * 128 + ((kb ^ nb) << 3);
;         v2u w; w.x = pk2(a.x, bq.x); w.y = pk2(c.x, d.x); *(LAS v2u*)t = w;
;         w.x = pk2(a.y, bq.y); w.y = pk2(c.y, d.y); *(LAS v2u*)(t + 128) = w;
;         w.x = pk2(a.z, bq.z); w.y = pk2(c.z, d.z); *(LAS v2u*)(t + 256) = w;
;         w.x = pk2(a.w, bq.w); w.y = pk2(c.w, d.w); *(LAS v2u*)(t + 384) = w; }
; #pragma unroll
;     for (int i = 0; i < 8; ++i) { const int n = 8 * i + (lane >> 3), p = lane & 7, s = (n >> 2) & 15;
;         v4u o = *(const LAS v4u*)(T + n * 128 + ((p ^ (s >> 1)) << 4));
;         if (s & 1) { const unsigned tx = o.x, ty = o.y; o.x = o.z; o.y = o.w; o.z = tx; o.w = ty; }
;         *(GAS v4u*)(WT + (size_t)(dn0 + n) * K + k0 + 8 * p) = o; }
; template <int PART> __device__ __forceinline__ void deferred_transposes(Frame& F, int gw, int ngw) {
;     ...
;         if (r < I_G) { const int nblk = DFF / 64, kb = r / nblk, nb = r % nblk, sn0 = nb * 64; transpose_item(F.in[21], DFF, WguT, DM, kb * 64, sn0, 256 * (sn0 / 128) + 128 + (sn0 % 128), F.lane, F.lds + F.wave * 8192, F.in[19]); continue; } r -= I_G;
	v_cndmask_b32_e64 v4, v6, v8, s[0:1]
	v_cndmask_b32_e64 v2, v8, v6, s[0:1]
	v_or_b32_e32 v6, s4, v78
	v_mul_u32_u24_e32 v42, 0x1600, v6
	v_add_u32_e32 v6, v82, v83
	v_cndmask_b32_e64 v5, v7, v9, s[0:1]
	v_cndmask_b32_e64 v3, v9, v7, s[0:1]
	ds_read_b128 v[6:9], v6
	v_lshl_add_u64 v[10:11], v[16:17], 0, v[42:43]
	global_store_dwordx4 v[10:11], v[2:5], off
	s_nop 1
	v_add_u32_e32 v2, v85, v86
	ds_read_b128 v[2:5], v2
	s_waitcnt lgkmcnt(1)
	v_cndmask_b32_e64 v10, v6, v8, s[0:1]
	v_cndmask_b32_e64 v8, v8, v6, s[0:1]
	v_or_b32_e32 v6, s4, v81
	v_mul_u32_u24_e32 v42, 0x1600, v6
	v_cndmask_b32_e64 v11, v7, v9, s[0:1]
	v_cndmask_b32_e64 v9, v9, v7, s[0:1]
	v_lshl_add_u64 v[6:7], v[16:17], 0, v[42:43]
	global_store_dwordx4 v[6:7], v[8:11], off
	s_waitcnt lgkmcnt(0)
	v_cndmask_b32_e64 v6, v2, v4, s[0:1]
	v_cndmask_b32_e64 v4, v4, v2, s[0:1]
	v_or_b32_e32 v2, s4, v84
	v_mul_u32_u24_e32 v42, 0x1600, v2
	v_add_u32_e32 v2, v88, v89
	v_cndmask_b32_e64 v7, v3, v5, s[0:1]
	v_cndmask_b32_e64 v5, v5, v3, s[0:1]
	ds_read_b128 v[8:11], v2
	v_lshl_add_u64 v[2:3], v[16:17], 0, v[42:43]
	global_store_dwordx4 v[2:3], v[4:7], off
	v_add_u32_e32 v2, v91, v92
	ds_read_b128 v[2:5], v2
	v_or_b32_e32 v6, s4, v87
	v_mul_u32_u24_e32 v42, 0x1600, v6
	s_waitcnt lgkmcnt(1)
	v_cndmask_b32_e64 v13, v9, v11, s[0:1]
	v_cndmask_b32_e64 v12, v8, v10, s[0:1]
	v_cndmask_b32_e64 v11, v11, v9, s[0:1]
	v_cndmask_b32_e64 v10, v10, v8, s[0:1]
	v_lshl_add_u64 v[6:7], v[16:17], 0, v[42:43]
	global_store_dwordx4 v[6:7], v[10:13], off
	s_waitcnt lgkmcnt(0)
	v_cndmask_b32_e64 v6, v2, v4, s[0:1]
	v_cndmask_b32_e64 v4, v4, v2, s[0:1]
	v_or_b32_e32 v2, s4, v90
	v_mul_u32_u24_e32 v42, 0x1600, v2
	v_add_u32_e32 v2, v94, v95
	ds_read_b128 v[8:11], v2
	v_cndmask_b32_e64 v7, v3, v5, s[0:1]
	v_cndmask_b32_e64 v5, v5, v3, s[0:1]
	v_lshl_add_u64 v[2:3], v[16:17], 0, v[42:43]
	global_store_dwordx4 v[2:3], v[4:7], off
	v_add_u32_e32 v2, v97, v98
	ds_read_b128 v[12:15], v2
	v_or_b32_e32 v6, s4, v93
	v_mul_u32_u24_e32 v42, 0x1600, v6
	s_waitcnt lgkmcnt(1)
	v_cndmask_b32_e64 v5, v9, v11, s[0:1]
	v_cndmask_b32_e64 v4, v8, v10, s[0:1]
	v_cndmask_b32_e64 v3, v11, v9, s[0:1]
	v_cndmask_b32_e64 v2, v10, v8, s[0:1]
	v_lshl_add_u64 v[6:7], v[16:17], 0, v[42:43]
	global_store_dwordx4 v[6:7], v[2:5], off
	v_or_b32_e32 v6, s4, v96
	v_mul_u32_u24_e32 v42, 0x1600, v6
	s_waitcnt lgkmcnt(0)
	v_cndmask_b32_e64 v5, v13, v15, s[0:1]
	v_cndmask_b32_e64 v4, v12, v14, s[0:1]
	v_cndmask_b32_e64 v3, v15, v13, s[0:1]
	v_cndmask_b32_e64 v2, v14, v12, s[0:1]
	v_lshl_add_u64 v[6:7], v[16:17], 0, v[42:43]
	s_mov_b64 s[4:5], 0
.LBB0_894:
	s_andn2_b64 vcc, exec, s[4:5]
	s_cbranch_vccnz .LBB0_904
	s_add_i32 s4, s3, 0x2c0
	s_and_b32 s5, s4, 0xffff
	s_mul_i32 s5, s5, 0xba2f
	s_lshr_b32 s6, s5, 21
	s_mul_i32 s5, s6, 44
	s_sub_i32 s4, s4, s5
	s_and_b32 s5, s4, 0xffff
	s_lshl_b32 s4, s6, 6
	s_lshl_b32 s12, s5, 8
	v_or_b32_e32 v3, s4, v99
	v_lshl_add_u64 v[64:65], v[50:51], 0, s[12:13]
	v_mad_u32_u24 v42, v3, s21, s21
	v_lshl_add_u64 v[6:7], v[64:65], 0, v[42:43]
	v_mad_u32_u24 v42, v3, s21, v47
	v_mad_u64_u32 v[4:5], s[6:7], v3, s21, v[64:65]
	v_lshl_add_u64 v[8:9], v[64:65], 0, v[42:43]
	v_mad_u32_u24 v42, v3, s21, v103
	global_load_dwordx4 v[14:17], v[4:5], off nt
	s_nop 0
	global_load_dwordx4 v[4:7], v[6:7], off nt
	v_lshl_add_u64 v[10:11], v[64:65], 0, v[42:43]
	global_load_dwordx4 v[30:33], v[8:9], off nt
	global_load_dwordx4 v[22:25], v[10:11], off nt
	v_cndmask_b32_e64 v8, 0, 1, s[14:15]
	v_mov_b32_e32 v2, 1.0
	v_cmp_ne_u32_e64 s[6:7], 1, v8
	s_andn2_b64 vcc, exec, s[14:15]
	v_mov_b32_e32 v38, 1.0
	v_mov_b32_e32 v8, 1.0
	v_mov_b32_e32 v40, 1.0
	v_mov_b32_e32 v66, 1.0
	s_cbranch_vccnz .LBB0_897
	v_readlane_b32 s60, v238, 29
	v_lshlrev_b32_e32 v3, 2, v3
	v_readlane_b32 s66, v238, 35
	v_readlane_b32 s67, v238, 36
	v_readlane_b32 s61, v238, 30
	v_readlane_b32 s62, v238, 31
	v_readlane_b32 s63, v238, 32
	v_readlane_b32 s64, v238, 33
	v_readlane_b32 s65, v238, 34
	global_load_dwordx4 v[38:41], v3, s[66:67]
	v_readlane_b32 s68, v238, 37
	v_readlane_b32 s69, v238, 38
	v_readlane_b32 s70, v238, 39
	v_readlane_b32 s71, v238, 40
	v_readlane_b32 s72, v238, 41
	v_readlane_b32 s73, v238, 42
	v_readlane_b32 s74, v238, 43
	v_readlane_b32 s75, v238, 44
	s_waitcnt vmcnt(0)
	v_mov_b32_e32 v8, v39
	v_mov_b32_e32 v66, v41
.LBB0_897:
	v_or_b32_e32 v3, s4, v100
	v_mad_u32_u24 v42, v3, s21, s21
	v_lshl_add_u64 v[12:13], v[64:65], 0, v[42:43]
	v_mad_u32_u24 v42, v3, s21, v47
	v_lshl_add_u64 v[26:27], v[64:65], 0, v[42:43]
	v_mad_u32_u24 v42, v3, s21, v103
	v_mad_u64_u32 v[10:11], s[22:23], v3, s21, v[64:65]
	s_waitcnt lgkmcnt(0)
	v_lshl_add_u64 v[28:29], v[64:65], 0, v[42:43]
	global_load_dwordx4 v[18:21], v[10:11], off nt
	s_nop 0
	global_load_dwordx4 v[10:13], v[12:13], off nt
	s_nop 0
	global_load_dwordx4 v[34:37], v[26:27], off nt
	s_nop 0
	global_load_dwordx4 v[26:29], v[28:29], off nt
	s_waitcnt vmcnt(0)
	v_pk_mul_f32 v[14:15], v[14:15], v[38:39] op_sel_hi:[1,0]
	v_pk_mul_f32 v[4:5], v[4:5], v[8:9] op_sel_hi:[1,0]
	v_pk_mul_f32 v[30:31], v[30:31], v[40:41] op_sel_hi:[1,0]
	v_pk_mul_f32 v[22:23], v[22:23], v[66:67] op_sel_hi:[1,0]
	v_pk_mul_f32 v[16:17], v[16:17], v[38:39] op_sel_hi:[1,0]
	v_pk_mul_f32 v[6:7], v[6:7], v[8:9] op_sel_hi:[1,0]
	v_pk_mul_f32 v[8:9], v[32:33], v[40:41] op_sel_hi:[1,0]
	v_pk_mul_f32 v[24:25], v[24:25], v[66:67] op_sel_hi:[1,0]
	v_cvt_pk_bf16_f32 v32, v14, v4
	v_cvt_pk_bf16_f32 v33, v30, v22
	v_add_u32_e32 v14, v68, v69
	v_cvt_pk_bf16_f32 v4, v15, v5
	v_cvt_pk_bf16_f32 v5, v31, v23
	ds_write2_b64 v14, v[32:33], v[4:5] offset1:16
	v_cvt_pk_bf16_f32 v4, v16, v6
	v_cvt_pk_bf16_f32 v5, v8, v24
	v_cvt_pk_bf16_f32 v6, v17, v7
	v_cvt_pk_bf16_f32 v7, v9, v25
	ds_write2_b64 v14, v[4:5], v[6:7] offset0:32 offset1:48
	s_and_b64 vcc, exec, s[6:7]
	v_mov_b32_e32 v38, 1.0
	v_mov_b32_e32 v4, 1.0
	v_mov_b32_e32 v40, 1.0
	s_cbranch_vccnz .LBB0_899
	v_readlane_b32 s60, v238, 29
	v_lshlrev_b32_e32 v2, 2, v3
	v_readlane_b32 s66, v238, 35
	v_readlane_b32 s67, v238, 36
	v_readlane_b32 s61, v238, 30
	v_readlane_b32 s62, v238, 31
	v_readlane_b32 s63, v238, 32
	v_readlane_b32 s64, v238, 33
	v_readlane_b32 s65, v238, 34
	global_load_dwordx4 v[2:5], v2, s[66:67]
	v_readlane_b32 s68, v238, 37
	v_readlane_b32 s69, v238, 38
	v_readlane_b32 s70, v238, 39
	v_readlane_b32 s71, v238, 40
	v_readlane_b32 s72, v238, 41
	v_readlane_b32 s73, v238, 42
	v_readlane_b32 s74, v238, 43
	v_readlane_b32 s75, v238, 44
	s_waitcnt vmcnt(0)
	v_mov_b32_e32 v38, v3
	v_mov_b32_e32 v40, v5
; #define GAS __attribute__((address_space(1)))
; #define LAS __attribute__((address_space(3)))
; __device__ __forceinline__ unsigned pk2(float lo, float hi) { f32x2_t v = {lo, hi}; bf16x2_t h = __builtin_convertvector(v, bf16x2_t); return __builtin_bit_cast(unsigned, h); }
; __device__ __forceinline__ void transpose_item(const float* W, int ldw, bf16* WT, int K, int k0, int sn0, int dn0, int lane, LAS unsigned char* T, const float* kgain = nullptr) {
;     ...
;     for (int j = 0; j < 4; ++j) { const int kb = kq + 4 * j, k = k0 + 4 * kb; f32x4 r[4];
; #pragma unroll
;         for (int jj = 0; jj < 4; ++jj) r[jj] = *(const GAS f32x4*)(W + (size_t)(k + jj) * ldw + sn0 + 4 * nb);
;         f32x4 g = {1.f, 1.f, 1.f, 1.f}; if (kgain) g = *(const GAS f32x4*)(kgain + k);
;         const f32x4 a = r[0] * g.x, bq = r[1] * g.y, c = r[2] * g.z, d = r[3] * g.w;
;         LAS unsigned char* t = T + (4 * nb) * 128 + ((kb ^ nb) << 3);
;         v2u w; w.x = pk2(a.x, bq.x); w.y = pk2(c.x, d.x); *(LAS v2u*)t = w;
;         w.x = pk2(a.y, bq.y); w.y = pk2(c.y, d.y); *(LAS v2u*)(t + 128) = w;
;         w.x = pk2(a.z, bq.z); w.y = pk2(c.z, d.z); *(LAS v2u*)(t + 256) = w;
;         w.x = pk2(a.w, bq.w); w.y = pk2(c.w, d.w); *(LAS v2u*)(t + 384) = w; }
.LBB0_899:
	v_or_b32_e32 v3, s4, v101
	v_mad_u32_u24 v42, v3, s21, s21
	v_lshl_add_u64 v[8:9], v[64:65], 0, v[42:43]
	v_mad_u32_u24 v42, v3, s21, v47
	v_lshl_add_u64 v[22:23], v[64:65], 0, v[42:43]
	v_mad_u32_u24 v42, v3, s21, v103
	v_mad_u64_u32 v[6:7], s[22:23], v3, s21, v[64:65]
	v_lshl_add_u64 v[24:25], v[64:65], 0, v[42:43]
	global_load_dwordx4 v[14:17], v[6:7], off nt
	s_nop 0
	global_load_dwordx4 v[6:9], v[8:9], off nt
	s_nop 0
	global_load_dwordx4 v[30:33], v[22:23], off nt
	s_nop 0
	global_load_dwordx4 v[22:25], v[24:25], off nt
	v_pk_mul_f32 v[18:19], v[18:19], v[2:3] op_sel_hi:[1,0]
	v_pk_mul_f32 v[10:11], v[10:11], v[38:39] op_sel_hi:[1,0]
	v_pk_mul_f32 v[36:37], v[36:37], v[4:5] op_sel_hi:[1,0]
	v_pk_mul_f32 v[4:5], v[34:35], v[4:5] op_sel_hi:[1,0]
	v_pk_mul_f32 v[26:27], v[26:27], v[40:41] op_sel_hi:[1,0]
	v_pk_mul_f32 v[20:21], v[20:21], v[2:3] op_sel_hi:[1,0]
	v_pk_mul_f32 v[12:13], v[12:13], v[38:39] op_sel_hi:[1,0]
	v_pk_mul_f32 v[28:29], v[28:29], v[40:41] op_sel_hi:[1,0]
	v_cvt_pk_bf16_f32 v34, v18, v10
	v_cvt_pk_bf16_f32 v35, v4, v26
	v_add_u32_e32 v2, v68, v71
	v_cvt_pk_bf16_f32 v4, v19, v11
	v_cvt_pk_bf16_f32 v5, v5, v27
	ds_write2_b64 v2, v[34:35], v[4:5] offset1:16
	v_cvt_pk_bf16_f32 v4, v20, v12
	v_cvt_pk_bf16_f32 v5, v36, v28
	v_cvt_pk_bf16_f32 v10, v21, v13
	v_cvt_pk_bf16_f32 v11, v37, v29
	ds_write2_b64 v2, v[4:5], v[10:11] offset0:32 offset1:48
	v_mov_b32_e32 v2, 1.0
	s_and_b64 vcc, exec, s[6:7]
	v_mov_b32_e32 v10, 1.0
	v_mov_b32_e32 v4, 1.0
	v_mov_b32_e32 v12, 1.0
	v_mov_b32_e32 v66, 1.0
	s_cbranch_vccnz .LBB0_901
	v_readlane_b32 s60, v238, 29
	v_lshlrev_b32_e32 v3, 2, v3
	v_readlane_b32 s66, v238, 35
	v_readlane_b32 s67, v238, 36
	v_readlane_b32 s61, v238, 30
	v_readlane_b32 s62, v238, 31
	v_readlane_b32 s63, v238, 32
	v_readlane_b32 s64, v238, 33
	v_readlane_b32 s65, v238, 34
	global_load_dwordx4 v[10:13], v3, s[66:67]
	v_readlane_b32 s68, v238, 37
	v_readlane_b32 s69, v238, 38
	v_readlane_b32 s70, v238, 39
	v_readlane_b32 s71, v238, 40
	v_readlane_b32 s72, v238, 41
	v_readlane_b32 s73, v238, 42
	v_readlane_b32 s74, v238, 43
	v_readlane_b32 s75, v238, 44
	s_waitcnt vmcnt(0)
	v_mov_b32_e32 v4, v11
	v_mov_b32_e32 v66, v13
.LBB0_901:
	v_or_b32_e32 v3, s4, v102
	v_mad_u32_u24 v42, v3, s21, s21
	v_lshl_add_u64 v[20:21], v[64:65], 0, v[42:43]
	v_mad_u32_u24 v42, v3, s21, v47
	v_lshl_add_u64 v[26:27], v[64:65], 0, v[42:43]
	v_mad_u32_u24 v42, v3, s21, v103
	v_mad_u64_u32 v[18:19], s[22:23], v3, s21, v[64:65]
	v_lshl_add_u64 v[28:29], v[64:65], 0, v[42:43]
	global_load_dwordx4 v[34:37], v[18:19], off nt
	s_nop 0
	global_load_dwordx4 v[18:21], v[20:21], off nt
	s_nop 0
	global_load_dwordx4 v[38:41], v[26:27], off nt
	s_nop 0
	global_load_dwordx4 v[26:29], v[28:29], off nt
	s_waitcnt vmcnt(7)
	v_pk_mul_f32 v[16:17], v[16:17], v[10:11] op_sel_hi:[1,0]
	v_pk_mul_f32 v[10:11], v[14:15], v[10:11] op_sel_hi:[1,0]
	s_waitcnt vmcnt(6)
	v_pk_mul_f32 v[8:9], v[8:9], v[4:5] op_sel_hi:[1,0]
	v_pk_mul_f32 v[4:5], v[6:7], v[4:5] op_sel_hi:[1,0]
	s_waitcnt vmcnt(5)
	v_pk_mul_f32 v[6:7], v[32:33], v[12:13] op_sel_hi:[1,0]
	v_pk_mul_f32 v[12:13], v[30:31], v[12:13] op_sel_hi:[1,0]
	s_waitcnt vmcnt(4)
	v_pk_mul_f32 v[22:23], v[22:23], v[66:67] op_sel_hi:[1,0]
	v_pk_mul_f32 v[14:15], v[24:25], v[66:67] op_sel_hi:[1,0]
	v_cvt_pk_bf16_f32 v24, v10, v4
	v_cvt_pk_bf16_f32 v25, v12, v22
	v_add_u32_e32 v10, v68, v73
	v_cvt_pk_bf16_f32 v4, v11, v5
	v_cvt_pk_bf16_f32 v5, v13, v23
	ds_write2_b64 v10, v[24:25], v[4:5] offset1:16
	v_cvt_pk_bf16_f32 v4, v16, v8
	v_cvt_pk_bf16_f32 v5, v6, v14
	v_cvt_pk_bf16_f32 v6, v17, v9
	v_cvt_pk_bf16_f32 v7, v7, v15
	ds_write2_b64 v10, v[4:5], v[6:7] offset0:32 offset1:48
	s_and_b64 vcc, exec, s[6:7]
	v_mov_b32_e32 v8, 1.0
	v_mov_b32_e32 v4, 1.0
	v_mov_b32_e32 v6, 1.0
	s_cbranch_vccnz .LBB0_903
	v_readlane_b32 s60, v238, 29
	v_lshlrev_b32_e32 v2, 2, v3
	v_readlane_b32 s66, v238, 35
	v_readlane_b32 s67, v238, 36
	v_readlane_b32 s61, v238, 30
	v_readlane_b32 s62, v238, 31
	v_readlane_b32 s63, v238, 32
	v_readlane_b32 s64, v238, 33
	v_readlane_b32 s65, v238, 34
	global_load_dwordx4 v[2:5], v2, s[66:67]
	v_readlane_b32 s68, v238, 37
	v_readlane_b32 s69, v238, 38
	v_readlane_b32 s70, v238, 39
	v_readlane_b32 s71, v238, 40
	v_readlane_b32 s72, v238, 41
	v_readlane_b32 s73, v238, 42
	v_readlane_b32 s74, v238, 43
	v_readlane_b32 s75, v238, 44
	s_waitcnt vmcnt(0)
	v_mov_b32_e32 v8, v3
	v_mov_b32_e32 v6, v5

; #define GAS __attribute__((address_space(1)))
; __device__ __forceinline__ void transpose_item(const float* W, int ldw, bf16* WT, int K, int k0, int sn0, int dn0, int lane, LAS unsigned char* T, const float* kgain = nullptr) {
;     ...
;     for (int j = 0; j < 4; ++j) { const int kb = kq + 4 * j, k = k0 + 4 * kb; f32x4 r[4];
; #pragma unroll
;         for (int jj = 0; jj < 4; ++jj) r[jj] = *(const GAS f32x4*)(W + (size_t)(k + jj) * ldw + sn0 + 4 * nb);
;         f32x4 g = {1.f, 1.f, 1.f, 1.f}; if (kgain) g = *(const GAS f32x4*)(kgain + k);
; template <int PART> __device__ __forceinline__ void deferred_transposes(Frame& F, int gw, int ngw) {
;     ...
;         if (r < I_G) { const int nblk = DFF / 64, kb = r / nblk, nb = r % nblk, sn0 = nb * 64; transpose_item(F.in[20], DFF, WguT, DM, kb * 64, sn0, 256 * (sn0 / 128) + (sn0 % 128), F.lane, F.lds + F.wave * 8192, F.in[19]); continue; } r -= I_G;
.LBB0_905:
	s_andn2_b64 vcc, exec, s[4:5]
	s_cbranch_vccnz .LBB0_915
	s_add_i32 s4, s3, 0x580
	s_and_b32 s5, s4, 0xffff
	s_mul_i32 s5, s5, 0xba2f
	s_lshr_b32 s6, s5, 21
	s_mul_i32 s5, s6, 44
	s_sub_i32 s4, s4, s5
	s_and_b32 s5, s4, 0xffff
	s_lshl_b32 s4, s6, 6
	s_lshl_b32 s12, s5, 8
	v_or_b32_e32 v3, s4, v99
	v_lshl_add_u64 v[64:65], v[54:55], 0, s[12:13]
	v_mad_u32_u24 v42, v3, s21, s21
	v_lshl_add_u64 v[6:7], v[64:65], 0, v[42:43]
	v_mad_u32_u24 v42, v3, s21, v47
	v_mad_u64_u32 v[4:5], s[6:7], v3, s21, v[64:65]
	v_lshl_add_u64 v[8:9], v[64:65], 0, v[42:43]
	v_mad_u32_u24 v42, v3, s21, v103
	global_load_dwordx4 v[14:17], v[4:5], off nt
	s_nop 0
	global_load_dwordx4 v[4:7], v[6:7], off nt
	v_lshl_add_u64 v[10:11], v[64:65], 0, v[42:43]
	global_load_dwordx4 v[30:33], v[8:9], off nt
	global_load_dwordx4 v[22:25], v[10:11], off nt
	v_cndmask_b32_e64 v8, 0, 1, s[14:15]
	v_mov_b32_e32 v2, 1.0
	v_cmp_ne_u32_e64 s[6:7], 1, v8
	s_andn2_b64 vcc, exec, s[14:15]
	v_mov_b32_e32 v38, 1.0
	v_mov_b32_e32 v8, 1.0
	v_mov_b32_e32 v40, 1.0
	v_mov_b32_e32 v66, 1.0
	s_cbranch_vccnz .LBB0_908
	v_readlane_b32 s60, v238, 29
	v_lshlrev_b32_e32 v3, 2, v3
	v_readlane_b32 s66, v238, 35
	v_readlane_b32 s67, v238, 36
	v_readlane_b32 s61, v238, 30
	v_readlane_b32 s62, v238, 31
	v_readlane_b32 s63, v238, 32
	v_readlane_b32 s64, v238, 33
	v_readlane_b32 s65, v238, 34
	global_load_dwordx4 v[38:41], v3, s[66:67]
	v_readlane_b32 s68, v238, 37
	v_readlane_b32 s69, v238, 38
	v_readlane_b32 s70, v238, 39
	v_readlane_b32 s71, v238, 40
	v_readlane_b32 s72, v238, 41
	v_readlane_b32 s73, v238, 42
	v_readlane_b32 s74, v238, 43
	v_readlane_b32 s75, v238, 44
	s_waitcnt vmcnt(0)
	v_mov_b32_e32 v8, v39
	v_mov_b32_e32 v66, v41

; #define GAS __attribute__((address_space(1)))
; #define LAS __attribute__((address_space(3)))
; __device__ __forceinline__ unsigned pk2(float lo, float hi) { f32x2_t v = {lo, hi}; bf16x2_t h = __builtin_convertvector(v, bf16x2_t); return __builtin_bit_cast(unsigned, h); }
; __device__ __forceinline__ void transpose_item(const float* W, int ldw, bf16* WT, int K, int k0, int sn0, int dn0, int lane, LAS unsigned char* T, const float* kgain = nullptr) {
;     ...
;     for (int j = 0; j < 4; ++j) { const int kb = kq + 4 * j, k = k0 + 4 * kb; f32x4 r[4];
; #pragma unroll
;         for (int jj = 0; jj < 4; ++jj) r[jj] = *(const GAS f32x4*)(W + (size_t)(k + jj) * ldw + sn0 + 4 * nb);
;         f32x4 g = {1.f, 1.f, 1.f, 1.f}; if (kgain) g = *(const GAS f32x4*)(kgain + k);
;         const f32x4 a = r[0] * g.x, bq = r[1] * g.y, c = r[2] * g.z, d = r[3] * g.w;
;         LAS unsigned char* t = T + (4 * nb) * 128 + ((kb ^ nb) << 3);
;         v2u w; w.x = pk2(a.x, bq.x); w.y = pk2(c.x, d.x); *(LAS v2u*)t = w;
;         w.x = pk2(a.y, bq.y); w.y = pk2(c.y, d.y); *(LAS v2u*)(t + 128) = w;
;         w.x = pk2(a.z, bq.z); w.y = pk2(c.z, d.z); *(LAS v2u*)(t + 256) = w;
;         w.x = pk2(a.w, bq.w); w.y = pk2(c.w, d.w); *(LAS v2u*)(t + 384) = w; }
; template <int PART> __device__ __forceinline__ void deferred_transposes(Frame& F, int gw, int ngw) {
;     ...
;         if (r < I_OUT) { const int nblk = DM / 64, kb = r / nblk, nb = r % nblk; transpose_item(F.in[18], DM, WoutT, DM, kb * 64, nb * 64, nb * 64, F.lane, F.lds + F.wave * 8192); continue; } r -= I_OUT;
.LBB0_916:
	s_andn2_b64 vcc, exec, s[4:5]
	s_cbranch_vccnz .LBB0_918
	s_and_b32 s4, s17, 0xffffffc0
	s_addk_i32 s4, 0x1a00
	v_or_b32_e32 v42, s4, v99
	s_and_b32 s6, s19, 0x3c0
	v_lshlrev_b64 v[2:3], 12, v[42:43]
	v_or_b32_e32 v4, 1, v42
	v_or_b32_e32 v10, 2, v42
	v_or_b32_e32 v42, 3, v42
	s_lshl_b32 s12, s6, 2
	v_mov_b32_e32 v5, v43
	v_mov_b32_e32 v11, v43
	v_lshlrev_b64 v[12:13], 12, v[42:43]
	v_or_b32_e32 v42, s4, v100
	v_lshl_add_u64 v[64:65], v[56:57], 0, s[12:13]
	v_lshlrev_b64 v[4:5], 12, v[4:5]
	v_lshlrev_b64 v[10:11], 12, v[10:11]
	s_waitcnt vmcnt(0)
	v_lshlrev_b64 v[18:19], 12, v[42:43]
	v_or_b32_e32 v20, 1, v42
	v_mov_b32_e32 v21, v43
	v_or_b32_e32 v26, 2, v42
	v_mov_b32_e32 v27, v43
	v_or_b32_e32 v42, 3, v42
	v_lshl_add_u64 v[2:3], v[64:65], 0, v[2:3]
	v_lshl_add_u64 v[6:7], v[64:65], 0, v[4:5]
	v_lshl_add_u64 v[10:11], v[64:65], 0, v[10:11]
	v_lshl_add_u64 v[14:15], v[64:65], 0, v[12:13]
	v_lshlrev_b64 v[20:21], 12, v[20:21]
	v_lshlrev_b64 v[26:27], 12, v[26:27]
	s_waitcnt lgkmcnt(0)
	v_lshlrev_b64 v[28:29], 12, v[42:43]
	v_or_b32_e32 v42, s4, v101
	global_load_dwordx4 v[2:5], v[2:3], off nt
	s_nop 0
	global_load_dwordx4 v[6:9], v[6:7], off nt
	s_nop 0
	global_load_dwordx4 v[10:13], v[10:11], off nt
	s_nop 0
	global_load_dwordx4 v[14:17], v[14:15], off nt
	v_lshl_add_u64 v[18:19], v[64:65], 0, v[18:19]
	v_lshl_add_u64 v[22:23], v[64:65], 0, v[20:21]
	v_lshl_add_u64 v[26:27], v[64:65], 0, v[26:27]
	v_lshl_add_u64 v[30:31], v[64:65], 0, v[28:29]
	v_lshlrev_b64 v[34:35], 12, v[42:43]
	v_or_b32_e32 v36, 1, v42
	v_mov_b32_e32 v37, v43
	v_or_b32_e32 v104, 2, v42
	v_mov_b32_e32 v105, v43
	v_or_b32_e32 v42, 3, v42
	global_load_dwordx4 v[18:21], v[18:19], off nt
	s_nop 0
	global_load_dwordx4 v[22:25], v[22:23], off nt
	s_nop 0
	global_load_dwordx4 v[26:29], v[26:27], off nt
	s_nop 0
	global_load_dwordx4 v[30:33], v[30:31], off nt
	v_lshlrev_b64 v[36:37], 12, v[36:37]
	v_lshlrev_b64 v[104:105], 12, v[104:105]
	v_lshlrev_b64 v[106:107], 12, v[42:43]
	v_or_b32_e32 v42, s4, v102
	v_lshl_add_u64 v[34:35], v[64:65], 0, v[34:35]
	v_lshl_add_u64 v[38:39], v[64:65], 0, v[36:37]
	v_lshl_add_u64 v[104:105], v[64:65], 0, v[104:105]
	v_lshl_add_u64 v[108:109], v[64:65], 0, v[106:107]
	v_or_b32_e32 v114, 1, v42
	v_mov_b32_e32 v115, v43
	v_or_b32_e32 v120, 2, v42
	v_mov_b32_e32 v121, v43
	global_load_dwordx4 v[34:37], v[34:35], off nt
	s_nop 0
	global_load_dwordx4 v[38:41], v[38:39], off nt
	s_nop 0
	global_load_dwordx4 v[104:107], v[104:105], off nt
	s_nop 0
	global_load_dwordx4 v[108:111], v[108:109], off nt
	v_lshlrev_b64 v[112:113], 12, v[42:43]
	v_lshlrev_b64 v[114:115], 12, v[114:115]
	v_lshlrev_b64 v[120:121], 12, v[120:121]
	v_or_b32_e32 v42, 3, v42
	v_lshl_add_u64 v[112:113], v[64:65], 0, v[112:113]
	v_lshl_add_u64 v[116:117], v[64:65], 0, v[114:115]
	v_lshl_add_u64 v[120:121], v[64:65], 0, v[120:121]
	v_lshlrev_b64 v[122:123], 12, v[42:43]
	global_load_dwordx4 v[112:115], v[112:113], off nt
	s_nop 0
	global_load_dwordx4 v[116:119], v[116:117], off nt
	v_lshl_add_u64 v[64:65], v[64:65], 0, v[122:123]
	global_load_dwordx4 v[120:123], v[120:121], off nt
	s_nop 0
	global_load_dwordx4 v[124:127], v[64:65], off nt
	v_add_u32_e32 v42, v68, v69
	s_mov_b32 s5, s13
	s_waitcnt vmcnt(14)
	v_cvt_pk_bf16_f32 v64, v2, v6
	s_waitcnt vmcnt(12)
	v_cvt_pk_bf16_f32 v65, v10, v14
	v_cvt_pk_bf16_f32 v2, v3, v7
	v_cvt_pk_bf16_f32 v3, v11, v15
	v_cvt_pk_bf16_f32 v6, v4, v8
	v_cvt_pk_bf16_f32 v4, v5, v9
	v_cvt_pk_bf16_f32 v5, v13, v17
	v_cvt_pk_bf16_f32 v7, v12, v16
	ds_write2_b64 v42, v[64:65], v[2:3] offset1:16
	ds_write2_b64 v42, v[6:7], v[4:5] offset0:32 offset1:48
	v_add_u32_e32 v6, v68, v71
	v_lshl_add_u64 v[16:17], s[4:5], 1, v[58:59]
	s_waitcnt vmcnt(10)
	v_cvt_pk_bf16_f32 v2, v18, v22
	s_waitcnt vmcnt(8)
	v_cvt_pk_bf16_f32 v3, v26, v30
	v_cvt_pk_bf16_f32 v4, v19, v23
	v_cvt_pk_bf16_f32 v5, v27, v31
	ds_write2_b64 v6, v[2:3], v[4:5] offset1:16
	v_cvt_pk_bf16_f32 v2, v20, v24
	v_cvt_pk_bf16_f32 v3, v28, v32
	v_cvt_pk_bf16_f32 v4, v21, v25
	v_cvt_pk_bf16_f32 v5, v29, v33
	ds_write2_b64 v6, v[2:3], v[4:5] offset0:32 offset1:48
	v_add_u32_e32 v6, v68, v73
	s_waitcnt vmcnt(6)
; #define GAS __attribute__((address_space(1)))
; #define LAS __attribute__((address_space(3)))
; __device__ __forceinline__ unsigned pk2(float lo, float hi) { f32x2_t v = {lo, hi}; bf16x2_t h = __builtin_convertvector(v, bf16x2_t); return __builtin_bit_cast(unsigned, h); }
; __device__ __forceinline__ void transpose_item(const float* W, int ldw, bf16* WT, int K, int k0, int sn0, int dn0, int lane, LAS unsigned char* T, const float* kgain = nullptr) {
;     ...
;         LAS unsigned char* t = T + (4 * nb) * 128 + ((kb ^ nb) << 3);
;         v2u w; w.x = pk2(a.x, bq.x); w.y = pk2(c.x, d.x); *(LAS v2u*)t = w;
;         w.x = pk2(a.y, bq.y); w.y = pk2(c.y, d.y); *(LAS v2u*)(t + 128) = w;
;         w.x = pk2(a.z, bq.z); w.y = pk2(c.z, d.z); *(LAS v2u*)(t + 256) = w;
;         w.x = pk2(a.w, bq.w); w.y = pk2(c.w, d.w); *(LAS v2u*)(t + 384) = w; }
; #pragma unroll
;     for (int i = 0; i < 8; ++i) { const int n = 8 * i + (lane >> 3), p = lane & 7, s = (n >> 2) & 15;
;         v4u o = *(const LAS v4u*)(T + n * 128 + ((p ^ (s >> 1)) << 4));
;         if (s & 1) { const unsigned tx = o.x, ty = o.y; o.x = o.z; o.y = o.w; o.z = tx; o.w = ty; }
;         *(GAS v4u*)(WT + (size_t)(dn0 + n) * K + k0 + 8 * p) = o; }
	v_cvt_pk_bf16_f32 v2, v34, v38
	s_waitcnt vmcnt(4)
	v_cvt_pk_bf16_f32 v3, v104, v108
	v_cvt_pk_bf16_f32 v4, v35, v39
	v_cvt_pk_bf16_f32 v5, v105, v109
	ds_write2_b64 v6, v[2:3], v[4:5] offset1:16
	v_cvt_pk_bf16_f32 v2, v36, v40
	v_cvt_pk_bf16_f32 v3, v106, v110
	v_cvt_pk_bf16_f32 v4, v37, v41
	v_cvt_pk_bf16_f32 v5, v107, v111
	ds_write2_b64 v6, v[2:3], v[4:5] offset0:32 offset1:48
	s_waitcnt vmcnt(2)
	v_cvt_pk_bf16_f32 v2, v112, v116
	v_add_u32_e32 v6, v68, v75
	s_waitcnt vmcnt(0)
	v_cvt_pk_bf16_f32 v3, v120, v124
	v_cvt_pk_bf16_f32 v4, v113, v117
	v_cvt_pk_bf16_f32 v5, v121, v125
	ds_write2_b64 v6, v[2:3], v[4:5] offset1:16
	v_cvt_pk_bf16_f32 v2, v114, v118
	v_cvt_pk_bf16_f32 v3, v122, v126
	v_cvt_pk_bf16_f32 v4, v115, v119
	v_cvt_pk_bf16_f32 v5, v123, v127
	ds_write2_b64 v6, v[2:3], v[4:5] offset0:32 offset1:48
	v_add_u32_e32 v2, v77, v46
	ds_read_b128 v[2:5], v2
	v_add_u32_e32 v6, v79, v80
	ds_read_b128 v[6:9], v6
	s_waitcnt lgkmcnt(1)
	v_cndmask_b32_e64 v12, v2, v4, s[0:1]
	v_cndmask_b32_e64 v10, v4, v2, s[0:1]
	v_or_b32_e32 v2, s6, v76
	v_lshlrev_b32_e32 v42, 11, v2
	v_cndmask_b32_e64 v13, v3, v5, s[0:1]
	v_cndmask_b32_e64 v11, v5, v3, s[0:1]
	v_lshl_add_u64 v[2:3], v[16:17], 0, v[42:43]
	global_store_dwordx4 v[2:3], v[10:13], off
	s_waitcnt lgkmcnt(0)
	v_cndmask_b32_e64 v4, v6, v8, s[0:1]
	v_cndmask_b32_e64 v2, v8, v6, s[0:1]
	v_or_b32_e32 v6, s6, v78
	v_lshlrev_b32_e32 v42, 11, v6
	v_add_u32_e32 v6, v82, v83
	v_cndmask_b32_e64 v5, v7, v9, s[0:1]
	v_cndmask_b32_e64 v3, v9, v7, s[0:1]
	ds_read_b128 v[6:9], v6
	v_lshl_add_u64 v[10:11], v[16:17], 0, v[42:43]
	global_store_dwordx4 v[10:11], v[2:5], off
	s_nop 1
	v_add_u32_e32 v2, v85, v86
	ds_read_b128 v[2:5], v2
	s_waitcnt lgkmcnt(1)
	v_cndmask_b32_e64 v10, v6, v8, s[0:1]
	v_cndmask_b32_e64 v8, v8, v6, s[0:1]
	v_or_b32_e32 v6, s6, v81
	v_lshlrev_b32_e32 v42, 11, v6
	v_cndmask_b32_e64 v11, v7, v9, s[0:1]
	v_cndmask_b32_e64 v9, v9, v7, s[0:1]
	v_lshl_add_u64 v[6:7], v[16:17], 0, v[42:43]
	global_store_dwordx4 v[6:7], v[8:11], off
	s_waitcnt lgkmcnt(0)
	v_cndmask_b32_e64 v6, v2, v4, s[0:1]
	v_cndmask_b32_e64 v4, v4, v2, s[0:1]
	v_or_b32_e32 v2, s6, v84
	v_lshlrev_b32_e32 v42, 11, v2
	v_add_u32_e32 v2, v88, v89
	v_cndmask_b32_e64 v7, v3, v5, s[0:1]
	v_cndmask_b32_e64 v5, v5, v3, s[0:1]
	ds_read_b128 v[8:11], v2
	v_lshl_add_u64 v[2:3], v[16:17], 0, v[42:43]
	global_store_dwordx4 v[2:3], v[4:7], off
	v_add_u32_e32 v2, v91, v92
	ds_read_b128 v[2:5], v2
	v_or_b32_e32 v6, s6, v87
	v_lshlrev_b32_e32 v42, 11, v6
	s_waitcnt lgkmcnt(1)
	v_cndmask_b32_e64 v13, v9, v11, s[0:1]
	v_cndmask_b32_e64 v12, v8, v10, s[0:1]
	v_cndmask_b32_e64 v11, v11, v9, s[0:1]
	v_cndmask_b32_e64 v10, v10, v8, s[0:1]
	v_lshl_add_u64 v[6:7], v[16:17], 0, v[42:43]
	global_store_dwordx4 v[6:7], v[10:13], off
	s_waitcnt lgkmcnt(0)
	v_cndmask_b32_e64 v6, v2, v4, s[0:1]
	v_cndmask_b32_e64 v4, v4, v2, s[0:1]
	v_or_b32_e32 v2, s6, v90
	v_lshlrev_b32_e32 v42, 11, v2
	v_add_u32_e32 v2, v94, v95
	ds_read_b128 v[8:11], v2
	v_cndmask_b32_e64 v7, v3, v5, s[0:1]
	v_cndmask_b32_e64 v5, v5, v3, s[0:1]
	v_lshl_add_u64 v[2:3], v[16:17], 0, v[42:43]
	global_store_dwordx4 v[2:3], v[4:7], off
	v_add_u32_e32 v2, v97, v98
	ds_read_b128 v[12:15], v2
	v_or_b32_e32 v6, s6, v93
	v_lshlrev_b32_e32 v42, 11, v6
	s_waitcnt lgkmcnt(1)
	v_cndmask_b32_e64 v5, v9, v11, s[0:1]
	v_cndmask_b32_e64 v4, v8, v10, s[0:1]
	v_cndmask_b32_e64 v3, v11, v9, s[0:1]
	v_cndmask_b32_e64 v2, v10, v8, s[0:1]
	v_lshl_add_u64 v[6:7], v[16:17], 0, v[42:43]
	global_store_dwordx4 v[6:7], v[2:5], off
	v_or_b32_e32 v6, s6, v96
	v_lshlrev_b32_e32 v42, 11, v6
	s_waitcnt lgkmcnt(0)
	v_cndmask_b32_e64 v5, v13, v15, s[0:1]
	v_cndmask_b32_e64 v4, v12, v14, s[0:1]
	v_cndmask_b32_e64 v3, v15, v13, s[0:1]
	v_cndmask_b32_e64 v2, v14, v12, s[0:1]
	v_lshl_add_u64 v[6:7], v[16:17], 0, v[42:43]

; #define GAS __attribute__((address_space(1)))
; #define LAS __attribute__((address_space(3)))
; __device__ __forceinline__ unsigned pk2(float lo, float hi) { f32x2_t v = {lo, hi}; bf16x2_t h = __builtin_convertvector(v, bf16x2_t); return __builtin_bit_cast(unsigned, h); }
; __device__ __forceinline__ void transpose_item(const float* W, int ldw, bf16* WT, int K, int k0, int sn0, int dn0, int lane, LAS unsigned char* T, const float* kgain = nullptr) {
;     ...
;     for (int j = 0; j < 4; ++j) { const int kb = kq + 4 * j, k = k0 + 4 * kb; f32x4 r[4];
; #pragma unroll
;         for (int jj = 0; jj < 4; ++jj) r[jj] = *(const GAS f32x4*)(W + (size_t)(k + jj) * ldw + sn0 + 4 * nb);
;         f32x4 g = {1.f, 1.f, 1.f, 1.f}; if (kgain) g = *(const GAS f32x4*)(kgain + k);
;         const f32x4 a = r[0] * g.x, bq = r[1] * g.y, c = r[2] * g.z, d = r[3] * g.w;
;         LAS unsigned char* t = T + (4 * nb) * 128 + ((kb ^ nb) << 3);
;         v2u w; w.x = pk2(a.x, bq.x); w.y = pk2(c.x, d.x); *(LAS v2u*)t = w;
;         w.x = pk2(a.y, bq.y); w.y = pk2(c.y, d.y); *(LAS v2u*)(t + 128) = w;
;         w.x = pk2(a.z, bq.z); w.y = pk2(c.z, d.z); *(LAS v2u*)(t + 256) = w;
;         w.x = pk2(a.w, bq.w); w.y = pk2(c.w, d.w); *(LAS v2u*)(t + 384) = w; }
; template <int PART> __device__ __forceinline__ void deferred_transposes(Frame& F, int gw, int ngw) {
;     ...
;         if (r < I_GLU) { const int nblk = S5W / 64, kb = r / nblk, nb = r % nblk; transpose_item(F.in[16], S5W, WgluT, S5W, kb * 64, nb * 64, nb * 64, F.lane, F.lds + F.wave * 8192); continue; } r -= I_GLU;
.LBB0_919:
	s_andn2_b64 vcc, exec, s[4:5]
	s_cbranch_vccnz .LBB0_888
	s_add_i32 s4, s3, 0x6c0
	s_ashr_i32 s5, s4, 31
	s_lshr_b32 s5, s5, 29
	s_add_i32 s5, s4, s5
	s_and_b32 s6, s5, 0x3fffff8
	s_lshl_b32 s5, s5, 3
	s_sub_i32 s4, s4, s6
	s_and_b32 s6, s5, 0xffffffc0
	v_or_b32_e32 v10, s6, v99
	v_ashrrev_i32_e32 v11, 31, v10
	s_lshl_b32 s4, s4, 6
	v_lshlrev_b64 v[2:3], 11, v[10:11]
	v_or_b32_e32 v4, 1, v10
	v_or_b32_e32 v12, 2, v10
	v_or_b32_e32 v10, 3, v10
	v_or_b32_e32 v26, s6, v100
	s_ashr_i32 s5, s4, 31
	v_ashrrev_i32_e32 v5, 31, v4
	v_ashrrev_i32_e32 v13, 31, v12
	v_ashrrev_i32_e32 v11, 31, v10
	v_ashrrev_i32_e32 v27, 31, v26
	v_lshl_add_u64 v[64:65], s[4:5], 2, v[60:61]
	v_lshlrev_b64 v[4:5], 11, v[4:5]
	v_lshlrev_b64 v[12:13], 11, v[12:13]
	v_lshlrev_b64 v[10:11], 11, v[10:11]
	s_waitcnt vmcnt(0)
	v_lshlrev_b64 v[18:19], 11, v[26:27]
	v_or_b32_e32 v20, 1, v26
	s_waitcnt lgkmcnt(0)
	v_or_b32_e32 v28, 2, v26
	v_or_b32_e32 v26, 3, v26
	v_or_b32_e32 v104, s6, v101
	v_lshl_add_u64 v[2:3], v[64:65], 0, v[2:3]
	v_lshl_add_u64 v[6:7], v[64:65], 0, v[4:5]
	v_lshl_add_u64 v[12:13], v[64:65], 0, v[12:13]
	v_lshl_add_u64 v[14:15], v[64:65], 0, v[10:11]
	v_ashrrev_i32_e32 v21, 31, v20
	v_ashrrev_i32_e32 v29, 31, v28
	v_ashrrev_i32_e32 v27, 31, v26
	v_ashrrev_i32_e32 v105, 31, v104
	global_load_dwordx4 v[2:5], v[2:3], off nt
	s_nop 0
	global_load_dwordx4 v[6:9], v[6:7], off nt
	s_nop 0
	global_load_dwordx4 v[10:13], v[12:13], off nt
	s_nop 0
	global_load_dwordx4 v[14:17], v[14:15], off nt
	v_lshlrev_b64 v[20:21], 11, v[20:21]
	v_lshlrev_b64 v[28:29], 11, v[28:29]
	v_lshlrev_b64 v[26:27], 11, v[26:27]
	v_lshlrev_b64 v[34:35], 11, v[104:105]
	v_or_b32_e32 v36, 1, v104
	v_or_b32_e32 v106, 2, v104
	v_or_b32_e32 v104, 3, v104
	v_lshl_add_u64 v[18:19], v[64:65], 0, v[18:19]
	v_lshl_add_u64 v[22:23], v[64:65], 0, v[20:21]
	v_lshl_add_u64 v[28:29], v[64:65], 0, v[28:29]
	v_lshl_add_u64 v[30:31], v[64:65], 0, v[26:27]
	v_ashrrev_i32_e32 v37, 31, v36
	v_ashrrev_i32_e32 v107, 31, v106
	v_ashrrev_i32_e32 v105, 31, v104
	v_or_b32_e32 v120, s6, v102
	global_load_dwordx4 v[18:21], v[18:19], off nt
	s_nop 0
	global_load_dwordx4 v[22:25], v[22:23], off nt
	s_nop 0
	global_load_dwordx4 v[26:29], v[28:29], off nt
	s_nop 0
	global_load_dwordx4 v[30:33], v[30:31], off nt
	v_lshlrev_b64 v[36:37], 11, v[36:37]
	v_lshlrev_b64 v[106:107], 11, v[106:107]
	v_lshlrev_b64 v[104:105], 11, v[104:105]
	v_ashrrev_i32_e32 v121, 31, v120
	v_or_b32_e32 v114, 1, v120
	v_or_b32_e32 v122, 2, v120
	v_lshl_add_u64 v[34:35], v[64:65], 0, v[34:35]
	v_lshl_add_u64 v[38:39], v[64:65], 0, v[36:37]
	v_lshl_add_u64 v[106:107], v[64:65], 0, v[106:107]
	v_lshl_add_u64 v[108:109], v[64:65], 0, v[104:105]
	v_lshlrev_b64 v[112:113], 11, v[120:121]
	v_ashrrev_i32_e32 v115, 31, v114
	v_ashrrev_i32_e32 v123, 31, v122
	v_or_b32_e32 v120, 3, v120
	global_load_dwordx4 v[34:37], v[34:35], off nt
	s_nop 0
	global_load_dwordx4 v[38:41], v[38:39], off nt
	s_nop 0
	global_load_dwordx4 v[104:107], v[106:107], off nt
	s_nop 0
	global_load_dwordx4 v[108:111], v[108:109], off nt
	v_lshlrev_b64 v[114:115], 11, v[114:115]
	v_lshlrev_b64 v[122:123], 11, v[122:123]
	v_ashrrev_i32_e32 v121, 31, v120
	v_lshl_add_u64 v[112:113], v[64:65], 0, v[112:113]
	v_lshl_add_u64 v[116:117], v[64:65], 0, v[114:115]
	v_lshl_add_u64 v[122:123], v[64:65], 0, v[122:123]
	v_lshlrev_b64 v[120:121], 11, v[120:121]
	global_load_dwordx4 v[112:115], v[112:113], off nt
	s_nop 0
	global_load_dwordx4 v[116:119], v[116:117], off nt
	v_lshl_add_u64 v[64:65], v[64:65], 0, v[120:121]
	global_load_dwordx4 v[120:123], v[122:123], off nt
	s_nop 0
	global_load_dwordx4 v[124:127], v[64:65], off nt
	s_ashr_i32 s7, s6, 31
	s_waitcnt vmcnt(14)
	v_cvt_pk_bf16_f32 v64, v2, v6
	s_waitcnt vmcnt(12)
	v_cvt_pk_bf16_f32 v65, v10, v14
	v_add_u32_e32 v6, v68, v69
	v_cvt_pk_bf16_f32 v2, v3, v7
	v_cvt_pk_bf16_f32 v3, v11, v15
	ds_write2_b64 v6, v[64:65], v[2:3] offset1:16
	v_cvt_pk_bf16_f32 v2, v4, v8
	v_cvt_pk_bf16_f32 v3, v12, v16
	v_cvt_pk_bf16_f32 v4, v5, v9
	v_cvt_pk_bf16_f32 v5, v13, v17
	ds_write2_b64 v6, v[2:3], v[4:5] offset0:32 offset1:48
	v_add_u32_e32 v6, v68, v71
	v_lshl_add_u64 v[16:17], s[6:7], 1, v[62:63]
	s_waitcnt vmcnt(10)
	v_cvt_pk_bf16_f32 v2, v18, v22
	s_waitcnt vmcnt(8)
; #define GAS __attribute__((address_space(1)))
; #define LAS __attribute__((address_space(3)))
; __device__ __forceinline__ unsigned pk2(float lo, float hi) { f32x2_t v = {lo, hi}; bf16x2_t h = __builtin_convertvector(v, bf16x2_t); return __builtin_bit_cast(unsigned, h); }
; __device__ __forceinline__ void transpose_item(const float* W, int ldw, bf16* WT, int K, int k0, int sn0, int dn0, int lane, LAS unsigned char* T, const float* kgain = nullptr) {
;     ...
;         LAS unsigned char* t = T + (4 * nb) * 128 + ((kb ^ nb) << 3);
;         v2u w; w.x = pk2(a.x, bq.x); w.y = pk2(c.x, d.x); *(LAS v2u*)t = w;
;         w.x = pk2(a.y, bq.y); w.y = pk2(c.y, d.y); *(LAS v2u*)(t + 128) = w;
;         w.x = pk2(a.z, bq.z); w.y = pk2(c.z, d.z); *(LAS v2u*)(t + 256) = w;
;         w.x = pk2(a.w, bq.w); w.y = pk2(c.w, d.w); *(LAS v2u*)(t + 384) = w; }
; #pragma unroll
;     for (int i = 0; i < 8; ++i) { const int n = 8 * i + (lane >> 3), p = lane & 7, s = (n >> 2) & 15;
;         v4u o = *(const LAS v4u*)(T + n * 128 + ((p ^ (s >> 1)) << 4));
;         if (s & 1) { const unsigned tx = o.x, ty = o.y; o.x = o.z; o.y = o.w; o.z = tx; o.w = ty; }
;         *(GAS v4u*)(WT + (size_t)(dn0 + n) * K + k0 + 8 * p) = o; }
	v_cvt_pk_bf16_f32 v3, v26, v30
	v_cvt_pk_bf16_f32 v4, v19, v23
	v_cvt_pk_bf16_f32 v5, v27, v31
	ds_write2_b64 v6, v[2:3], v[4:5] offset1:16
	v_cvt_pk_bf16_f32 v2, v20, v24
	v_cvt_pk_bf16_f32 v3, v28, v32
	v_cvt_pk_bf16_f32 v4, v21, v25
	v_cvt_pk_bf16_f32 v5, v29, v33
	ds_write2_b64 v6, v[2:3], v[4:5] offset0:32 offset1:48
	v_add_u32_e32 v6, v68, v73
	s_waitcnt vmcnt(6)
	v_cvt_pk_bf16_f32 v2, v34, v38
	s_waitcnt vmcnt(4)
	v_cvt_pk_bf16_f32 v3, v104, v108
	v_cvt_pk_bf16_f32 v4, v35, v39
	v_cvt_pk_bf16_f32 v5, v105, v109
	ds_write2_b64 v6, v[2:3], v[4:5] offset1:16
	v_cvt_pk_bf16_f32 v2, v36, v40
	v_cvt_pk_bf16_f32 v3, v106, v110
	v_cvt_pk_bf16_f32 v4, v37, v41
	v_cvt_pk_bf16_f32 v5, v107, v111
	ds_write2_b64 v6, v[2:3], v[4:5] offset0:32 offset1:48
	s_waitcnt vmcnt(2)
	v_cvt_pk_bf16_f32 v2, v112, v116
	s_waitcnt vmcnt(0)
	v_cvt_pk_bf16_f32 v3, v120, v124
	v_add_u32_e32 v6, v68, v75
	v_cvt_pk_bf16_f32 v4, v113, v117
	v_cvt_pk_bf16_f32 v5, v121, v125
	ds_write2_b64 v6, v[2:3], v[4:5] offset1:16
	v_cvt_pk_bf16_f32 v2, v114, v118
	v_cvt_pk_bf16_f32 v3, v122, v126
	v_cvt_pk_bf16_f32 v4, v115, v119
	v_cvt_pk_bf16_f32 v5, v123, v127
	ds_write2_b64 v6, v[2:3], v[4:5] offset0:32 offset1:48
	v_add_u32_e32 v2, v77, v46
	ds_read_b128 v[2:5], v2
	v_add_u32_e32 v6, v79, v80
	ds_read_b128 v[6:9], v6
	s_waitcnt lgkmcnt(1)
	v_cndmask_b32_e64 v12, v2, v4, s[0:1]
	v_cndmask_b32_e64 v10, v4, v2, s[0:1]
	v_or_b32_e32 v2, s4, v76
	v_cndmask_b32_e64 v13, v3, v5, s[0:1]
	v_cndmask_b32_e64 v11, v5, v3, s[0:1]
	v_ashrrev_i32_e32 v3, 31, v2
	v_lshlrev_b64 v[2:3], 10, v[2:3]
	v_lshl_add_u64 v[2:3], v[16:17], 0, v[2:3]
	global_store_dwordx4 v[2:3], v[10:13], off
	s_waitcnt lgkmcnt(0)
	v_cndmask_b32_e64 v4, v6, v8, s[0:1]
	v_cndmask_b32_e64 v2, v8, v6, s[0:1]
	v_or_b32_e32 v6, s4, v78
	v_cndmask_b32_e64 v5, v7, v9, s[0:1]
	v_cndmask_b32_e64 v3, v9, v7, s[0:1]
	v_ashrrev_i32_e32 v7, 31, v6
	v_lshlrev_b64 v[10:11], 10, v[6:7]
	v_add_u32_e32 v6, v82, v83
	ds_read_b128 v[6:9], v6
	v_lshl_add_u64 v[10:11], v[16:17], 0, v[10:11]
	global_store_dwordx4 v[10:11], v[2:5], off
	s_nop 1
	v_add_u32_e32 v2, v85, v86
	ds_read_b128 v[2:5], v2
	s_waitcnt lgkmcnt(1)
	v_cndmask_b32_e64 v10, v6, v8, s[0:1]
	v_cndmask_b32_e64 v8, v8, v6, s[0:1]
	v_or_b32_e32 v6, s4, v81
	v_cndmask_b32_e64 v11, v7, v9, s[0:1]
	v_cndmask_b32_e64 v9, v9, v7, s[0:1]
	v_ashrrev_i32_e32 v7, 31, v6
	v_lshlrev_b64 v[6:7], 10, v[6:7]
	v_lshl_add_u64 v[6:7], v[16:17], 0, v[6:7]
	global_store_dwordx4 v[6:7], v[8:11], off
	s_waitcnt lgkmcnt(0)
	v_cndmask_b32_e64 v6, v2, v4, s[0:1]
	v_cndmask_b32_e64 v4, v4, v2, s[0:1]
	v_or_b32_e32 v2, s4, v84
	v_cndmask_b32_e64 v7, v3, v5, s[0:1]
	v_cndmask_b32_e64 v5, v5, v3, s[0:1]
	v_ashrrev_i32_e32 v3, 31, v2
	v_lshlrev_b64 v[2:3], 10, v[2:3]
	v_add_u32_e32 v8, v88, v89
	v_lshl_add_u64 v[2:3], v[16:17], 0, v[2:3]
	ds_read_b128 v[8:11], v8
	global_store_dwordx4 v[2:3], v[4:7], off
	v_add_u32_e32 v2, v91, v92
	ds_read_b128 v[2:5], v2
	v_or_b32_e32 v6, s4, v87
	v_ashrrev_i32_e32 v7, 31, v6
	v_lshlrev_b64 v[6:7], 10, v[6:7]
	s_waitcnt lgkmcnt(1)
	v_cndmask_b32_e64 v13, v9, v11, s[0:1]
	v_cndmask_b32_e64 v12, v8, v10, s[0:1]
	v_cndmask_b32_e64 v11, v11, v9, s[0:1]
	v_cndmask_b32_e64 v10, v10, v8, s[0:1]
	v_lshl_add_u64 v[6:7], v[16:17], 0, v[6:7]
	global_store_dwordx4 v[6:7], v[10:13], off
	s_waitcnt lgkmcnt(0)
	v_cndmask_b32_e64 v6, v2, v4, s[0:1]
	v_cndmask_b32_e64 v4, v4, v2, s[0:1]
	v_or_b32_e32 v2, s4, v90
	v_cndmask_b32_e64 v7, v3, v5, s[0:1]
	v_cndmask_b32_e64 v5, v5, v3, s[0:1]
	v_ashrrev_i32_e32 v3, 31, v2
	v_add_u32_e32 v8, v94, v95
	v_lshlrev_b64 v[2:3], 10, v[2:3]
	ds_read_b128 v[8:11], v8
	v_lshl_add_u64 v[2:3], v[16:17], 0, v[2:3]
	global_store_dwordx4 v[2:3], v[4:7], off
	v_add_u32_e32 v2, v97, v98
	ds_read_b128 v[12:15], v2
	v_or_b32_e32 v6, s4, v93
	v_ashrrev_i32_e32 v7, 31, v6
	v_lshlrev_b64 v[6:7], 10, v[6:7]
	s_waitcnt lgkmcnt(1)
	v_cndmask_b32_e64 v5, v9, v11, s[0:1]
	v_cndmask_b32_e64 v4, v8, v10, s[0:1]
	v_cndmask_b32_e64 v3, v11, v9, s[0:1]
	v_cndmask_b32_e64 v2, v10, v8, s[0:1]
	v_lshl_add_u64 v[6:7], v[16:17], 0, v[6:7]
	global_store_dwordx4 v[6:7], v[2:5], off
	v_or_b32_e32 v6, s4, v96
	v_ashrrev_i32_e32 v7, 31, v6
	v_lshlrev_b64 v[6:7], 10, v[6:7]
	s_waitcnt lgkmcnt(0)
	v_cndmask_b32_e64 v5, v13, v15, s[0:1]
	v_cndmask_b32_e64 v4, v12, v14, s[0:1]
	v_cndmask_b32_e64 v3, v15, v13, s[0:1]
	v_cndmask_b32_e64 v2, v14, v12, s[0:1]
	v_lshl_add_u64 v[6:7], v[16:17], 0, v[6:7]
	s_branch .LBB0_888

; #define GAS __attribute__((address_space(1)))
; #define LAS __attribute__((address_space(3)))
; __device__ __forceinline__ unsigned pk2(float lo, float hi) { f32x2_t v = {lo, hi}; bf16x2_t h = __builtin_convertvector(v, bf16x2_t); return __builtin_bit_cast(unsigned, h); }
; __device__ __forceinline__ void transpose_item(const float* W, int ldw, bf16* WT, int K, int k0, int sn0, int dn0, int lane, LAS unsigned char* T, const float* kgain = nullptr) {
;     const int nb = lane & 15, kq = lane >> 4;
; #pragma unroll
;     for (int j = 0; j < 4; ++j) { const int kb = kq + 4 * j, k = k0 + 4 * kb; f32x4 r[4];
; #pragma unroll
;         for (int jj = 0; jj < 4; ++jj) r[jj] = *(const GAS f32x4*)(W + (size_t)(k + jj) * ldw + sn0 + 4 * nb);
;         f32x4 g = {1.f, 1.f, 1.f, 1.f}; if (kgain) g = *(const GAS f32x4*)(kgain + k);
;         const f32x4 a = r[0] * g.x, bq = r[1] * g.y, c = r[2] * g.z, d = r[3] * g.w;
;         LAS unsigned char* t = T + (4 * nb) * 128 + ((kb ^ nb) << 3);
;         v2u w; w.x = pk2(a.x, bq.x); w.y = pk2(c.x, d.x); *(LAS v2u*)t = w;
;         w.x = pk2(a.y, bq.y); w.y = pk2(c.y, d.y); *(LAS v2u*)(t + 128) = w;
;         w.x = pk2(a.z, bq.z); w.y = pk2(c.z, d.z); *(LAS v2u*)(t + 256) = w;
;         w.x = pk2(a.w, bq.w); w.y = pk2(c.w, d.w); *(LAS v2u*)(t + 384) = w; }
; #pragma unroll
;     for (int i = 0; i < 8; ++i) { const int n = 8 * i + (lane >> 3), p = lane & 7, s = (n >> 2) & 15;
;         v4u o = *(const LAS v4u*)(T + n * 128 + ((p ^ (s >> 1)) << 4));
;         if (s & 1) { const unsigned tx = o.x, ty = o.y; o.x = o.z; o.y = o.w; o.z = tx; o.w = ty; }
;         *(GAS v4u*)(WT + (size_t)(dn0 + n) * K + k0 + 8 * p) = o; }
; template <int PART> __device__ __forceinline__ void deferred_transposes(Frame& F, int gw, int ngw) {
;     ...
;         { const int nblk = DM / 64, kb = r / nblk, nb = r % nblk; transpose_item(F.in[22], DM, WdT, DFF, kb * 64, nb * 64, nb * 64, F.lane, F.lds + F.wave * 8192); }
.LBB0_926:
	s_mov_b32 s20, s4
	s_cmpk_gt_i32 s4, 0xf97f
	s_mov_b64 s[4:5], -1
	s_cbranch_scc0 .LBB0_956
	s_cmpk_gt_i32 s20, 0xfa7f
	s_cbranch_scc0 .LBB0_953
	s_cmpk_gt_i32 s20, 0xfd3f
	s_cbranch_scc0 .LBB0_942
	s_cmp_gt_i32 s20, -1
	s_cbranch_scc0 .LBB0_931
	s_and_b32 s5, s20, 0x1ffffff0
	s_and_b32 s4, s11, 0x3c0
	v_or_b32_e32 v2, s5, v67
	s_lshl_b32 s12, s4, 2
	v_lshlrev_b32_e32 v42, 2, v2
	v_lshl_add_u64 v[64:65], v[44:45], 0, s[12:13]
	v_lshlrev_b64 v[2:3], 12, v[42:43]
	v_lshl_add_u64 v[10:11], v[64:65], 0, v[2:3]
	v_or_b32_e32 v2, 1, v42
	v_mov_b32_e32 v3, v43
	v_lshlrev_b64 v[2:3], 12, v[2:3]
	v_lshl_add_u64 v[12:13], v[64:65], 0, v[2:3]
	global_load_dwordx4 v[2:5], v[10:11], off nt
	global_load_dwordx4 v[6:9], v[12:13], off nt
	v_or_b32_e32 v10, 2, v42
	v_mov_b32_e32 v11, v43
	v_lshlrev_b64 v[10:11], 12, v[10:11]
	v_or_b32_e32 v42, 3, v42
	s_waitcnt vmcnt(0)
	v_lshl_add_u64 v[18:19], v[64:65], 0, v[10:11]
	v_lshlrev_b64 v[10:11], 12, v[42:43]
	v_lshl_add_u64 v[20:21], v[64:65], 0, v[10:11]
	global_load_dwordx4 v[10:13], v[18:19], off nt
	global_load_dwordx4 v[14:17], v[20:21], off nt
	v_or_b32_e32 v18, s5, v70
	v_lshlrev_b32_e32 v42, 2, v18
	v_lshlrev_b64 v[18:19], 12, v[42:43]
	v_lshl_add_u64 v[26:27], v[64:65], 0, v[18:19]
	v_or_b32_e32 v18, 1, v42
	v_mov_b32_e32 v19, v43
	v_lshlrev_b64 v[18:19], 12, v[18:19]
	s_waitcnt lgkmcnt(0)
	v_lshl_add_u64 v[28:29], v[64:65], 0, v[18:19]
	global_load_dwordx4 v[18:21], v[26:27], off nt
	global_load_dwordx4 v[22:25], v[28:29], off nt
	v_or_b32_e32 v26, 2, v42
	v_mov_b32_e32 v27, v43
	v_lshlrev_b64 v[26:27], 12, v[26:27]
	v_or_b32_e32 v42, 3, v42
	v_lshl_add_u64 v[34:35], v[64:65], 0, v[26:27]
	v_lshlrev_b64 v[26:27], 12, v[42:43]
	v_lshl_add_u64 v[36:37], v[64:65], 0, v[26:27]
	global_load_dwordx4 v[26:29], v[34:35], off nt
	global_load_dwordx4 v[30:33], v[36:37], off nt
	v_or_b32_e32 v34, s5, v72
	v_lshlrev_b32_e32 v42, 2, v34
	v_lshlrev_b64 v[34:35], 12, v[42:43]
	v_lshl_add_u64 v[104:105], v[64:65], 0, v[34:35]
	v_or_b32_e32 v34, 1, v42
	v_mov_b32_e32 v35, v43
	v_lshlrev_b64 v[34:35], 12, v[34:35]
	v_lshl_add_u64 v[106:107], v[64:65], 0, v[34:35]
	global_load_dwordx4 v[34:37], v[104:105], off nt
	global_load_dwordx4 v[38:41], v[106:107], off nt
	v_or_b32_e32 v104, 2, v42
	v_mov_b32_e32 v105, v43
	v_lshlrev_b64 v[104:105], 12, v[104:105]
	v_or_b32_e32 v42, 3, v42
	v_lshl_add_u64 v[112:113], v[64:65], 0, v[104:105]
	v_lshlrev_b64 v[104:105], 12, v[42:43]
	v_or_b32_e32 v42, s5, v74
	v_lshlrev_b32_e32 v42, 2, v42
	v_lshl_add_u64 v[114:115], v[64:65], 0, v[104:105]
	global_load_dwordx4 v[104:107], v[112:113], off nt
	global_load_dwordx4 v[108:111], v[114:115], off nt
	v_lshlrev_b64 v[112:113], 12, v[42:43]
	v_lshl_add_u64 v[120:121], v[64:65], 0, v[112:113]
	v_or_b32_e32 v112, 1, v42
	v_mov_b32_e32 v113, v43
	v_lshlrev_b64 v[112:113], 12, v[112:113]
	v_lshl_add_u64 v[122:123], v[64:65], 0, v[112:113]
	global_load_dwordx4 v[112:115], v[120:121], off nt
	global_load_dwordx4 v[116:119], v[122:123], off nt
	v_or_b32_e32 v120, 2, v42
	v_mov_b32_e32 v121, v43
	v_lshlrev_b64 v[120:121], 12, v[120:121]
	v_or_b32_e32 v42, 3, v42
	v_lshl_add_u64 v[120:121], v[64:65], 0, v[120:121]
	v_lshlrev_b64 v[122:123], 12, v[42:43]
	v_lshl_add_u64 v[64:65], v[64:65], 0, v[122:123]
	global_load_dwordx4 v[120:123], v[120:121], off nt
	s_nop 0
	global_load_dwordx4 v[124:127], v[64:65], off nt
	v_add_u32_e32 v42, v68, v69
	s_and_b32 s5, s3, 0x7fffffc0
	s_lshl_b32 s12, s5, 1
	v_cvt_pk_bf16_f32 v64, v2, v6
	v_cvt_pk_bf16_f32 v2, v3, v7
	v_cvt_pk_bf16_f32 v6, v4, v8
	s_waitcnt vmcnt(12)
	v_cvt_pk_bf16_f32 v65, v10, v14
	v_cvt_pk_bf16_f32 v3, v11, v15
	ds_write2_b64 v42, v[64:65], v[2:3] offset1:16
	v_cvt_pk_bf16_f32 v7, v12, v16
	v_cvt_pk_bf16_f32 v2, v5, v9
	v_cvt_pk_bf16_f32 v3, v13, v17
	ds_write2_b64 v42, v[6:7], v[2:3] offset0:32 offset1:48
	v_add_u32_e32 v6, v68, v71
	v_lshl_add_u64 v[16:17], v[48:49], 0, s[12:13]
	s_waitcnt vmcnt(10)
	v_cvt_pk_bf16_f32 v2, v18, v22
	v_cvt_pk_bf16_f32 v4, v19, v23
	s_waitcnt vmcnt(8)
	v_cvt_pk_bf16_f32 v3, v26, v30
	v_cvt_pk_bf16_f32 v5, v27, v31
	ds_write2_b64 v6, v[2:3], v[4:5] offset1:16
	v_cvt_pk_bf16_f32 v2, v20, v24
	v_cvt_pk_bf16_f32 v3, v28, v32
	v_cvt_pk_bf16_f32 v4, v21, v25
	v_cvt_pk_bf16_f32 v5, v29, v33
	ds_write2_b64 v6, v[2:3], v[4:5] offset0:32 offset1:48
	v_add_u32_e32 v6, v68, v73
	s_waitcnt vmcnt(6)
	v_cvt_pk_bf16_f32 v2, v34, v38
	v_cvt_pk_bf16_f32 v4, v35, v39
	s_waitcnt vmcnt(4)
	v_cvt_pk_bf16_f32 v3, v104, v108
	v_cvt_pk_bf16_f32 v5, v105, v109
	ds_write2_b64 v6, v[2:3], v[4:5] offset1:16
	v_cvt_pk_bf16_f32 v2, v36, v40
	v_cvt_pk_bf16_f32 v3, v106, v110
	v_cvt_pk_bf16_f32 v4, v37, v41
	v_cvt_pk_bf16_f32 v5, v107, v111
	ds_write2_b64 v6, v[2:3], v[4:5] offset0:32 offset1:48
	s_waitcnt vmcnt(2)
	v_cvt_pk_bf16_f32 v2, v112, v116
	v_add_u32_e32 v6, v68, v75
	v_cvt_pk_bf16_f32 v4, v113, v117
	s_waitcnt vmcnt(0)
	v_cvt_pk_bf16_f32 v3, v120, v124
	v_cvt_pk_bf16_f32 v5, v121, v125
	ds_write2_b64 v6, v[2:3], v[4:5] offset1:16
	v_cvt_pk_bf16_f32 v2, v114, v118
	v_cvt_pk_bf16_f32 v3, v122, v126
	v_cvt_pk_bf16_f32 v4, v115, v119
	v_cvt_pk_bf16_f32 v5, v123, v127
	ds_write2_b64 v6, v[2:3], v[4:5] offset0:32 offset1:48
	v_add_u32_e32 v2, v77, v46
	ds_read_b128 v[2:5], v2
	v_add_u32_e32 v6, v79, v80
	ds_read_b128 v[6:9], v6
	s_waitcnt lgkmcnt(1)
	v_cndmask_b32_e64 v12, v2, v4, s[0:1]
	v_cndmask_b32_e64 v10, v4, v2, s[0:1]
	v_or_b32_e32 v2, s4, v76
	v_mul_u32_u24_e32 v42, 0x1600, v2
	v_cndmask_b32_e64 v13, v3, v5, s[0:1]
	v_cndmask_b32_e64 v11, v5, v3, s[0:1]
	v_lshl_add_u64 v[2:3], v[16:17], 0, v[42:43]
	global_store_dwordx4 v[2:3], v[10:13], off
	s_waitcnt lgkmcnt(0)
; #define GAS __attribute__((address_space(1)))
; #define LAS __attribute__((address_space(3)))
; __device__ __forceinline__ unsigned pk2(float lo, float hi) { f32x2_t v = {lo, hi}; bf16x2_t h = __builtin_convertvector(v, bf16x2_t); return __builtin_bit_cast(unsigned, h); }
; __device__ __forceinline__ void transpose_item(const float* W, int ldw, bf16* WT, int K, int k0, int sn0, int dn0, int lane, LAS unsigned char* T, const float* kgain = nullptr) {
;     ...
;     for (int j = 0; j < 4; ++j) { const int kb = kq + 4 * j, k = k0 + 4 * kb; f32x4 r[4];
; #pragma unroll
;         for (int jj = 0; jj < 4; ++jj) r[jj] = *(const GAS f32x4*)(W + (size_t)(k + jj) * ldw + sn0 + 4 * nb);
;         f32x4 g = {1.f, 1.f, 1.f, 1.f}; if (kgain) g = *(const GAS f32x4*)(kgain + k);
;         const f32x4 a = r[0] * g.x, bq = r[1] * g.y, c = r[2] * g.z, d = r[3] * g.w;
;         LAS unsigned char* t = T + (4 * nb) * 128 + ((kb ^ nb) << 3);
;         v2u w; w.x = pk2(a.x, bq.x); w.y = pk2(c.x, d.x); *(LAS v2u*)t = w;
;         w.x = pk2(a.y, bq.y); w.y = pk2(c.y, d.y); *(LAS v2u*)(t + 128) = w;
;         w.x = pk2(a.z, bq.z); w.y = pk2(c.z, d.z); *(LAS v2u*)(t + 256) = w;
;         w.x = pk2(a.w, bq.w); w.y = pk2(c.w, d.w); *(LAS v2u*)(t + 384) = w; }
; #pragma unroll
;     for (int i = 0; i < 8; ++i) { const int n = 8 * i + (lane >> 3), p = lane & 7, s = (n >> 2) & 15;
;         v4u o = *(const LAS v4u*)(T + n * 128 + ((p ^ (s >> 1)) << 4));
;         if (s & 1) { const unsigned tx = o.x, ty = o.y; o.x = o.z; o.y = o.w; o.z = tx; o.w = ty; }
;         *(GAS v4u*)(WT + (size_t)(dn0 + n) * K + k0 + 8 * p) = o; }
; template <int PART> __device__ __forceinline__ void deferred_transposes(Frame& F, int gw, int ngw) {
;     ...
;         if (r < I_G) { const int nblk = DFF / 64, kb = r / nblk, nb = r % nblk, sn0 = nb * 64; transpose_item(F.in[21], DFF, WguT, DM, kb * 64, sn0, 256 * (sn0 / 128) + 128 + (sn0 % 128), F.lane, F.lds + F.wave * 8192, F.in[19]); continue; } r -= I_G;
	v_cndmask_b32_e64 v4, v6, v8, s[0:1]
	v_cndmask_b32_e64 v2, v8, v6, s[0:1]
	v_or_b32_e32 v6, s4, v78
	v_mul_u32_u24_e32 v42, 0x1600, v6
	v_add_u32_e32 v6, v82, v83
	v_cndmask_b32_e64 v5, v7, v9, s[0:1]
	v_cndmask_b32_e64 v3, v9, v7, s[0:1]
	ds_read_b128 v[6:9], v6
	v_lshl_add_u64 v[10:11], v[16:17], 0, v[42:43]
	global_store_dwordx4 v[10:11], v[2:5], off
	s_nop 1
	v_add_u32_e32 v2, v85, v86
	ds_read_b128 v[2:5], v2
	s_waitcnt lgkmcnt(1)
	v_cndmask_b32_e64 v10, v6, v8, s[0:1]
	v_cndmask_b32_e64 v8, v8, v6, s[0:1]
	v_or_b32_e32 v6, s4, v81
	v_mul_u32_u24_e32 v42, 0x1600, v6
	v_cndmask_b32_e64 v11, v7, v9, s[0:1]
	v_cndmask_b32_e64 v9, v9, v7, s[0:1]
	v_lshl_add_u64 v[6:7], v[16:17], 0, v[42:43]
	global_store_dwordx4 v[6:7], v[8:11], off
	s_waitcnt lgkmcnt(0)
	v_cndmask_b32_e64 v6, v2, v4, s[0:1]
	v_cndmask_b32_e64 v4, v4, v2, s[0:1]
	v_or_b32_e32 v2, s4, v84
	v_mul_u32_u24_e32 v42, 0x1600, v2
	v_add_u32_e32 v2, v88, v89
	v_cndmask_b32_e64 v7, v3, v5, s[0:1]
	v_cndmask_b32_e64 v5, v5, v3, s[0:1]
	ds_read_b128 v[8:11], v2
	v_lshl_add_u64 v[2:3], v[16:17], 0, v[42:43]
	global_store_dwordx4 v[2:3], v[4:7], off
	v_add_u32_e32 v2, v91, v92
	ds_read_b128 v[2:5], v2
	v_or_b32_e32 v6, s4, v87
	v_mul_u32_u24_e32 v42, 0x1600, v6
	s_waitcnt lgkmcnt(1)
	v_cndmask_b32_e64 v13, v9, v11, s[0:1]
	v_cndmask_b32_e64 v12, v8, v10, s[0:1]
	v_cndmask_b32_e64 v11, v11, v9, s[0:1]
	v_cndmask_b32_e64 v10, v10, v8, s[0:1]
	v_lshl_add_u64 v[6:7], v[16:17], 0, v[42:43]
	global_store_dwordx4 v[6:7], v[10:13], off
	s_waitcnt lgkmcnt(0)
	v_cndmask_b32_e64 v6, v2, v4, s[0:1]
	v_cndmask_b32_e64 v4, v4, v2, s[0:1]
	v_or_b32_e32 v2, s4, v90
	v_mul_u32_u24_e32 v42, 0x1600, v2
	v_add_u32_e32 v2, v94, v95
	ds_read_b128 v[8:11], v2
	v_cndmask_b32_e64 v7, v3, v5, s[0:1]
	v_cndmask_b32_e64 v5, v5, v3, s[0:1]
	v_lshl_add_u64 v[2:3], v[16:17], 0, v[42:43]
	global_store_dwordx4 v[2:3], v[4:7], off
	v_add_u32_e32 v2, v97, v98
	ds_read_b128 v[12:15], v2
	v_or_b32_e32 v6, s4, v93
	v_mul_u32_u24_e32 v42, 0x1600, v6
	s_waitcnt lgkmcnt(1)
	v_cndmask_b32_e64 v5, v9, v11, s[0:1]
	v_cndmask_b32_e64 v4, v8, v10, s[0:1]
	v_cndmask_b32_e64 v3, v11, v9, s[0:1]
	v_cndmask_b32_e64 v2, v10, v8, s[0:1]
	v_lshl_add_u64 v[6:7], v[16:17], 0, v[42:43]
	global_store_dwordx4 v[6:7], v[2:5], off
	v_or_b32_e32 v6, s4, v96
	v_mul_u32_u24_e32 v42, 0x1600, v6
	s_waitcnt lgkmcnt(0)
	v_cndmask_b32_e64 v5, v13, v15, s[0:1]
	v_cndmask_b32_e64 v4, v12, v14, s[0:1]
	v_cndmask_b32_e64 v3, v15, v13, s[0:1]
	v_cndmask_b32_e64 v2, v14, v12, s[0:1]
	v_lshl_add_u64 v[6:7], v[16:17], 0, v[42:43]
	s_mov_b64 s[4:5], 0
.LBB0_931:
	s_andn2_b64 vcc, exec, s[4:5]
	s_cbranch_vccnz .LBB0_941
	s_add_i32 s4, s20, 0x2c0
	s_and_b32 s5, s4, 0xffff
	s_mul_i32 s5, s5, 0xba2f
	s_lshr_b32 s6, s5, 21
	s_mul_i32 s5, s6, 44
	s_sub_i32 s4, s4, s5
	s_and_b32 s5, s4, 0xffff
	s_lshl_b32 s4, s6, 6
	s_lshl_b32 s12, s5, 8
	v_or_b32_e32 v3, s4, v99
	v_lshl_add_u64 v[64:65], v[50:51], 0, s[12:13]
	v_mad_u32_u24 v42, v3, s17, s17
	v_mad_u64_u32 v[8:9], s[6:7], v3, s17, v[64:65]
	v_lshl_add_u64 v[10:11], v[64:65], 0, v[42:43]
	v_mad_u32_u24 v42, v3, s17, v47
	global_load_dwordx4 v[14:17], v[8:9], off nt
	global_load_dwordx4 v[4:7], v[10:11], off nt
	v_lshl_add_u64 v[8:9], v[64:65], 0, v[42:43]
	v_mad_u32_u24 v42, v3, s17, v103
	v_lshl_add_u64 v[10:11], v[64:65], 0, v[42:43]
	global_load_dwordx4 v[30:33], v[8:9], off nt
	global_load_dwordx4 v[22:25], v[10:11], off nt
	v_cndmask_b32_e64 v8, 0, 1, s[14:15]
	v_mov_b32_e32 v2, 1.0
	v_cmp_ne_u32_e64 s[6:7], 1, v8
	s_andn2_b64 vcc, exec, s[14:15]
	v_mov_b32_e32 v38, 1.0
	v_mov_b32_e32 v8, 1.0
	v_mov_b32_e32 v40, 1.0
	v_mov_b32_e32 v66, 1.0
	s_cbranch_vccnz .LBB0_934
	v_readlane_b32 s60, v238, 29
	v_lshlrev_b32_e32 v3, 2, v3
	v_readlane_b32 s66, v238, 35
	v_readlane_b32 s67, v238, 36
	v_readlane_b32 s61, v238, 30
	v_readlane_b32 s62, v238, 31
	v_readlane_b32 s63, v238, 32
	v_readlane_b32 s64, v238, 33
	v_readlane_b32 s65, v238, 34
	global_load_dwordx4 v[38:41], v3, s[66:67]
	v_readlane_b32 s68, v238, 37
	v_readlane_b32 s69, v238, 38
	v_readlane_b32 s70, v238, 39
	v_readlane_b32 s71, v238, 40
	v_readlane_b32 s72, v238, 41
	v_readlane_b32 s73, v238, 42
	v_readlane_b32 s74, v238, 43
	v_readlane_b32 s75, v238, 44
	s_waitcnt vmcnt(0)
	v_mov_b32_e32 v8, v39
	v_mov_b32_e32 v66, v41
.LBB0_934:
	v_or_b32_e32 v3, s4, v100
	v_mad_u32_u24 v42, v3, s17, s17
	s_waitcnt lgkmcnt(0)
	v_lshl_add_u64 v[28:29], v[64:65], 0, v[42:43]
	v_mad_u32_u24 v42, v3, s17, v47
	v_mad_u64_u32 v[26:27], s[18:19], v3, s17, v[64:65]
	v_lshl_add_u64 v[104:105], v[64:65], 0, v[42:43]
	v_mad_u32_u24 v42, v3, s17, v103
	global_load_dwordx4 v[18:21], v[26:27], off nt
	global_load_dwordx4 v[10:13], v[28:29], off nt
	v_lshl_add_u64 v[106:107], v[64:65], 0, v[42:43]
	global_load_dwordx4 v[34:37], v[104:105], off nt
	global_load_dwordx4 v[26:29], v[106:107], off nt
	s_waitcnt vmcnt(0)
	v_pk_mul_f32 v[14:15], v[14:15], v[38:39] op_sel_hi:[1,0]
	v_pk_mul_f32 v[4:5], v[4:5], v[8:9] op_sel_hi:[1,0]
	v_pk_mul_f32 v[30:31], v[30:31], v[40:41] op_sel_hi:[1,0]
	v_pk_mul_f32 v[22:23], v[22:23], v[66:67] op_sel_hi:[1,0]
	v_pk_mul_f32 v[16:17], v[16:17], v[38:39] op_sel_hi:[1,0]
	v_pk_mul_f32 v[6:7], v[6:7], v[8:9] op_sel_hi:[1,0]
	v_pk_mul_f32 v[8:9], v[32:33], v[40:41] op_sel_hi:[1,0]
	v_pk_mul_f32 v[24:25], v[24:25], v[66:67] op_sel_hi:[1,0]
	v_cvt_pk_bf16_f32 v32, v14, v4
	v_cvt_pk_bf16_f32 v33, v30, v22
	v_add_u32_e32 v14, v68, v69
	v_cvt_pk_bf16_f32 v4, v15, v5
	v_cvt_pk_bf16_f32 v5, v31, v23
	ds_write2_b64 v14, v[32:33], v[4:5] offset1:16
	v_cvt_pk_bf16_f32 v4, v16, v6
	v_cvt_pk_bf16_f32 v5, v8, v24
	v_cvt_pk_bf16_f32 v6, v17, v7
	v_cvt_pk_bf16_f32 v7, v9, v25
	ds_write2_b64 v14, v[4:5], v[6:7] offset0:32 offset1:48
	s_and_b64 vcc, exec, s[6:7]
	v_mov_b32_e32 v38, 1.0
	v_mov_b32_e32 v4, 1.0
	v_mov_b32_e32 v40, 1.0
	s_cbranch_vccnz .LBB0_936
	v_readlane_b32 s60, v238, 29
	v_lshlrev_b32_e32 v2, 2, v3
	v_readlane_b32 s66, v238, 35
	v_readlane_b32 s67, v238, 36
	v_readlane_b32 s61, v238, 30
	v_readlane_b32 s62, v238, 31
	v_readlane_b32 s63, v238, 32
	v_readlane_b32 s64, v238, 33
	v_readlane_b32 s65, v238, 34
	global_load_dwordx4 v[2:5], v2, s[66:67]
	v_readlane_b32 s68, v238, 37
	v_readlane_b32 s69, v238, 38
	v_readlane_b32 s70, v238, 39
	v_readlane_b32 s71, v238, 40
	v_readlane_b32 s72, v238, 41
	v_readlane_b32 s73, v238, 42
	v_readlane_b32 s74, v238, 43
	v_readlane_b32 s75, v238, 44
	s_waitcnt vmcnt(0)
	v_mov_b32_e32 v38, v3
	v_mov_b32_e32 v40, v5
; #define GAS __attribute__((address_space(1)))
; #define LAS __attribute__((address_space(3)))
; __device__ __forceinline__ unsigned pk2(float lo, float hi) { f32x2_t v = {lo, hi}; bf16x2_t h = __builtin_convertvector(v, bf16x2_t); return __builtin_bit_cast(unsigned, h); }
; __device__ __forceinline__ void transpose_item(const float* W, int ldw, bf16* WT, int K, int k0, int sn0, int dn0, int lane, LAS unsigned char* T, const float* kgain = nullptr) {
;     ...
;     for (int j = 0; j < 4; ++j) { const int kb = kq + 4 * j, k = k0 + 4 * kb; f32x4 r[4];
; #pragma unroll
;         for (int jj = 0; jj < 4; ++jj) r[jj] = *(const GAS f32x4*)(W + (size_t)(k + jj) * ldw + sn0 + 4 * nb);
;         f32x4 g = {1.f, 1.f, 1.f, 1.f}; if (kgain) g = *(const GAS f32x4*)(kgain + k);
;         const f32x4 a = r[0] * g.x, bq = r[1] * g.y, c = r[2] * g.z, d = r[3] * g.w;
;         LAS unsigned char* t = T + (4 * nb) * 128 + ((kb ^ nb) << 3);
;         v2u w; w.x = pk2(a.x, bq.x); w.y = pk2(c.x, d.x); *(LAS v2u*)t = w;
;         w.x = pk2(a.y, bq.y); w.y = pk2(c.y, d.y); *(LAS v2u*)(t + 128) = w;
;         w.x = pk2(a.z, bq.z); w.y = pk2(c.z, d.z); *(LAS v2u*)(t + 256) = w;
;         w.x = pk2(a.w, bq.w); w.y = pk2(c.w, d.w); *(LAS v2u*)(t + 384) = w; }
; template <int PART> __device__ __forceinline__ void deferred_transposes(Frame& F, int gw, int ngw) {
;     ...
;         if (r < I_G) { const int nblk = DFF / 64, kb = r / nblk, nb = r % nblk, sn0 = nb * 64; transpose_item(F.in[20], DFF, WguT, DM, kb * 64, sn0, 256 * (sn0 / 128) + (sn0 % 128), F.lane, F.lds + F.wave * 8192, F.in[19]); continue; } r -= I_G;
;         if (r < I_G) { const int nblk = DFF / 64, kb = r / nblk, nb = r % nblk, sn0 = nb * 64; transpose_item(F.in[21], DFF, WguT, DM, kb * 64, sn0, 256 * (sn0 / 128) + 128 + (sn0 % 128), F.lane, F.lds + F.wave * 8192, F.in[19]); continue; } r -= I_G;
.LBB0_936:
	v_or_b32_e32 v3, s4, v101
	v_mad_u32_u24 v42, v3, s17, s17
	v_lshl_add_u64 v[24:25], v[64:65], 0, v[42:43]
	v_mad_u32_u24 v42, v3, s17, v47
	v_mad_u64_u32 v[22:23], s[18:19], v3, s17, v[64:65]
	v_lshl_add_u64 v[104:105], v[64:65], 0, v[42:43]
	v_mad_u32_u24 v42, v3, s17, v103
	global_load_dwordx4 v[14:17], v[22:23], off nt
	global_load_dwordx4 v[6:9], v[24:25], off nt
	v_lshl_add_u64 v[106:107], v[64:65], 0, v[42:43]
	global_load_dwordx4 v[30:33], v[104:105], off nt
	global_load_dwordx4 v[22:25], v[106:107], off nt
	v_pk_mul_f32 v[18:19], v[18:19], v[2:3] op_sel_hi:[1,0]
	v_pk_mul_f32 v[10:11], v[10:11], v[38:39] op_sel_hi:[1,0]
	v_pk_mul_f32 v[36:37], v[36:37], v[4:5] op_sel_hi:[1,0]
	v_pk_mul_f32 v[4:5], v[34:35], v[4:5] op_sel_hi:[1,0]
	v_pk_mul_f32 v[26:27], v[26:27], v[40:41] op_sel_hi:[1,0]
	v_pk_mul_f32 v[20:21], v[20:21], v[2:3] op_sel_hi:[1,0]
	v_pk_mul_f32 v[12:13], v[12:13], v[38:39] op_sel_hi:[1,0]
	v_pk_mul_f32 v[28:29], v[28:29], v[40:41] op_sel_hi:[1,0]
	v_cvt_pk_bf16_f32 v34, v18, v10
	v_cvt_pk_bf16_f32 v35, v4, v26
	v_add_u32_e32 v2, v68, v71
	v_cvt_pk_bf16_f32 v4, v19, v11
	v_cvt_pk_bf16_f32 v5, v5, v27
	ds_write2_b64 v2, v[34:35], v[4:5] offset1:16
	v_cvt_pk_bf16_f32 v4, v20, v12
	v_cvt_pk_bf16_f32 v5, v36, v28
	v_cvt_pk_bf16_f32 v10, v21, v13
	v_cvt_pk_bf16_f32 v11, v37, v29
	ds_write2_b64 v2, v[4:5], v[10:11] offset0:32 offset1:48
	v_mov_b32_e32 v2, 1.0
	s_and_b64 vcc, exec, s[6:7]
	v_mov_b32_e32 v10, 1.0
	v_mov_b32_e32 v4, 1.0
	v_mov_b32_e32 v12, 1.0
	v_mov_b32_e32 v66, 1.0
	s_cbranch_vccnz .LBB0_938
	v_readlane_b32 s60, v238, 29
	v_lshlrev_b32_e32 v3, 2, v3
	v_readlane_b32 s66, v238, 35
	v_readlane_b32 s67, v238, 36
	v_readlane_b32 s61, v238, 30
	v_readlane_b32 s62, v238, 31
	v_readlane_b32 s63, v238, 32
	v_readlane_b32 s64, v238, 33
	v_readlane_b32 s65, v238, 34
	global_load_dwordx4 v[10:13], v3, s[66:67]
	v_readlane_b32 s68, v238, 37
	v_readlane_b32 s69, v238, 38
	v_readlane_b32 s70, v238, 39
	v_readlane_b32 s71, v238, 40
	v_readlane_b32 s72, v238, 41
	v_readlane_b32 s73, v238, 42
	v_readlane_b32 s74, v238, 43
	v_readlane_b32 s75, v238, 44
	s_waitcnt vmcnt(0)
	v_mov_b32_e32 v4, v11
	v_mov_b32_e32 v66, v13
.LBB0_938:
	v_or_b32_e32 v3, s4, v102
	v_mad_u32_u24 v42, v3, s17, s17
	v_lshl_add_u64 v[28:29], v[64:65], 0, v[42:43]
	v_mad_u32_u24 v42, v3, s17, v47
	v_mad_u64_u32 v[26:27], s[18:19], v3, s17, v[64:65]
	v_lshl_add_u64 v[104:105], v[64:65], 0, v[42:43]
	v_mad_u32_u24 v42, v3, s17, v103
	global_load_dwordx4 v[34:37], v[26:27], off nt
	global_load_dwordx4 v[18:21], v[28:29], off nt
	v_lshl_add_u64 v[64:65], v[64:65], 0, v[42:43]
	global_load_dwordx4 v[38:41], v[104:105], off nt
	global_load_dwordx4 v[26:29], v[64:65], off nt
	s_waitcnt vmcnt(7)
	v_pk_mul_f32 v[16:17], v[16:17], v[10:11] op_sel_hi:[1,0]
	v_pk_mul_f32 v[10:11], v[14:15], v[10:11] op_sel_hi:[1,0]
	s_waitcnt vmcnt(6)
	v_pk_mul_f32 v[8:9], v[8:9], v[4:5] op_sel_hi:[1,0]
	v_pk_mul_f32 v[4:5], v[6:7], v[4:5] op_sel_hi:[1,0]
	s_waitcnt vmcnt(5)
	v_pk_mul_f32 v[6:7], v[32:33], v[12:13] op_sel_hi:[1,0]
	v_pk_mul_f32 v[12:13], v[30:31], v[12:13] op_sel_hi:[1,0]
	s_waitcnt vmcnt(4)
	v_pk_mul_f32 v[22:23], v[22:23], v[66:67] op_sel_hi:[1,0]
	v_pk_mul_f32 v[14:15], v[24:25], v[66:67] op_sel_hi:[1,0]
	v_cvt_pk_bf16_f32 v24, v10, v4
	v_cvt_pk_bf16_f32 v25, v12, v22
	v_add_u32_e32 v10, v68, v73
	v_cvt_pk_bf16_f32 v4, v11, v5
	v_cvt_pk_bf16_f32 v5, v13, v23
	ds_write2_b64 v10, v[24:25], v[4:5] offset1:16
	v_cvt_pk_bf16_f32 v4, v16, v8
	v_cvt_pk_bf16_f32 v5, v6, v14
	v_cvt_pk_bf16_f32 v6, v17, v9
	v_cvt_pk_bf16_f32 v7, v7, v15
	ds_write2_b64 v10, v[4:5], v[6:7] offset0:32 offset1:48
	s_and_b64 vcc, exec, s[6:7]
	v_mov_b32_e32 v8, 1.0
	v_mov_b32_e32 v4, 1.0
	v_mov_b32_e32 v6, 1.0
	s_cbranch_vccnz .LBB0_940
	v_readlane_b32 s60, v238, 29
	v_lshlrev_b32_e32 v2, 2, v3
	v_readlane_b32 s66, v238, 35
	v_readlane_b32 s67, v238, 36
	v_readlane_b32 s61, v238, 30
	v_readlane_b32 s62, v238, 31
	v_readlane_b32 s63, v238, 32
	v_readlane_b32 s64, v238, 33
	v_readlane_b32 s65, v238, 34
	global_load_dwordx4 v[2:5], v2, s[66:67]
	v_readlane_b32 s68, v238, 37
	v_readlane_b32 s69, v238, 38
	v_readlane_b32 s70, v238, 39
	v_readlane_b32 s71, v238, 40
	v_readlane_b32 s72, v238, 41
	v_readlane_b32 s73, v238, 42
	v_readlane_b32 s74, v238, 43
	v_readlane_b32 s75, v238, 44
	s_waitcnt vmcnt(0)
	v_mov_b32_e32 v8, v3
	v_mov_b32_e32 v6, v5

; #define GAS __attribute__((address_space(1)))
; #define LAS __attribute__((address_space(3)))
; __device__ __forceinline__ unsigned pk2(float lo, float hi) { f32x2_t v = {lo, hi}; bf16x2_t h = __builtin_convertvector(v, bf16x2_t); return __builtin_bit_cast(unsigned, h); }
; __device__ __forceinline__ void transpose_item(const float* W, int ldw, bf16* WT, int K, int k0, int sn0, int dn0, int lane, LAS unsigned char* T, const float* kgain = nullptr) {
;     ...
;     for (int j = 0; j < 4; ++j) { const int kb = kq + 4 * j, k = k0 + 4 * kb; f32x4 r[4];
; #pragma unroll
;         for (int jj = 0; jj < 4; ++jj) r[jj] = *(const GAS f32x4*)(W + (size_t)(k + jj) * ldw + sn0 + 4 * nb);
;         f32x4 g = {1.f, 1.f, 1.f, 1.f}; if (kgain) g = *(const GAS f32x4*)(kgain + k);
;         const f32x4 a = r[0] * g.x, bq = r[1] * g.y, c = r[2] * g.z, d = r[3] * g.w;
;         LAS unsigned char* t = T + (4 * nb) * 128 + ((kb ^ nb) << 3);
;         v2u w; w.x = pk2(a.x, bq.x); w.y = pk2(c.x, d.x); *(LAS v2u*)t = w;
;         w.x = pk2(a.y, bq.y); w.y = pk2(c.y, d.y); *(LAS v2u*)(t + 128) = w;
;         w.x = pk2(a.z, bq.z); w.y = pk2(c.z, d.z); *(LAS v2u*)(t + 256) = w;
;         w.x = pk2(a.w, bq.w); w.y = pk2(c.w, d.w); *(LAS v2u*)(t + 384) = w; }
; template <int PART> __device__ __forceinline__ void deferred_transposes(Frame& F, int gw, int ngw) {
;     ...
;         if (r < I_G) { const int nblk = DFF / 64, kb = r / nblk, nb = r % nblk, sn0 = nb * 64; transpose_item(F.in[20], DFF, WguT, DM, kb * 64, sn0, 256 * (sn0 / 128) + (sn0 % 128), F.lane, F.lds + F.wave * 8192, F.in[19]); continue; } r -= I_G;
;         if (r < I_G) { const int nblk = DFF / 64, kb = r / nblk, nb = r % nblk, sn0 = nb * 64; transpose_item(F.in[21], DFF, WguT, DM, kb * 64, sn0, 256 * (sn0 / 128) + 128 + (sn0 % 128), F.lane, F.lds + F.wave * 8192, F.in[19]); continue; } r -= I_G;
.LBB0_942:
	s_andn2_b64 vcc, exec, s[4:5]
	s_cbranch_vccnz .LBB0_952
	s_add_i32 s4, s20, 0x580
	s_and_b32 s5, s4, 0xffff
	s_mul_i32 s5, s5, 0xba2f
	s_lshr_b32 s6, s5, 21
	s_mul_i32 s5, s6, 44
	s_sub_i32 s4, s4, s5
	s_and_b32 s5, s4, 0xffff
	s_lshl_b32 s4, s6, 6
	s_lshl_b32 s12, s5, 8
	v_or_b32_e32 v3, s4, v99
	v_lshl_add_u64 v[64:65], v[54:55], 0, s[12:13]
	v_mad_u32_u24 v42, v3, s17, s17
	v_mad_u64_u32 v[8:9], s[6:7], v3, s17, v[64:65]
	v_lshl_add_u64 v[10:11], v[64:65], 0, v[42:43]
	v_mad_u32_u24 v42, v3, s17, v47
	global_load_dwordx4 v[14:17], v[8:9], off nt
	global_load_dwordx4 v[4:7], v[10:11], off nt
	v_lshl_add_u64 v[8:9], v[64:65], 0, v[42:43]
	v_mad_u32_u24 v42, v3, s17, v103
	v_lshl_add_u64 v[10:11], v[64:65], 0, v[42:43]
	global_load_dwordx4 v[30:33], v[8:9], off nt
	global_load_dwordx4 v[22:25], v[10:11], off nt
	v_cndmask_b32_e64 v8, 0, 1, s[14:15]
	v_mov_b32_e32 v2, 1.0
	v_cmp_ne_u32_e64 s[6:7], 1, v8
	s_andn2_b64 vcc, exec, s[14:15]
	v_mov_b32_e32 v38, 1.0
	v_mov_b32_e32 v8, 1.0
	v_mov_b32_e32 v40, 1.0
	v_mov_b32_e32 v66, 1.0
	s_cbranch_vccnz .LBB0_945
	v_readlane_b32 s60, v238, 29
	v_lshlrev_b32_e32 v3, 2, v3
	v_readlane_b32 s66, v238, 35
	v_readlane_b32 s67, v238, 36
	v_readlane_b32 s61, v238, 30
	v_readlane_b32 s62, v238, 31
	v_readlane_b32 s63, v238, 32
	v_readlane_b32 s64, v238, 33
	v_readlane_b32 s65, v238, 34
	global_load_dwordx4 v[38:41], v3, s[66:67]
	v_readlane_b32 s68, v238, 37
	v_readlane_b32 s69, v238, 38
	v_readlane_b32 s70, v238, 39
	v_readlane_b32 s71, v238, 40
	v_readlane_b32 s72, v238, 41
	v_readlane_b32 s73, v238, 42
	v_readlane_b32 s74, v238, 43
	v_readlane_b32 s75, v238, 44
	s_waitcnt vmcnt(0)
	v_mov_b32_e32 v8, v39
	v_mov_b32_e32 v66, v41

; #define GAS __attribute__((address_space(1)))
; #define LAS __attribute__((address_space(3)))
; __device__ __forceinline__ unsigned pk2(float lo, float hi) { f32x2_t v = {lo, hi}; bf16x2_t h = __builtin_convertvector(v, bf16x2_t); return __builtin_bit_cast(unsigned, h); }
; __device__ __forceinline__ void transpose_item(const float* W, int ldw, bf16* WT, int K, int k0, int sn0, int dn0, int lane, LAS unsigned char* T, const float* kgain = nullptr) {
;     ...
;     for (int j = 0; j < 4; ++j) { const int kb = kq + 4 * j, k = k0 + 4 * kb; f32x4 r[4];
; #pragma unroll
;         for (int jj = 0; jj < 4; ++jj) r[jj] = *(const GAS f32x4*)(W + (size_t)(k + jj) * ldw + sn0 + 4 * nb);
;         f32x4 g = {1.f, 1.f, 1.f, 1.f}; if (kgain) g = *(const GAS f32x4*)(kgain + k);
;         const f32x4 a = r[0] * g.x, bq = r[1] * g.y, c = r[2] * g.z, d = r[3] * g.w;
;         LAS unsigned char* t = T + (4 * nb) * 128 + ((kb ^ nb) << 3);
;         v2u w; w.x = pk2(a.x, bq.x); w.y = pk2(c.x, d.x); *(LAS v2u*)t = w;
;         w.x = pk2(a.y, bq.y); w.y = pk2(c.y, d.y); *(LAS v2u*)(t + 128) = w;
;         w.x = pk2(a.z, bq.z); w.y = pk2(c.z, d.z); *(LAS v2u*)(t + 256) = w;
;         w.x = pk2(a.w, bq.w); w.y = pk2(c.w, d.w); *(LAS v2u*)(t + 384) = w; }
; template <int PART> __device__ __forceinline__ void deferred_transposes(Frame& F, int gw, int ngw) {
;     ...
;         if (r < I_OUT) { const int nblk = DM / 64, kb = r / nblk, nb = r % nblk; transpose_item(F.in[18], DM, WoutT, DM, kb * 64, nb * 64, nb * 64, F.lane, F.lds + F.wave * 8192); continue; } r -= I_OUT;
.LBB0_953:
	s_andn2_b64 vcc, exec, s[4:5]
	s_cbranch_vccnz .LBB0_955
	s_and_b32 s4, s3, 0xffffffc0
	s_addk_i32 s4, 0x1a00
	s_and_b32 s6, s11, 0x3c0
	s_lshl_b32 s12, s6, 2
	v_or_b32_e32 v42, s4, v99
	v_lshl_add_u64 v[64:65], v[56:57], 0, s[12:13]
	v_lshlrev_b64 v[2:3], 12, v[42:43]
	v_lshl_add_u64 v[10:11], v[64:65], 0, v[2:3]
	v_or_b32_e32 v2, 1, v42
	v_mov_b32_e32 v3, v43
	v_lshlrev_b64 v[2:3], 12, v[2:3]
	v_lshl_add_u64 v[12:13], v[64:65], 0, v[2:3]
	global_load_dwordx4 v[2:5], v[10:11], off nt
	global_load_dwordx4 v[6:9], v[12:13], off nt
	v_or_b32_e32 v10, 2, v42
	v_mov_b32_e32 v11, v43
	v_lshlrev_b64 v[10:11], 12, v[10:11]
	v_or_b32_e32 v42, 3, v42
	s_waitcnt vmcnt(0)
	v_lshl_add_u64 v[18:19], v[64:65], 0, v[10:11]
	v_lshlrev_b64 v[10:11], 12, v[42:43]
	v_or_b32_e32 v42, s4, v100
	v_lshl_add_u64 v[20:21], v[64:65], 0, v[10:11]
	global_load_dwordx4 v[10:13], v[18:19], off nt
	global_load_dwordx4 v[14:17], v[20:21], off nt
	v_lshlrev_b64 v[18:19], 12, v[42:43]
	v_lshl_add_u64 v[26:27], v[64:65], 0, v[18:19]
	v_or_b32_e32 v18, 1, v42
	v_mov_b32_e32 v19, v43
	v_lshlrev_b64 v[18:19], 12, v[18:19]
	s_waitcnt lgkmcnt(0)
	v_lshl_add_u64 v[28:29], v[64:65], 0, v[18:19]
	global_load_dwordx4 v[18:21], v[26:27], off nt
	global_load_dwordx4 v[22:25], v[28:29], off nt
	v_or_b32_e32 v26, 2, v42
	v_mov_b32_e32 v27, v43
	v_lshlrev_b64 v[26:27], 12, v[26:27]
	v_or_b32_e32 v42, 3, v42
	v_lshl_add_u64 v[34:35], v[64:65], 0, v[26:27]
	v_lshlrev_b64 v[26:27], 12, v[42:43]
	v_or_b32_e32 v42, s4, v101
	v_lshl_add_u64 v[36:37], v[64:65], 0, v[26:27]
	global_load_dwordx4 v[26:29], v[34:35], off nt
	global_load_dwordx4 v[30:33], v[36:37], off nt
	v_lshlrev_b64 v[34:35], 12, v[42:43]
	v_lshl_add_u64 v[104:105], v[64:65], 0, v[34:35]
	v_or_b32_e32 v34, 1, v42
	v_mov_b32_e32 v35, v43
	v_lshlrev_b64 v[34:35], 12, v[34:35]
	v_lshl_add_u64 v[106:107], v[64:65], 0, v[34:35]
	global_load_dwordx4 v[34:37], v[104:105], off nt
	global_load_dwordx4 v[38:41], v[106:107], off nt
	v_or_b32_e32 v104, 2, v42
	v_mov_b32_e32 v105, v43
	v_lshlrev_b64 v[104:105], 12, v[104:105]
	v_or_b32_e32 v42, 3, v42
	v_lshl_add_u64 v[112:113], v[64:65], 0, v[104:105]
	v_lshlrev_b64 v[104:105], 12, v[42:43]
	v_or_b32_e32 v42, s4, v102
	v_lshl_add_u64 v[114:115], v[64:65], 0, v[104:105]
	global_load_dwordx4 v[104:107], v[112:113], off nt
	global_load_dwordx4 v[108:111], v[114:115], off nt
	v_lshlrev_b64 v[112:113], 12, v[42:43]
	v_lshl_add_u64 v[120:121], v[64:65], 0, v[112:113]
	v_or_b32_e32 v112, 1, v42
	v_mov_b32_e32 v113, v43
	v_lshlrev_b64 v[112:113], 12, v[112:113]
	v_lshl_add_u64 v[122:123], v[64:65], 0, v[112:113]
	global_load_dwordx4 v[112:115], v[120:121], off nt
	global_load_dwordx4 v[116:119], v[122:123], off nt
	v_or_b32_e32 v120, 2, v42
	v_mov_b32_e32 v121, v43
	v_lshlrev_b64 v[120:121], 12, v[120:121]
	v_or_b32_e32 v42, 3, v42
	v_lshl_add_u64 v[120:121], v[64:65], 0, v[120:121]
	v_lshlrev_b64 v[122:123], 12, v[42:43]
	v_lshl_add_u64 v[64:65], v[64:65], 0, v[122:123]
	global_load_dwordx4 v[120:123], v[120:121], off nt
	s_nop 0
	global_load_dwordx4 v[124:127], v[64:65], off nt
	v_add_u32_e32 v42, v68, v69
	s_mov_b32 s5, s13
	v_cvt_pk_bf16_f32 v64, v2, v6
	v_cvt_pk_bf16_f32 v2, v3, v7
	v_cvt_pk_bf16_f32 v6, v4, v8
	v_cvt_pk_bf16_f32 v4, v5, v9
	s_waitcnt vmcnt(12)
	v_cvt_pk_bf16_f32 v65, v10, v14
	v_cvt_pk_bf16_f32 v3, v11, v15
	v_cvt_pk_bf16_f32 v5, v13, v17
	v_cvt_pk_bf16_f32 v7, v12, v16
	ds_write2_b64 v42, v[64:65], v[2:3] offset1:16
	ds_write2_b64 v42, v[6:7], v[4:5] offset0:32 offset1:48
	v_add_u32_e32 v6, v68, v71
	v_lshl_add_u64 v[16:17], s[4:5], 1, v[58:59]
	s_waitcnt vmcnt(10)
	v_cvt_pk_bf16_f32 v2, v18, v22
	v_cvt_pk_bf16_f32 v4, v19, v23
	s_waitcnt vmcnt(8)
	v_cvt_pk_bf16_f32 v3, v26, v30
	v_cvt_pk_bf16_f32 v5, v27, v31
	ds_write2_b64 v6, v[2:3], v[4:5] offset1:16
	v_cvt_pk_bf16_f32 v2, v20, v24
	v_cvt_pk_bf16_f32 v3, v28, v32
	v_cvt_pk_bf16_f32 v4, v21, v25
	v_cvt_pk_bf16_f32 v5, v29, v33
	ds_write2_b64 v6, v[2:3], v[4:5] offset0:32 offset1:48
	s_waitcnt vmcnt(6)
; #define GAS __attribute__((address_space(1)))
; #define LAS __attribute__((address_space(3)))
; __device__ __forceinline__ unsigned pk2(float lo, float hi) { f32x2_t v = {lo, hi}; bf16x2_t h = __builtin_convertvector(v, bf16x2_t); return __builtin_bit_cast(unsigned, h); }
; __device__ __forceinline__ void transpose_item(const float* W, int ldw, bf16* WT, int K, int k0, int sn0, int dn0, int lane, LAS unsigned char* T, const float* kgain = nullptr) {
;     ...
;         LAS unsigned char* t = T + (4 * nb) * 128 + ((kb ^ nb) << 3);
;         v2u w; w.x = pk2(a.x, bq.x); w.y = pk2(c.x, d.x); *(LAS v2u*)t = w;
;         w.x = pk2(a.y, bq.y); w.y = pk2(c.y, d.y); *(LAS v2u*)(t + 128) = w;
;         w.x = pk2(a.z, bq.z); w.y = pk2(c.z, d.z); *(LAS v2u*)(t + 256) = w;
;         w.x = pk2(a.w, bq.w); w.y = pk2(c.w, d.w); *(LAS v2u*)(t + 384) = w; }
; #pragma unroll
;     for (int i = 0; i < 8; ++i) { const int n = 8 * i + (lane >> 3), p = lane & 7, s = (n >> 2) & 15;
;         v4u o = *(const LAS v4u*)(T + n * 128 + ((p ^ (s >> 1)) << 4));
;         if (s & 1) { const unsigned tx = o.x, ty = o.y; o.x = o.z; o.y = o.w; o.z = tx; o.w = ty; }
;         *(GAS v4u*)(WT + (size_t)(dn0 + n) * K + k0 + 8 * p) = o; }
	v_cvt_pk_bf16_f32 v2, v34, v38
	v_add_u32_e32 v6, v68, v73
	v_cvt_pk_bf16_f32 v4, v35, v39
	s_waitcnt vmcnt(4)
	v_cvt_pk_bf16_f32 v3, v104, v108
	v_cvt_pk_bf16_f32 v5, v105, v109
	ds_write2_b64 v6, v[2:3], v[4:5] offset1:16
	v_cvt_pk_bf16_f32 v2, v36, v40
	v_cvt_pk_bf16_f32 v3, v106, v110
	v_cvt_pk_bf16_f32 v4, v37, v41
	v_cvt_pk_bf16_f32 v5, v107, v111
	ds_write2_b64 v6, v[2:3], v[4:5] offset0:32 offset1:48
	s_waitcnt vmcnt(2)
	v_cvt_pk_bf16_f32 v2, v112, v116
	v_add_u32_e32 v6, v68, v75
	v_cvt_pk_bf16_f32 v4, v113, v117
	s_waitcnt vmcnt(0)
	v_cvt_pk_bf16_f32 v3, v120, v124
	v_cvt_pk_bf16_f32 v5, v121, v125
	ds_write2_b64 v6, v[2:3], v[4:5] offset1:16
	v_cvt_pk_bf16_f32 v2, v114, v118
	v_cvt_pk_bf16_f32 v3, v122, v126
	v_cvt_pk_bf16_f32 v4, v115, v119
	v_cvt_pk_bf16_f32 v5, v123, v127
	ds_write2_b64 v6, v[2:3], v[4:5] offset0:32 offset1:48
	v_add_u32_e32 v2, v77, v46
	ds_read_b128 v[2:5], v2
	v_add_u32_e32 v6, v79, v80
	ds_read_b128 v[6:9], v6
	s_waitcnt lgkmcnt(1)
	v_cndmask_b32_e64 v12, v2, v4, s[0:1]
	v_cndmask_b32_e64 v10, v4, v2, s[0:1]
	v_or_b32_e32 v2, s6, v76
	v_lshlrev_b32_e32 v42, 11, v2
	v_cndmask_b32_e64 v13, v3, v5, s[0:1]
	v_cndmask_b32_e64 v11, v5, v3, s[0:1]
	v_lshl_add_u64 v[2:3], v[16:17], 0, v[42:43]
	global_store_dwordx4 v[2:3], v[10:13], off
	s_waitcnt lgkmcnt(0)
	v_cndmask_b32_e64 v4, v6, v8, s[0:1]
	v_cndmask_b32_e64 v2, v8, v6, s[0:1]
	v_or_b32_e32 v6, s6, v78
	v_lshlrev_b32_e32 v42, 11, v6
	v_add_u32_e32 v6, v82, v83
	v_cndmask_b32_e64 v5, v7, v9, s[0:1]
	v_cndmask_b32_e64 v3, v9, v7, s[0:1]
	ds_read_b128 v[6:9], v6
	v_lshl_add_u64 v[10:11], v[16:17], 0, v[42:43]
	global_store_dwordx4 v[10:11], v[2:5], off
	s_nop 1
	v_add_u32_e32 v2, v85, v86
	ds_read_b128 v[2:5], v2
	s_waitcnt lgkmcnt(1)
	v_cndmask_b32_e64 v10, v6, v8, s[0:1]
	v_cndmask_b32_e64 v8, v8, v6, s[0:1]
	v_or_b32_e32 v6, s6, v81
	v_lshlrev_b32_e32 v42, 11, v6
	v_cndmask_b32_e64 v11, v7, v9, s[0:1]
	v_cndmask_b32_e64 v9, v9, v7, s[0:1]
	v_lshl_add_u64 v[6:7], v[16:17], 0, v[42:43]
	global_store_dwordx4 v[6:7], v[8:11], off
	s_waitcnt lgkmcnt(0)
	v_cndmask_b32_e64 v6, v2, v4, s[0:1]
	v_cndmask_b32_e64 v4, v4, v2, s[0:1]
	v_or_b32_e32 v2, s6, v84
	v_lshlrev_b32_e32 v42, 11, v2
	v_add_u32_e32 v2, v88, v89
	v_cndmask_b32_e64 v7, v3, v5, s[0:1]
	v_cndmask_b32_e64 v5, v5, v3, s[0:1]
	ds_read_b128 v[8:11], v2
	v_lshl_add_u64 v[2:3], v[16:17], 0, v[42:43]
	global_store_dwordx4 v[2:3], v[4:7], off
	v_add_u32_e32 v2, v91, v92
	ds_read_b128 v[2:5], v2
	v_or_b32_e32 v6, s6, v87
	v_lshlrev_b32_e32 v42, 11, v6
	s_waitcnt lgkmcnt(1)
	v_cndmask_b32_e64 v13, v9, v11, s[0:1]
	v_cndmask_b32_e64 v12, v8, v10, s[0:1]
	v_cndmask_b32_e64 v11, v11, v9, s[0:1]
	v_cndmask_b32_e64 v10, v10, v8, s[0:1]
	v_lshl_add_u64 v[6:7], v[16:17], 0, v[42:43]
	global_store_dwordx4 v[6:7], v[10:13], off
	s_waitcnt lgkmcnt(0)
	v_cndmask_b32_e64 v6, v2, v4, s[0:1]
	v_cndmask_b32_e64 v4, v4, v2, s[0:1]
	v_or_b32_e32 v2, s6, v90
	v_lshlrev_b32_e32 v42, 11, v2
	v_add_u32_e32 v2, v94, v95
	ds_read_b128 v[8:11], v2
	v_cndmask_b32_e64 v7, v3, v5, s[0:1]
	v_cndmask_b32_e64 v5, v5, v3, s[0:1]
	v_lshl_add_u64 v[2:3], v[16:17], 0, v[42:43]
	global_store_dwordx4 v[2:3], v[4:7], off
	v_add_u32_e32 v2, v97, v98
	ds_read_b128 v[12:15], v2
	v_or_b32_e32 v6, s6, v93
	v_lshlrev_b32_e32 v42, 11, v6
	s_waitcnt lgkmcnt(1)
	v_cndmask_b32_e64 v5, v9, v11, s[0:1]
	v_cndmask_b32_e64 v4, v8, v10, s[0:1]
	v_cndmask_b32_e64 v3, v11, v9, s[0:1]
	v_cndmask_b32_e64 v2, v10, v8, s[0:1]
	v_lshl_add_u64 v[6:7], v[16:17], 0, v[42:43]
	global_store_dwordx4 v[6:7], v[2:5], off
	v_or_b32_e32 v6, s6, v96
	v_lshlrev_b32_e32 v42, 11, v6
	s_waitcnt lgkmcnt(0)
	v_cndmask_b32_e64 v5, v13, v15, s[0:1]
	v_cndmask_b32_e64 v4, v12, v14, s[0:1]
	v_cndmask_b32_e64 v3, v15, v13, s[0:1]
	v_cndmask_b32_e64 v2, v14, v12, s[0:1]
	v_lshl_add_u64 v[6:7], v[16:17], 0, v[42:43]

; #define GAS __attribute__((address_space(1)))
; #define LAS __attribute__((address_space(3)))
; __device__ __forceinline__ unsigned pk2(float lo, float hi) { f32x2_t v = {lo, hi}; bf16x2_t h = __builtin_convertvector(v, bf16x2_t); return __builtin_bit_cast(unsigned, h); }
; __device__ __forceinline__ void transpose_item(const float* W, int ldw, bf16* WT, int K, int k0, int sn0, int dn0, int lane, LAS unsigned char* T, const float* kgain = nullptr) {
;     ...
;     for (int j = 0; j < 4; ++j) { const int kb = kq + 4 * j, k = k0 + 4 * kb; f32x4 r[4];
; #pragma unroll
;         for (int jj = 0; jj < 4; ++jj) r[jj] = *(const GAS f32x4*)(W + (size_t)(k + jj) * ldw + sn0 + 4 * nb);
;         f32x4 g = {1.f, 1.f, 1.f, 1.f}; if (kgain) g = *(const GAS f32x4*)(kgain + k);
;         const f32x4 a = r[0] * g.x, bq = r[1] * g.y, c = r[2] * g.z, d = r[3] * g.w;
;         LAS unsigned char* t = T + (4 * nb) * 128 + ((kb ^ nb) << 3);
;         v2u w; w.x = pk2(a.x, bq.x); w.y = pk2(c.x, d.x); *(LAS v2u*)t = w;
;         w.x = pk2(a.y, bq.y); w.y = pk2(c.y, d.y); *(LAS v2u*)(t + 128) = w;
;         w.x = pk2(a.z, bq.z); w.y = pk2(c.z, d.z); *(LAS v2u*)(t + 256) = w;
;         w.x = pk2(a.w, bq.w); w.y = pk2(c.w, d.w); *(LAS v2u*)(t + 384) = w; }
; template <int PART> __device__ __forceinline__ void deferred_transposes(Frame& F, int gw, int ngw) {
;     ...
;         if (r < I_GLU) { const int nblk = S5W / 64, kb = r / nblk, nb = r % nblk; transpose_item(F.in[16], S5W, WgluT, S5W, kb * 64, nb * 64, nb * 64, F.lane, F.lds + F.wave * 8192); continue; } r -= I_GLU;
.LBB0_956:
	s_andn2_b64 vcc, exec, s[4:5]
	s_cbranch_vccnz .LBB0_925
	s_add_i32 s4, s20, 0x6c0
	s_ashr_i32 s5, s4, 31
	s_lshr_b32 s5, s5, 29
	s_add_i32 s5, s4, s5
	s_and_b32 s6, s5, 0x3fffff8
	s_lshl_b32 s5, s5, 3
	s_sub_i32 s4, s4, s6
	s_and_b32 s6, s5, 0xffffffc0
	s_lshl_b32 s4, s4, 6
	v_or_b32_e32 v10, s6, v99
	s_ashr_i32 s5, s4, 31
	v_ashrrev_i32_e32 v11, 31, v10
	v_lshl_add_u64 v[64:65], s[4:5], 2, v[60:61]
	v_lshlrev_b64 v[2:3], 11, v[10:11]
	v_lshl_add_u64 v[12:13], v[64:65], 0, v[2:3]
	v_or_b32_e32 v2, 1, v10
	v_ashrrev_i32_e32 v3, 31, v2
	v_lshlrev_b64 v[2:3], 11, v[2:3]
	v_lshl_add_u64 v[14:15], v[64:65], 0, v[2:3]
	global_load_dwordx4 v[2:5], v[12:13], off nt
	global_load_dwordx4 v[6:9], v[14:15], off nt
	v_or_b32_e32 v12, 2, v10
	v_ashrrev_i32_e32 v13, 31, v12
	v_or_b32_e32 v10, 3, v10
	v_lshlrev_b64 v[12:13], 11, v[12:13]
	v_ashrrev_i32_e32 v11, 31, v10
	v_or_b32_e32 v26, s6, v100
	s_waitcnt vmcnt(0)
	v_lshl_add_u64 v[18:19], v[64:65], 0, v[12:13]
	v_lshlrev_b64 v[10:11], 11, v[10:11]
	v_ashrrev_i32_e32 v27, 31, v26
	v_lshl_add_u64 v[20:21], v[64:65], 0, v[10:11]
	global_load_dwordx4 v[10:13], v[18:19], off nt
	global_load_dwordx4 v[14:17], v[20:21], off nt
	v_lshlrev_b64 v[18:19], 11, v[26:27]
	s_waitcnt lgkmcnt(0)
	v_lshl_add_u64 v[28:29], v[64:65], 0, v[18:19]
	v_or_b32_e32 v18, 1, v26
	v_ashrrev_i32_e32 v19, 31, v18
	v_lshlrev_b64 v[18:19], 11, v[18:19]
	v_lshl_add_u64 v[30:31], v[64:65], 0, v[18:19]
	global_load_dwordx4 v[18:21], v[28:29], off nt
	global_load_dwordx4 v[22:25], v[30:31], off nt
	v_or_b32_e32 v28, 2, v26
	v_ashrrev_i32_e32 v29, 31, v28
	v_or_b32_e32 v26, 3, v26
	v_lshlrev_b64 v[28:29], 11, v[28:29]
	v_ashrrev_i32_e32 v27, 31, v26
	v_or_b32_e32 v104, s6, v101
	v_lshl_add_u64 v[34:35], v[64:65], 0, v[28:29]
	v_lshlrev_b64 v[26:27], 11, v[26:27]
	v_ashrrev_i32_e32 v105, 31, v104
	v_lshl_add_u64 v[36:37], v[64:65], 0, v[26:27]
	global_load_dwordx4 v[26:29], v[34:35], off nt
	global_load_dwordx4 v[30:33], v[36:37], off nt
	v_lshlrev_b64 v[34:35], 11, v[104:105]
	v_lshl_add_u64 v[106:107], v[64:65], 0, v[34:35]
	v_or_b32_e32 v34, 1, v104
	v_ashrrev_i32_e32 v35, 31, v34
	v_lshlrev_b64 v[34:35], 11, v[34:35]
	v_lshl_add_u64 v[108:109], v[64:65], 0, v[34:35]
	global_load_dwordx4 v[34:37], v[106:107], off nt
	global_load_dwordx4 v[38:41], v[108:109], off nt
	v_or_b32_e32 v106, 2, v104
	v_ashrrev_i32_e32 v107, 31, v106
	v_or_b32_e32 v104, 3, v104
	v_lshlrev_b64 v[106:107], 11, v[106:107]
	v_ashrrev_i32_e32 v105, 31, v104
	v_or_b32_e32 v120, s6, v102
	v_lshl_add_u64 v[112:113], v[64:65], 0, v[106:107]
	v_lshlrev_b64 v[104:105], 11, v[104:105]
	v_ashrrev_i32_e32 v121, 31, v120
	v_lshl_add_u64 v[114:115], v[64:65], 0, v[104:105]
	global_load_dwordx4 v[104:107], v[112:113], off nt
	global_load_dwordx4 v[108:111], v[114:115], off nt
	v_lshlrev_b64 v[112:113], 11, v[120:121]
	v_lshl_add_u64 v[122:123], v[64:65], 0, v[112:113]
	v_or_b32_e32 v112, 1, v120
	v_ashrrev_i32_e32 v113, 31, v112
	v_lshlrev_b64 v[112:113], 11, v[112:113]
	v_lshl_add_u64 v[124:125], v[64:65], 0, v[112:113]
	global_load_dwordx4 v[112:115], v[122:123], off nt
	global_load_dwordx4 v[116:119], v[124:125], off nt
	v_or_b32_e32 v122, 2, v120
	v_ashrrev_i32_e32 v123, 31, v122
	v_or_b32_e32 v120, 3, v120
	v_lshlrev_b64 v[122:123], 11, v[122:123]
	v_ashrrev_i32_e32 v121, 31, v120
	v_lshl_add_u64 v[122:123], v[64:65], 0, v[122:123]
	v_lshlrev_b64 v[120:121], 11, v[120:121]
	v_lshl_add_u64 v[64:65], v[64:65], 0, v[120:121]
	global_load_dwordx4 v[120:123], v[122:123], off nt
	s_nop 0
	global_load_dwordx4 v[124:127], v[64:65], off nt
	s_ashr_i32 s7, s6, 31
	v_cvt_pk_bf16_f32 v64, v2, v6
	v_add_u32_e32 v6, v68, v69
	v_cvt_pk_bf16_f32 v2, v3, v7
	s_waitcnt vmcnt(12)
	v_cvt_pk_bf16_f32 v65, v10, v14
	v_cvt_pk_bf16_f32 v3, v11, v15
	ds_write2_b64 v6, v[64:65], v[2:3] offset1:16
	v_cvt_pk_bf16_f32 v2, v4, v8
	v_cvt_pk_bf16_f32 v3, v12, v16
	v_cvt_pk_bf16_f32 v4, v5, v9
	v_cvt_pk_bf16_f32 v5, v13, v17
	ds_write2_b64 v6, v[2:3], v[4:5] offset0:32 offset1:48
	s_waitcnt vmcnt(10)
	v_cvt_pk_bf16_f32 v2, v18, v22
	v_add_u32_e32 v6, v68, v71
	v_cvt_pk_bf16_f32 v4, v19, v23
	v_lshl_add_u64 v[16:17], s[6:7], 1, v[62:63]
	s_waitcnt vmcnt(8)
; #define GAS __attribute__((address_space(1)))
; #define LAS __attribute__((address_space(3)))
; __device__ __forceinline__ unsigned pk2(float lo, float hi) { f32x2_t v = {lo, hi}; bf16x2_t h = __builtin_convertvector(v, bf16x2_t); return __builtin_bit_cast(unsigned, h); }
; __device__ __forceinline__ void transpose_item(const float* W, int ldw, bf16* WT, int K, int k0, int sn0, int dn0, int lane, LAS unsigned char* T, const float* kgain = nullptr) {
;     ...
;         LAS unsigned char* t = T + (4 * nb) * 128 + ((kb ^ nb) << 3);
;         v2u w; w.x = pk2(a.x, bq.x); w.y = pk2(c.x, d.x); *(LAS v2u*)t = w;
;         w.x = pk2(a.y, bq.y); w.y = pk2(c.y, d.y); *(LAS v2u*)(t + 128) = w;
;         w.x = pk2(a.z, bq.z); w.y = pk2(c.z, d.z); *(LAS v2u*)(t + 256) = w;
;         w.x = pk2(a.w, bq.w); w.y = pk2(c.w, d.w); *(LAS v2u*)(t + 384) = w; }
; #pragma unroll
;     for (int i = 0; i < 8; ++i) { const int n = 8 * i + (lane >> 3), p = lane & 7, s = (n >> 2) & 15;
;         v4u o = *(const LAS v4u*)(T + n * 128 + ((p ^ (s >> 1)) << 4));
;         if (s & 1) { const unsigned tx = o.x, ty = o.y; o.x = o.z; o.y = o.w; o.z = tx; o.w = ty; }
;         *(GAS v4u*)(WT + (size_t)(dn0 + n) * K + k0 + 8 * p) = o; }
; template <int PART> __device__ __forceinline__ void deferred_transposes(Frame& F, int gw, int ngw) {
;     ...
;     for (int it = gw; it < NITEMS; it += ngw) {
;         int r = (PART == 0) ? it : it + N0;
;         if (r < I_GLU) { const int nblk = S5W / 64, kb = r / nblk, nb = r % nblk; transpose_item(F.in[16], S5W, WgluT, S5W, kb * 64, nb * 64, nb * 64, F.lane, F.lds + F.wave * 8192); continue; } r -= I_GLU;
	v_cvt_pk_bf16_f32 v3, v26, v30
	v_cvt_pk_bf16_f32 v5, v27, v31
	ds_write2_b64 v6, v[2:3], v[4:5] offset1:16
	v_cvt_pk_bf16_f32 v2, v20, v24
	v_cvt_pk_bf16_f32 v3, v28, v32
	v_cvt_pk_bf16_f32 v4, v21, v25
	v_cvt_pk_bf16_f32 v5, v29, v33
	ds_write2_b64 v6, v[2:3], v[4:5] offset0:32 offset1:48
	s_waitcnt vmcnt(6)
	v_cvt_pk_bf16_f32 v2, v34, v38
	v_add_u32_e32 v6, v68, v73
	v_cvt_pk_bf16_f32 v4, v35, v39
	s_waitcnt vmcnt(4)
	v_cvt_pk_bf16_f32 v3, v104, v108
	v_cvt_pk_bf16_f32 v5, v105, v109
	ds_write2_b64 v6, v[2:3], v[4:5] offset1:16
	v_cvt_pk_bf16_f32 v2, v36, v40
	v_cvt_pk_bf16_f32 v3, v106, v110
	v_cvt_pk_bf16_f32 v4, v37, v41
	v_cvt_pk_bf16_f32 v5, v107, v111
	ds_write2_b64 v6, v[2:3], v[4:5] offset0:32 offset1:48
	s_waitcnt vmcnt(2)
	v_cvt_pk_bf16_f32 v2, v112, v116
	v_add_u32_e32 v6, v68, v75
	v_cvt_pk_bf16_f32 v4, v113, v117
	s_waitcnt vmcnt(0)
	v_cvt_pk_bf16_f32 v3, v120, v124
	v_cvt_pk_bf16_f32 v5, v121, v125
	ds_write2_b64 v6, v[2:3], v[4:5] offset1:16
	v_cvt_pk_bf16_f32 v2, v114, v118
	v_cvt_pk_bf16_f32 v3, v122, v126
	v_cvt_pk_bf16_f32 v4, v115, v119
	v_cvt_pk_bf16_f32 v5, v123, v127
	ds_write2_b64 v6, v[2:3], v[4:5] offset0:32 offset1:48
	v_add_u32_e32 v2, v77, v46
	ds_read_b128 v[2:5], v2
	v_add_u32_e32 v6, v79, v80
	ds_read_b128 v[6:9], v6
	s_waitcnt lgkmcnt(1)
	v_cndmask_b32_e64 v12, v2, v4, s[0:1]
	v_cndmask_b32_e64 v10, v4, v2, s[0:1]
	v_or_b32_e32 v2, s4, v76
	v_cndmask_b32_e64 v13, v3, v5, s[0:1]
	v_cndmask_b32_e64 v11, v5, v3, s[0:1]
	v_ashrrev_i32_e32 v3, 31, v2
	v_lshlrev_b64 v[2:3], 10, v[2:3]
	v_lshl_add_u64 v[2:3], v[16:17], 0, v[2:3]
	global_store_dwordx4 v[2:3], v[10:13], off
	s_waitcnt lgkmcnt(0)
	v_cndmask_b32_e64 v4, v6, v8, s[0:1]
	v_cndmask_b32_e64 v2, v8, v6, s[0:1]
	v_or_b32_e32 v6, s4, v78
	v_cndmask_b32_e64 v5, v7, v9, s[0:1]
	v_cndmask_b32_e64 v3, v9, v7, s[0:1]
	v_ashrrev_i32_e32 v7, 31, v6
	v_lshlrev_b64 v[10:11], 10, v[6:7]
	v_add_u32_e32 v6, v82, v83
	ds_read_b128 v[6:9], v6
	v_lshl_add_u64 v[10:11], v[16:17], 0, v[10:11]
	global_store_dwordx4 v[10:11], v[2:5], off
	s_nop 1
	v_add_u32_e32 v2, v85, v86
	ds_read_b128 v[2:5], v2
	s_waitcnt lgkmcnt(1)
	v_cndmask_b32_e64 v10, v6, v8, s[0:1]
	v_cndmask_b32_e64 v8, v8, v6, s[0:1]
	v_or_b32_e32 v6, s4, v81
	v_cndmask_b32_e64 v11, v7, v9, s[0:1]
	v_cndmask_b32_e64 v9, v9, v7, s[0:1]
	v_ashrrev_i32_e32 v7, 31, v6
	v_lshlrev_b64 v[6:7], 10, v[6:7]
	v_lshl_add_u64 v[6:7], v[16:17], 0, v[6:7]
	global_store_dwordx4 v[6:7], v[8:11], off
	s_waitcnt lgkmcnt(0)
	v_cndmask_b32_e64 v6, v2, v4, s[0:1]
	v_cndmask_b32_e64 v4, v4, v2, s[0:1]
	v_or_b32_e32 v2, s4, v84
	v_cndmask_b32_e64 v7, v3, v5, s[0:1]
	v_cndmask_b32_e64 v5, v5, v3, s[0:1]
	v_ashrrev_i32_e32 v3, 31, v2
	v_lshlrev_b64 v[2:3], 10, v[2:3]
	v_add_u32_e32 v8, v88, v89
	v_lshl_add_u64 v[2:3], v[16:17], 0, v[2:3]
	ds_read_b128 v[8:11], v8
	global_store_dwordx4 v[2:3], v[4:7], off
	v_add_u32_e32 v2, v91, v92
	ds_read_b128 v[2:5], v2
	v_or_b32_e32 v6, s4, v87
	v_ashrrev_i32_e32 v7, 31, v6
	v_lshlrev_b64 v[6:7], 10, v[6:7]
	s_waitcnt lgkmcnt(1)
	v_cndmask_b32_e64 v13, v9, v11, s[0:1]
	v_cndmask_b32_e64 v12, v8, v10, s[0:1]
	v_cndmask_b32_e64 v11, v11, v9, s[0:1]
	v_cndmask_b32_e64 v10, v10, v8, s[0:1]
	v_lshl_add_u64 v[6:7], v[16:17], 0, v[6:7]
	global_store_dwordx4 v[6:7], v[10:13], off
	s_waitcnt lgkmcnt(0)
	v_cndmask_b32_e64 v6, v2, v4, s[0:1]
	v_cndmask_b32_e64 v4, v4, v2, s[0:1]
	v_or_b32_e32 v2, s4, v90
	v_cndmask_b32_e64 v7, v3, v5, s[0:1]
	v_cndmask_b32_e64 v5, v5, v3, s[0:1]
	v_ashrrev_i32_e32 v3, 31, v2
	v_add_u32_e32 v8, v94, v95
	v_lshlrev_b64 v[2:3], 10, v[2:3]
	ds_read_b128 v[8:11], v8
	v_lshl_add_u64 v[2:3], v[16:17], 0, v[2:3]
	global_store_dwordx4 v[2:3], v[4:7], off
	v_add_u32_e32 v2, v97, v98
	ds_read_b128 v[12:15], v2
	v_or_b32_e32 v6, s4, v93
	v_ashrrev_i32_e32 v7, 31, v6
	v_lshlrev_b64 v[6:7], 10, v[6:7]
	s_waitcnt lgkmcnt(1)
	v_cndmask_b32_e64 v5, v9, v11, s[0:1]
	v_cndmask_b32_e64 v4, v8, v10, s[0:1]
	v_cndmask_b32_e64 v3, v11, v9, s[0:1]
	v_cndmask_b32_e64 v2, v10, v8, s[0:1]
	v_lshl_add_u64 v[6:7], v[16:17], 0, v[6:7]
	global_store_dwordx4 v[6:7], v[2:5], off
	v_or_b32_e32 v6, s4, v96
	v_ashrrev_i32_e32 v7, 31, v6
	v_lshlrev_b64 v[6:7], 10, v[6:7]
	s_waitcnt lgkmcnt(0)
	v_cndmask_b32_e64 v5, v13, v15, s[0:1]
	v_cndmask_b32_e64 v4, v12, v14, s[0:1]
	v_cndmask_b32_e64 v3, v15, v13, s[0:1]
	v_cndmask_b32_e64 v2, v14, v12, s[0:1]
	v_lshl_add_u64 v[6:7], v[16:17], 0, v[6:7]
	s_branch .LBB0_925
